# additionally: first K-loop iteration of every GEMM tile peeled, its first MFMA per accumulator takes C = 0, the 128 accumulator-zeroing v_mov per tile removed
# baseline (speedup 1.0000x reference)
; #define PG8_STAGE(bufoff, gbase, voff) do { _Pragma("unroll") for (int _i = 0; _i < 2; ++_i) \
;         __builtin_amdgcn_global_load_lds((const unsigned*)((const char*)(gbase) + (voff)[_i]), (PG8_LAS unsigned*)(lds + (bufoff) + ldsw + _i * 8192), 16, 0, 0); } while (0)
; #define PG8_LDA(dst, b, h) do { _Pragma("unroll") for (int m = 0; m < 4; ++m) _Pragma("unroll") for (int k = 0; k < 2; ++k) dst[m][k] = *(const PG8_LAS bf16x8*)(lds + PG8_SA(b, h) + aoff + m * 2048 + k * 1024); } while (0)
; #define PG8_LDB(dst, b, h) do { _Pragma("unroll") for (int n = 0; n < 2; ++n) _Pragma("unroll") for (int k = 0; k < 2; ++k) dst[n][k] = *(const PG8_LAS bf16x8*)(lds + PG8_SB(b, h) + boff + n * 2048 + k * 1024); } while (0)
; #define PG8_MMA(ai, bj, At, Bt) do { __builtin_amdgcn_s_setprio(1); _Pragma("unroll") for (int m = 0; m < 4; ++m) _Pragma("unroll") for (int n = 0; n < 2; ++n) _Pragma("unroll") for (int k = 0; k < 2; ++k) \
;         acc[ai][bj][m][n] = __builtin_amdgcn_mfma_f32_16x16x32_bf16(Bt[n][k], At[m][k], acc[ai][bj][m][n], 0, 0, 0); __builtin_amdgcn_s_setprio(0); } while (0)
; #define PG8_BAR __builtin_amdgcn_s_barrier()
; template <class Epi, class Sched, bool ALIGN_EPI = false, bool SP2 = false>
; __device__ __forceinline__ void gemm_phase(PG8_LAS unsigned char* lds, const Gemm g, const Sched& S, const Epi& E) {
;     ...
;         const bool has_next = S.next(ui + 1, nxt);
;         const char* nA = has_next ? (const char*)g.A + (size_t)nxt.pm * tstep : cA; const char* nB = has_next ? (const char*)g.Bt + (size_t)nxt.pn * tstep : cB;
;         for (int t = 0; t < nt; t += 2) {
;             const bool last = (t == nt - 2);
;             const char* a1 = cA + (size_t)(t + 1) * kstep;
;             const char* a2 = last ? nA : cA + (size_t)(t + 2) * kstep; const char* b2 = last ? nB : cB + (size_t)(t + 2) * kstep;
;             const char* a3 = a2 + kstep; const char* b3 = b2 + kstep;
;             if (last && has_next) S.a_ready(nxt);
;             if constexpr (SP2) {
;             PG8_LDB(B0, 0, 0); PG8_LDB(B1, 0, 1); PG8_SCHED; PG8_LDA(At, 0, 0); PG8_STAGE(PG8_SA(1, 1), a1 + hstep, voffA);
;             PG8_WAIT_V(8); PG8_WAIT_L(0); PG8_BAR; PG8_MMA(0, 0, At, B0); PG8_MMA(0, 1, At, B1); PG8_BAR; PG8_SCHED;
;             PG8_LDA(At, 0, 1); PG8_STAGE(PG8_SB(0, 0), b2, voffB); PG8_STAGE(PG8_SB(0, 1), b2 + hstep, voffB); PG8_STAGE(PG8_SA(0, 0), a2, voffA);
.LBB0_161:
	s_and_b64 s[98:99], s[38:39], exec
	s_cselect_b32 s71, s26, s56
	s_cselect_b32 s73, s24, s55
	s_ashr_i32 s27, s26, 31
	s_lshl_b64 s[34:35], s[26:27], 19
	s_add_u32 s40, s2, s34
	s_addc_u32 s41, s3, s35
	s_and_b64 s[34:35], s[38:39], exec
	s_cselect_b32 s27, s41, s47
	s_cselect_b32 s34, s40, s46
	s_ashr_i32 s25, s24, 31
	s_lshl_b64 s[42:43], s[24:25], 19
	s_add_u32 s42, s4, s42
	s_addc_u32 s43, s5, s43
	s_and_b64 s[48:49], s[38:39], exec
	s_cselect_b32 s25, s43, s45
	s_cselect_b32 s35, s42, s44
	s_add_u32 s57, s44, 0x100
	s_addc_u32 s58, s45, 0
	s_add_u32 s44, s46, 0x40080
	s_addc_u32 s45, s47, 0
	s_mov_b32 s59, -2
	s_add_u32 s10, s44, 0xfffc0080
	s_addc_u32 s11, s45, -1
	s_add_i32 s60, 16, 0x10000
	s_cmp_eq_u32 s59, 12
	s_cselect_b32 s49, s27, s11
	s_cselect_b32 s48, s34, s10
	s_cselect_b32 s47, s25, s58
	s_cselect_b32 s46, s35, s57
	s_add_i32 s10, 16, 0x14000
	v_add_u32_e32 v102, s60, v183
	v_add_u32_e32 v180, s10, v183
	ds_read_b128 v[90:93], v102
	ds_read_b128 v[94:97], v102 offset:1024
	ds_read_b128 v[98:101], v102 offset:2048
	ds_read_b128 v[102:105], v102 offset:3072
	ds_read_b128 v[158:161], v180
	ds_read_b128 v[176:179], v180 offset:1024
	ds_read_b128 v[186:189], v180 offset:2048
	ds_read_b128 v[190:193], v180 offset:3072
	v_lshl_add_u64 v[180:181], s[44:45], 0, v[156:157]
	s_add_i32 m0, s7, 0xc000
	ds_read_b128 v[194:197], v185
	ds_read_b128 v[198:201], v185 offset:1024
	ds_read_b128 v[202:205], v185 offset:2048
	ds_read_b128 v[206:209], v185 offset:3072
	ds_read_b128 v[210:213], v185 offset:4096
	ds_read_b128 v[214:217], v185 offset:5120
	ds_read_b128 v[218:221], v185 offset:6144
	ds_read_b128 v[222:225], v185 offset:7168
	global_load_lds_dwordx4 v[180:181], off
	v_lshl_add_u64 v[180:181], s[44:45], 0, v[154:155]
	s_add_i32 m0, s7, 0xe000
	s_nop 0
	global_load_lds_dwordx4 v[180:181], off
	s_waitcnt vmcnt(8)
	s_waitcnt lgkmcnt(0)
	s_setprio 1
	s_barrier
	v_mfma_f32_16x16x32_bf16 v[142:145], v[90:93], v[194:197], 0
	v_mfma_f32_16x16x32_bf16 v[142:145], v[94:97], v[198:201], v[142:145]
	v_mfma_f32_16x16x32_bf16 v[138:141], v[98:101], v[194:197], 0
	v_mfma_f32_16x16x32_bf16 v[138:141], v[102:105], v[198:201], v[138:141]
	v_mfma_f32_16x16x32_bf16 v[122:125], v[98:101], v[202:205], 0
	v_mfma_f32_16x16x32_bf16 v[122:125], v[102:105], v[206:209], v[122:125]
	v_mfma_f32_16x16x32_bf16 v[126:129], v[90:93], v[202:205], 0
	v_mfma_f32_16x16x32_bf16 v[126:129], v[94:97], v[206:209], v[126:129]
	v_mfma_f32_16x16x32_bf16 v[110:113], v[90:93], v[210:213], 0
	v_mfma_f32_16x16x32_bf16 v[110:113], v[94:97], v[214:217], v[110:113]
	v_mfma_f32_16x16x32_bf16 v[106:109], v[98:101], v[210:213], 0
	v_mfma_f32_16x16x32_bf16 v[106:109], v[102:105], v[214:217], v[106:109]
	v_mfma_f32_16x16x32_bf16 v[74:77], v[98:101], v[218:221], 0
	v_mfma_f32_16x16x32_bf16 v[74:77], v[102:105], v[222:225], v[74:77]
	v_mfma_f32_16x16x32_bf16 v[78:81], v[90:93], v[218:221], 0
	v_mfma_f32_16x16x32_bf16 v[78:81], v[94:97], v[222:225], v[78:81]
	v_mfma_f32_16x16x32_bf16 v[134:137], v[158:161], v[194:197], 0
	v_mfma_f32_16x16x32_bf16 v[134:137], v[176:179], v[198:201], v[134:137]
	v_mfma_f32_16x16x32_bf16 v[130:133], v[186:189], v[194:197], 0
	v_mfma_f32_16x16x32_bf16 v[130:133], v[190:193], v[198:201], v[130:133]
	v_mfma_f32_16x16x32_bf16 v[114:117], v[186:189], v[202:205], 0
	v_mfma_f32_16x16x32_bf16 v[114:117], v[190:193], v[206:209], v[114:117]
	v_mfma_f32_16x16x32_bf16 v[118:121], v[158:161], v[202:205], 0
	v_mfma_f32_16x16x32_bf16 v[118:121], v[176:179], v[206:209], v[118:121]
	v_mfma_f32_16x16x32_bf16 v[86:89], v[158:161], v[210:213], 0
	v_mfma_f32_16x16x32_bf16 v[86:89], v[176:179], v[214:217], v[86:89]
	v_mfma_f32_16x16x32_bf16 v[82:85], v[186:189], v[210:213], 0
	v_mfma_f32_16x16x32_bf16 v[82:85], v[190:193], v[214:217], v[82:85]
	v_mfma_f32_16x16x32_bf16 v[66:69], v[186:189], v[218:221], 0
	v_mfma_f32_16x16x32_bf16 v[66:69], v[190:193], v[222:225], v[66:69]
	v_mfma_f32_16x16x32_bf16 v[70:73], v[158:161], v[218:221], 0
	v_mfma_f32_16x16x32_bf16 v[70:73], v[176:179], v[222:225], v[70:73]
	s_barrier
	s_setprio 0
	s_add_i32 s11, s60, s6
	v_lshl_add_u64 v[180:181], s[46:47], 0, v[0:1]
	s_mov_b32 m0, s11
	ds_read_b128 v[194:197], v185 offset:16384
	ds_read_b128 v[198:201], v185 offset:17408
	ds_read_b128 v[202:205], v185 offset:18432
	ds_read_b128 v[206:209], v185 offset:19456
	ds_read_b128 v[210:213], v185 offset:20480
	ds_read_b128 v[214:217], v185 offset:21504
	ds_read_b128 v[218:221], v185 offset:22528
	ds_read_b128 v[222:225], v185 offset:23552
	global_load_lds_dwordx4 v[180:181], off
	s_add_i32 m0, s11, 0x2000
	s_add_u32 s60, s46, 0x40000
	v_lshl_add_u64 v[226:227], s[46:47], 0, v[146:147]
	s_addc_u32 s61, s47, 0
	s_add_i32 s10, s10, s6
	global_load_lds_dwordx4 v[226:227], off
	v_lshl_add_u64 v[238:239], s[60:61], 0, v[0:1]
	s_mov_b32 m0, s10
	v_lshl_add_u64 v[240:241], s[48:49], 0, v[148:149]
	global_load_lds_dwordx4 v[238:239], off
	v_lshl_add_u64 v[238:239], s[60:61], 0, v[146:147]
	s_add_i32 m0, s10, 0x2000
	s_nop 0
	global_load_lds_dwordx4 v[238:239], off
	v_lshl_add_u64 v[238:239], s[48:49], 0, v[150:151]
	s_mov_b32 m0, s7
	s_nop 0
	global_load_lds_dwordx4 v[238:239], off
	s_mov_b32 m0, s8
	s_nop 0
	global_load_lds_dwordx4 v[240:241], off
	s_waitcnt vmcnt(8)
	s_waitcnt lgkmcnt(0)
	s_setprio 1
	s_barrier
; #define PG8_STAGE(bufoff, gbase, voff) do { _Pragma("unroll") for (int _i = 0; _i < 2; ++_i) \
;         __builtin_amdgcn_global_load_lds((const unsigned*)((const char*)(gbase) + (voff)[_i]), (PG8_LAS unsigned*)(lds + (bufoff) + ldsw + _i * 8192), 16, 0, 0); } while (0)
; #define PG8_LDA(dst, b, h) do { _Pragma("unroll") for (int m = 0; m < 4; ++m) _Pragma("unroll") for (int k = 0; k < 2; ++k) dst[m][k] = *(const PG8_LAS bf16x8*)(lds + PG8_SA(b, h) + aoff + m * 2048 + k * 1024); } while (0)
; #define PG8_LDB(dst, b, h) do { _Pragma("unroll") for (int n = 0; n < 2; ++n) _Pragma("unroll") for (int k = 0; k < 2; ++k) dst[n][k] = *(const PG8_LAS bf16x8*)(lds + PG8_SB(b, h) + boff + n * 2048 + k * 1024); } while (0)
; #define PG8_MMA(ai, bj, At, Bt) do { __builtin_amdgcn_s_setprio(1); _Pragma("unroll") for (int m = 0; m < 4; ++m) _Pragma("unroll") for (int n = 0; n < 2; ++n) _Pragma("unroll") for (int k = 0; k < 2; ++k) \
;         acc[ai][bj][m][n] = __builtin_amdgcn_mfma_f32_16x16x32_bf16(Bt[n][k], At[m][k], acc[ai][bj][m][n], 0, 0, 0); __builtin_amdgcn_s_setprio(0); } while (0)
; #define PG8_WAIT_V(n) asm volatile("s_waitcnt vmcnt(" #n ")" ::: "memory")
; #define PG8_WAIT_L(n) asm volatile("s_waitcnt lgkmcnt(" #n ")" ::: "memory")
; #define PG8_BAR __builtin_amdgcn_s_barrier()
; #define PG8_SCHED __builtin_amdgcn_sched_barrier(0)
; template <class Epi, class Sched, bool ALIGN_EPI = false, bool SP2 = false>
; __device__ __forceinline__ void gemm_phase(PG8_LAS unsigned char* lds, const Gemm g, const Sched& S, const Epi& E) {
;     ...
;             PG8_WAIT_V(8); PG8_WAIT_L(0); PG8_BAR; PG8_MMA(1, 0, At, B0); PG8_MMA(1, 1, At, B1); PG8_BAR; PG8_SCHED;
;             PG8_LDB(B0, 1, 0); PG8_LDB(B1, 1, 1); PG8_SCHED; PG8_LDA(At, 1, 0); PG8_STAGE(PG8_SA(0, 1), a2 + hstep, voffA);
;             PG8_WAIT_V(8); PG8_WAIT_L(0); PG8_BAR; PG8_MMA(0, 0, At, B0); PG8_MMA(0, 1, At, B1); PG8_BAR; PG8_SCHED;
	v_mfma_f32_16x16x32_bf16 v[62:65], v[90:93], v[194:197], 0
	v_mfma_f32_16x16x32_bf16 v[62:65], v[94:97], v[198:201], v[62:65]
	v_mfma_f32_16x16x32_bf16 v[58:61], v[98:101], v[194:197], 0
	v_mfma_f32_16x16x32_bf16 v[58:61], v[102:105], v[198:201], v[58:61]
	v_mfma_f32_16x16x32_bf16 v[42:45], v[98:101], v[202:205], 0
	v_mfma_f32_16x16x32_bf16 v[42:45], v[102:105], v[206:209], v[42:45]
	v_mfma_f32_16x16x32_bf16 v[46:49], v[90:93], v[202:205], 0
	v_mfma_f32_16x16x32_bf16 v[46:49], v[94:97], v[206:209], v[46:49]
	v_mfma_f32_16x16x32_bf16 v[30:33], v[90:93], v[210:213], 0
	v_mfma_f32_16x16x32_bf16 v[30:33], v[94:97], v[214:217], v[30:33]
	v_mfma_f32_16x16x32_bf16 v[26:29], v[98:101], v[210:213], 0
	v_mfma_f32_16x16x32_bf16 v[26:29], v[102:105], v[214:217], v[26:29]
	v_mfma_f32_16x16x32_bf16 v[10:13], v[98:101], v[218:221], 0
	v_mfma_f32_16x16x32_bf16 v[10:13], v[102:105], v[222:225], v[10:13]
	v_mfma_f32_16x16x32_bf16 v[14:17], v[90:93], v[218:221], 0
	v_mfma_f32_16x16x32_bf16 v[14:17], v[94:97], v[222:225], v[14:17]
	v_mfma_f32_16x16x32_bf16 v[54:57], v[158:161], v[194:197], 0
	v_mfma_f32_16x16x32_bf16 v[54:57], v[176:179], v[198:201], v[54:57]
	v_mfma_f32_16x16x32_bf16 v[50:53], v[186:189], v[194:197], 0
	v_mfma_f32_16x16x32_bf16 v[50:53], v[190:193], v[198:201], v[50:53]
	v_mfma_f32_16x16x32_bf16 v[34:37], v[186:189], v[202:205], 0
	v_mfma_f32_16x16x32_bf16 v[34:37], v[190:193], v[206:209], v[34:37]
	v_mfma_f32_16x16x32_bf16 v[38:41], v[158:161], v[202:205], 0
	v_mfma_f32_16x16x32_bf16 v[38:41], v[176:179], v[206:209], v[38:41]
	v_mfma_f32_16x16x32_bf16 v[22:25], v[158:161], v[210:213], 0
	v_mfma_f32_16x16x32_bf16 v[22:25], v[176:179], v[214:217], v[22:25]
	v_mfma_f32_16x16x32_bf16 v[18:21], v[186:189], v[210:213], 0
	v_mfma_f32_16x16x32_bf16 v[18:21], v[190:193], v[214:217], v[18:21]
	v_mfma_f32_16x16x32_bf16 v[2:5], v[186:189], v[218:221], 0
	v_mfma_f32_16x16x32_bf16 v[2:5], v[190:193], v[222:225], v[2:5]
	v_mfma_f32_16x16x32_bf16 v[6:9], v[158:161], v[218:221], 0
	v_mfma_f32_16x16x32_bf16 v[6:9], v[176:179], v[222:225], v[6:9]
	s_barrier
	s_setprio 0
	s_add_i32 s10, 16, 0x18000
	s_add_i32 s11, 16, 0x1c000
	v_add_u32_e32 v102, s10, v183
	v_add_u32_e32 v190, s11, v183
	ds_read_b128 v[90:93], v102
	ds_read_b128 v[94:97], v102 offset:1024
	ds_read_b128 v[98:101], v102 offset:2048
	ds_read_b128 v[102:105], v102 offset:3072
	ds_read_b128 v[158:161], v190
	ds_read_b128 v[176:179], v190 offset:1024
	ds_read_b128 v[186:189], v190 offset:2048
	ds_read_b128 v[190:193], v190 offset:3072
	s_add_u32 s48, s48, 0x40000
	s_addc_u32 s49, s49, 0
	s_mov_b32 m0, s9
	v_lshl_add_u64 v[242:243], s[48:49], 0, v[150:151]
	ds_read_b128 v[194:197], v185 offset:32768
	ds_read_b128 v[198:201], v185 offset:33792
	ds_read_b128 v[202:205], v185 offset:34816
	ds_read_b128 v[206:209], v185 offset:35840
	ds_read_b128 v[210:213], v185 offset:36864
	ds_read_b128 v[214:217], v185 offset:37888
	ds_read_b128 v[218:221], v185 offset:38912
	ds_read_b128 v[222:225], v185 offset:39936
	global_load_lds_dwordx4 v[242:243], off
	v_lshl_add_u64 v[242:243], s[48:49], 0, v[148:149]
	s_mov_b32 m0, s50
	s_nop 0
	global_load_lds_dwordx4 v[242:243], off
	s_waitcnt vmcnt(8)
	s_waitcnt lgkmcnt(0)
	s_setprio 1
	s_barrier
	v_mfma_f32_16x16x32_bf16 v[142:145], v[90:93], v[194:197], v[142:145]
	v_mfma_f32_16x16x32_bf16 v[142:145], v[94:97], v[198:201], v[142:145]
	v_mfma_f32_16x16x32_bf16 v[138:141], v[98:101], v[194:197], v[138:141]
	v_mfma_f32_16x16x32_bf16 v[138:141], v[102:105], v[198:201], v[138:141]
	v_mfma_f32_16x16x32_bf16 v[122:125], v[98:101], v[202:205], v[122:125]
	v_mfma_f32_16x16x32_bf16 v[122:125], v[102:105], v[206:209], v[122:125]
	v_mfma_f32_16x16x32_bf16 v[126:129], v[90:93], v[202:205], v[126:129]
	v_mfma_f32_16x16x32_bf16 v[126:129], v[94:97], v[206:209], v[126:129]
	v_mfma_f32_16x16x32_bf16 v[110:113], v[90:93], v[210:213], v[110:113]
	v_mfma_f32_16x16x32_bf16 v[110:113], v[94:97], v[214:217], v[110:113]
	v_mfma_f32_16x16x32_bf16 v[106:109], v[98:101], v[210:213], v[106:109]
	v_mfma_f32_16x16x32_bf16 v[106:109], v[102:105], v[214:217], v[106:109]
	v_mfma_f32_16x16x32_bf16 v[74:77], v[98:101], v[218:221], v[74:77]
	v_mfma_f32_16x16x32_bf16 v[74:77], v[102:105], v[222:225], v[74:77]
	v_mfma_f32_16x16x32_bf16 v[78:81], v[90:93], v[218:221], v[78:81]
	v_mfma_f32_16x16x32_bf16 v[78:81], v[94:97], v[222:225], v[78:81]
	v_mfma_f32_16x16x32_bf16 v[134:137], v[158:161], v[194:197], v[134:137]
	v_mfma_f32_16x16x32_bf16 v[134:137], v[176:179], v[198:201], v[134:137]
	v_mfma_f32_16x16x32_bf16 v[130:133], v[186:189], v[194:197], v[130:133]
	v_mfma_f32_16x16x32_bf16 v[130:133], v[190:193], v[198:201], v[130:133]
	v_mfma_f32_16x16x32_bf16 v[114:117], v[186:189], v[202:205], v[114:117]
	v_mfma_f32_16x16x32_bf16 v[114:117], v[190:193], v[206:209], v[114:117]
	v_mfma_f32_16x16x32_bf16 v[118:121], v[158:161], v[202:205], v[118:121]
	v_mfma_f32_16x16x32_bf16 v[118:121], v[176:179], v[206:209], v[118:121]
	v_mfma_f32_16x16x32_bf16 v[86:89], v[158:161], v[210:213], v[86:89]
	v_mfma_f32_16x16x32_bf16 v[86:89], v[176:179], v[214:217], v[86:89]
	v_mfma_f32_16x16x32_bf16 v[82:85], v[186:189], v[210:213], v[82:85]
	v_mfma_f32_16x16x32_bf16 v[82:85], v[190:193], v[214:217], v[82:85]
	v_mfma_f32_16x16x32_bf16 v[66:69], v[186:189], v[218:221], v[66:69]
	v_mfma_f32_16x16x32_bf16 v[66:69], v[190:193], v[222:225], v[66:69]
	v_mfma_f32_16x16x32_bf16 v[70:73], v[158:161], v[218:221], v[70:73]
	v_mfma_f32_16x16x32_bf16 v[70:73], v[176:179], v[222:225], v[70:73]
	s_barrier
; #define PG8_STAGE(bufoff, gbase, voff) do { _Pragma("unroll") for (int _i = 0; _i < 2; ++_i) \
;         __builtin_amdgcn_global_load_lds((const unsigned*)((const char*)(gbase) + (voff)[_i]), (PG8_LAS unsigned*)(lds + (bufoff) + ldsw + _i * 8192), 16, 0, 0); } while (0)
; #define PG8_LDA(dst, b, h) do { _Pragma("unroll") for (int m = 0; m < 4; ++m) _Pragma("unroll") for (int k = 0; k < 2; ++k) dst[m][k] = *(const PG8_LAS bf16x8*)(lds + PG8_SA(b, h) + aoff + m * 2048 + k * 1024); } while (0)
; #define PG8_MMA(ai, bj, At, Bt) do { __builtin_amdgcn_s_setprio(1); _Pragma("unroll") for (int m = 0; m < 4; ++m) _Pragma("unroll") for (int n = 0; n < 2; ++n) _Pragma("unroll") for (int k = 0; k < 2; ++k) \
;         acc[ai][bj][m][n] = __builtin_amdgcn_mfma_f32_16x16x32_bf16(Bt[n][k], At[m][k], acc[ai][bj][m][n], 0, 0, 0); __builtin_amdgcn_s_setprio(0); } while (0)
; #define PG8_WAIT_V(n) asm volatile("s_waitcnt vmcnt(" #n ")" ::: "memory")
; #define PG8_WAIT_L(n) asm volatile("s_waitcnt lgkmcnt(" #n ")" ::: "memory")
; #define PG8_BAR __builtin_amdgcn_s_barrier()
; #define PG8_SCHED __builtin_amdgcn_sched_barrier(0)
; template <class Epi, class Sched, bool ALIGN_EPI = false, bool SP2 = false>
; __device__ __forceinline__ void gemm_phase(PG8_LAS unsigned char* lds, const Gemm g, const Sched& S, const Epi& E) {
;     ...
;         for (int t = 0; t < nt; t += 2) {
;             const bool last = (t == nt - 2);
;             const char* a1 = cA + (size_t)(t + 1) * kstep;
;             const char* a2 = last ? nA : cA + (size_t)(t + 2) * kstep; const char* b2 = last ? nB : cB + (size_t)(t + 2) * kstep;
;             const char* a3 = a2 + kstep; const char* b3 = b2 + kstep;
;     ...
;             PG8_LDA(At, 1, 1); PG8_STAGE(PG8_SB(1, 0), b3, voffB); PG8_STAGE(PG8_SB(1, 1), b3 + hstep, voffB); PG8_STAGE(PG8_SA(1, 0), a3, voffA);
;             PG8_WAIT_V(8); PG8_WAIT_L(0); PG8_BAR; PG8_MMA(1, 0, At, B0); PG8_MMA(1, 1, At, B1); PG8_BAR; PG8_SCHED;
	s_setprio 0
	s_add_i32 s10, s10, s6
	v_lshl_add_u64 v[180:181], v[180:181], 0, s[28:29]
	s_mov_b32 m0, s10
	ds_read_b128 v[194:197], v185 offset:49152
	ds_read_b128 v[198:201], v185 offset:50176
	ds_read_b128 v[202:205], v185 offset:51200
	ds_read_b128 v[206:209], v185 offset:52224
	ds_read_b128 v[210:213], v185 offset:53248
	ds_read_b128 v[214:217], v185 offset:54272
	ds_read_b128 v[218:221], v185 offset:55296
	ds_read_b128 v[222:225], v185 offset:56320
	global_load_lds_dwordx4 v[180:181], off
	s_add_i32 m0, s10, 0x2000
	s_add_u32 s46, s46, 0x40080
	v_lshl_add_u64 v[180:181], v[226:227], 0, s[28:29]
	s_addc_u32 s47, s47, 0
	s_add_i32 s10, s11, s6
	global_load_lds_dwordx4 v[180:181], off
	v_lshl_add_u64 v[180:181], s[46:47], 0, v[0:1]
	s_mov_b32 m0, s10
	s_nop 0
	global_load_lds_dwordx4 v[180:181], off
	v_lshl_add_u64 v[180:181], s[46:47], 0, v[146:147]
	s_add_i32 m0, s10, 0x2000
	s_nop 0
	global_load_lds_dwordx4 v[180:181], off
	v_lshl_add_u64 v[180:181], v[238:239], 0, s[28:29]
	s_mov_b32 m0, s52
	s_nop 0
	global_load_lds_dwordx4 v[180:181], off
	v_lshl_add_u64 v[180:181], v[240:241], 0, s[28:29]
	s_mov_b32 m0, s53
	s_nop 0
	global_load_lds_dwordx4 v[180:181], off
	s_waitcnt vmcnt(8)
	s_waitcnt lgkmcnt(0)
	s_setprio 1
	s_barrier
	v_mfma_f32_16x16x32_bf16 v[62:65], v[90:93], v[194:197], v[62:65]
	v_mfma_f32_16x16x32_bf16 v[62:65], v[94:97], v[198:201], v[62:65]
	v_mfma_f32_16x16x32_bf16 v[58:61], v[98:101], v[194:197], v[58:61]
	v_mfma_f32_16x16x32_bf16 v[58:61], v[102:105], v[198:201], v[58:61]
	v_mfma_f32_16x16x32_bf16 v[42:45], v[98:101], v[202:205], v[42:45]
	v_mfma_f32_16x16x32_bf16 v[42:45], v[102:105], v[206:209], v[42:45]
	v_mfma_f32_16x16x32_bf16 v[46:49], v[90:93], v[202:205], v[46:49]
	v_mfma_f32_16x16x32_bf16 v[46:49], v[94:97], v[206:209], v[46:49]
	v_mfma_f32_16x16x32_bf16 v[30:33], v[90:93], v[210:213], v[30:33]
	v_mfma_f32_16x16x32_bf16 v[30:33], v[94:97], v[214:217], v[30:33]
	v_mfma_f32_16x16x32_bf16 v[26:29], v[98:101], v[210:213], v[26:29]
	v_mfma_f32_16x16x32_bf16 v[26:29], v[102:105], v[214:217], v[26:29]
	v_mfma_f32_16x16x32_bf16 v[10:13], v[98:101], v[218:221], v[10:13]
	v_mfma_f32_16x16x32_bf16 v[10:13], v[102:105], v[222:225], v[10:13]
	v_mfma_f32_16x16x32_bf16 v[14:17], v[90:93], v[218:221], v[14:17]
	v_mfma_f32_16x16x32_bf16 v[14:17], v[94:97], v[222:225], v[14:17]
	v_mfma_f32_16x16x32_bf16 v[54:57], v[158:161], v[194:197], v[54:57]
	v_mfma_f32_16x16x32_bf16 v[54:57], v[176:179], v[198:201], v[54:57]
	v_mfma_f32_16x16x32_bf16 v[50:53], v[186:189], v[194:197], v[50:53]
	v_mfma_f32_16x16x32_bf16 v[50:53], v[190:193], v[198:201], v[50:53]
	v_mfma_f32_16x16x32_bf16 v[34:37], v[186:189], v[202:205], v[34:37]
	v_mfma_f32_16x16x32_bf16 v[34:37], v[190:193], v[206:209], v[34:37]
	v_mfma_f32_16x16x32_bf16 v[38:41], v[158:161], v[202:205], v[38:41]
	v_mfma_f32_16x16x32_bf16 v[38:41], v[176:179], v[206:209], v[38:41]
	v_mfma_f32_16x16x32_bf16 v[22:25], v[158:161], v[210:213], v[22:25]
	v_mfma_f32_16x16x32_bf16 v[22:25], v[176:179], v[214:217], v[22:25]
	v_mfma_f32_16x16x32_bf16 v[18:21], v[186:189], v[210:213], v[18:21]
	v_mfma_f32_16x16x32_bf16 v[18:21], v[190:193], v[214:217], v[18:21]
	v_mfma_f32_16x16x32_bf16 v[2:5], v[186:189], v[218:221], v[2:5]
	v_mfma_f32_16x16x32_bf16 v[2:5], v[190:193], v[222:225], v[2:5]
	v_mfma_f32_16x16x32_bf16 v[6:9], v[158:161], v[218:221], v[6:9]
	v_mfma_f32_16x16x32_bf16 v[6:9], v[176:179], v[222:225], v[6:9]
	s_barrier
	s_setprio 0
	s_add_i32 s59, s59, 2
	s_add_u32 s57, s57, 0x100
	s_addc_u32 s58, s58, 0
	s_add_u32 s44, s44, 0x100
	s_addc_u32 s45, s45, 0
	s_cmp_gt_u32 s59, 13

; #define PG8_STAGE(bufoff, gbase, voff) do { _Pragma("unroll") for (int _i = 0; _i < 2; ++_i) \
;         __builtin_amdgcn_global_load_lds((const unsigned*)((const char*)(gbase) + (voff)[_i]), (PG8_LAS unsigned*)(lds + (bufoff) + ldsw + _i * 8192), 16, 0, 0); } while (0)
; #define PG8_LDA(dst, b, h) do { _Pragma("unroll") for (int m = 0; m < 4; ++m) _Pragma("unroll") for (int k = 0; k < 2; ++k) dst[m][k] = *(const PG8_LAS bf16x8*)(lds + PG8_SA(b, h) + aoff + m * 2048 + k * 1024); } while (0)
; #define PG8_LDB(dst, b, h) do { _Pragma("unroll") for (int n = 0; n < 2; ++n) _Pragma("unroll") for (int k = 0; k < 2; ++k) dst[n][k] = *(const PG8_LAS bf16x8*)(lds + PG8_SB(b, h) + boff + n * 2048 + k * 1024); } while (0)
; #define PG8_MMA(ai, bj, At, Bt) do { __builtin_amdgcn_s_setprio(1); _Pragma("unroll") for (int m = 0; m < 4; ++m) _Pragma("unroll") for (int n = 0; n < 2; ++n) _Pragma("unroll") for (int k = 0; k < 2; ++k) \
;         acc[ai][bj][m][n] = __builtin_amdgcn_mfma_f32_16x16x32_bf16(Bt[n][k], At[m][k], acc[ai][bj][m][n], 0, 0, 0); __builtin_amdgcn_s_setprio(0); } while (0)
; #define PG8_BAR __builtin_amdgcn_s_barrier()
; template <class Epi, class Sched, bool ALIGN_EPI = false, bool SP2 = false>
; __device__ __forceinline__ void gemm_phase(PG8_LAS unsigned char* lds, const Gemm g, const Sched& S, const Epi& E) {
;     ...
;         const bool has_next = S.next(ui + 1, nxt);
;         const char* nA = has_next ? (const char*)g.A + (size_t)nxt.pm * tstep : cA; const char* nB = has_next ? (const char*)g.Bt + (size_t)nxt.pn * tstep : cB;
;         for (int t = 0; t < nt; t += 2) {
;             const bool last = (t == nt - 2);
;             const char* a1 = cA + (size_t)(t + 1) * kstep;
;             const char* a2 = last ? nA : cA + (size_t)(t + 2) * kstep; const char* b2 = last ? nB : cB + (size_t)(t + 2) * kstep;
;             const char* a3 = a2 + kstep; const char* b3 = b2 + kstep;
;             if (last && has_next) S.a_ready(nxt);
;             if constexpr (SP2) {
;             PG8_LDB(B0, 0, 0); PG8_LDB(B1, 0, 1); PG8_SCHED; PG8_LDA(At, 0, 0); PG8_STAGE(PG8_SA(1, 1), a1 + hstep, voffA);
;             PG8_WAIT_V(8); PG8_WAIT_L(0); PG8_BAR; PG8_MMA(0, 0, At, B0); PG8_MMA(0, 1, At, B1); PG8_BAR; PG8_SCHED;
;             PG8_LDA(At, 0, 1); PG8_STAGE(PG8_SB(0, 0), b2, voffB); PG8_STAGE(PG8_SB(0, 1), b2 + hstep, voffB); PG8_STAGE(PG8_SA(0, 0), a2, voffA);
.LBB0_242:
	s_ashr_i32 s41, s40, 31
	s_lshl_b64 s[34:35], s[40:41], 19
	s_add_u32 s42, s0, s34
	s_addc_u32 s43, s2, s35
	s_and_b64 s[34:35], s[38:39], exec
	s_cselect_b32 s34, s43, s49
	s_cselect_b32 s35, s42, s48
	s_ashr_i32 s27, s26, 31
	s_lshl_b64 s[44:45], s[26:27], 19
	s_add_u32 s44, s18, s44
	s_addc_u32 s45, s19, s45
	s_and_b64 s[50:51], s[38:39], exec
	s_cselect_b32 s27, s45, s47
	s_cselect_b32 s41, s44, s46
	s_add_u32 s55, s46, 0x100
	s_addc_u32 s56, s47, 0
	s_add_u32 s46, s48, 0x40080
	s_addc_u32 s47, s49, 0
	s_mov_b32 s57, -2
	s_add_u32 s10, s46, 0xfffc0080
	s_addc_u32 s11, s47, -1
	s_add_i32 s58, 16, 0x10000
	s_cmp_eq_u32 s57, 12
	s_cselect_b32 s51, s34, s11
	s_cselect_b32 s50, s35, s10
	s_cselect_b32 s49, s27, s56
	s_cselect_b32 s48, s41, s55
	s_add_i32 s10, 16, 0x14000
	v_add_u32_e32 v156, s58, v141
	v_add_u32_e32 v160, s10, v141
	ds_read_b128 v[144:147], v156
	ds_read_b128 v[148:151], v156 offset:1024
	ds_read_b128 v[152:155], v156 offset:2048
	ds_read_b128 v[156:159], v156 offset:3072
	ds_read_b128 v[176:179], v160
	ds_read_b128 v[180:183], v160 offset:1024
	ds_read_b128 v[184:187], v160 offset:2048
	ds_read_b128 v[188:191], v160 offset:3072
	v_lshl_add_u64 v[160:161], s[46:47], 0, v[138:139]
	s_add_i32 m0, s4, 0xc000
	ds_read_b128 v[192:195], v143
	ds_read_b128 v[196:199], v143 offset:1024
	ds_read_b128 v[200:203], v143 offset:2048
	ds_read_b128 v[204:207], v143 offset:3072
	ds_read_b128 v[208:211], v143 offset:4096
	ds_read_b128 v[212:215], v143 offset:5120
	ds_read_b128 v[216:219], v143 offset:6144
	ds_read_b128 v[220:223], v143 offset:7168
	global_load_lds_dwordx4 v[160:161], off
	v_lshl_add_u64 v[160:161], s[46:47], 0, v[136:137]
	s_add_i32 m0, s4, 0xe000
	s_nop 0
	global_load_lds_dwordx4 v[160:161], off
	s_waitcnt vmcnt(8)
	s_waitcnt lgkmcnt(0)
	s_setprio 1
	s_barrier
	v_mfma_f32_16x16x32_bf16 v[126:129], v[144:147], v[192:195], 0
	v_mfma_f32_16x16x32_bf16 v[126:129], v[148:151], v[196:199], v[126:129]
	v_mfma_f32_16x16x32_bf16 v[122:125], v[152:155], v[192:195], 0
	v_mfma_f32_16x16x32_bf16 v[122:125], v[156:159], v[196:199], v[122:125]
	v_mfma_f32_16x16x32_bf16 v[114:117], v[152:155], v[200:203], 0
	v_mfma_f32_16x16x32_bf16 v[114:117], v[156:159], v[204:207], v[114:117]
	v_mfma_f32_16x16x32_bf16 v[118:121], v[144:147], v[200:203], 0
	v_mfma_f32_16x16x32_bf16 v[118:121], v[148:151], v[204:207], v[118:121]
	v_mfma_f32_16x16x32_bf16 v[102:105], v[144:147], v[208:211], 0
	v_mfma_f32_16x16x32_bf16 v[102:105], v[148:151], v[212:215], v[102:105]
	v_mfma_f32_16x16x32_bf16 v[98:101], v[152:155], v[208:211], 0
	v_mfma_f32_16x16x32_bf16 v[98:101], v[156:159], v[212:215], v[98:101]
	v_mfma_f32_16x16x32_bf16 v[82:85], v[152:155], v[216:219], 0
	v_mfma_f32_16x16x32_bf16 v[82:85], v[156:159], v[220:223], v[82:85]
	v_mfma_f32_16x16x32_bf16 v[86:89], v[144:147], v[216:219], 0
	v_mfma_f32_16x16x32_bf16 v[86:89], v[148:151], v[220:223], v[86:89]
	v_mfma_f32_16x16x32_bf16 v[110:113], v[176:179], v[192:195], 0
	v_mfma_f32_16x16x32_bf16 v[110:113], v[180:183], v[196:199], v[110:113]
	v_mfma_f32_16x16x32_bf16 v[106:109], v[184:187], v[192:195], 0
	v_mfma_f32_16x16x32_bf16 v[106:109], v[188:191], v[196:199], v[106:109]
	v_mfma_f32_16x16x32_bf16 v[90:93], v[184:187], v[200:203], 0
	v_mfma_f32_16x16x32_bf16 v[90:93], v[188:191], v[204:207], v[90:93]
	v_mfma_f32_16x16x32_bf16 v[94:97], v[176:179], v[200:203], 0
	v_mfma_f32_16x16x32_bf16 v[94:97], v[180:183], v[204:207], v[94:97]
	v_mfma_f32_16x16x32_bf16 v[78:81], v[176:179], v[208:211], 0
	v_mfma_f32_16x16x32_bf16 v[78:81], v[180:183], v[212:215], v[78:81]
	v_mfma_f32_16x16x32_bf16 v[74:77], v[184:187], v[208:211], 0
	v_mfma_f32_16x16x32_bf16 v[74:77], v[188:191], v[212:215], v[74:77]
	v_mfma_f32_16x16x32_bf16 v[66:69], v[184:187], v[216:219], 0
	v_mfma_f32_16x16x32_bf16 v[66:69], v[188:191], v[220:223], v[66:69]
	v_mfma_f32_16x16x32_bf16 v[70:73], v[176:179], v[216:219], 0
	v_mfma_f32_16x16x32_bf16 v[70:73], v[180:183], v[220:223], v[70:73]
	s_barrier
	s_setprio 0
	s_add_i32 s11, s58, s3
	v_lshl_add_u64 v[160:161], s[48:49], 0, v[0:1]
	s_mov_b32 m0, s11
	ds_read_b128 v[192:195], v143 offset:16384
	ds_read_b128 v[196:199], v143 offset:17408
	ds_read_b128 v[200:203], v143 offset:18432
	ds_read_b128 v[204:207], v143 offset:19456
	ds_read_b128 v[208:211], v143 offset:20480
	ds_read_b128 v[212:215], v143 offset:21504
	ds_read_b128 v[216:219], v143 offset:22528
	ds_read_b128 v[220:223], v143 offset:23552
	global_load_lds_dwordx4 v[160:161], off
	s_add_i32 m0, s11, 0x2000
	s_add_u32 s58, s48, 0x40000
	v_lshl_add_u64 v[224:225], s[48:49], 0, v[130:131]
	s_addc_u32 s59, s49, 0
	s_add_i32 s10, s10, s3
	global_load_lds_dwordx4 v[224:225], off
	v_lshl_add_u64 v[226:227], s[58:59], 0, v[0:1]
	s_mov_b32 m0, s10
	v_lshl_add_u64 v[238:239], s[50:51], 0, v[132:133]
	global_load_lds_dwordx4 v[226:227], off
	v_lshl_add_u64 v[226:227], s[58:59], 0, v[130:131]
	s_add_i32 m0, s10, 0x2000
	s_nop 0
	global_load_lds_dwordx4 v[226:227], off
	v_lshl_add_u64 v[226:227], s[50:51], 0, v[134:135]
	s_mov_b32 m0, s4
	s_nop 0
	global_load_lds_dwordx4 v[226:227], off
	s_mov_b32 m0, s5
	s_nop 0
	global_load_lds_dwordx4 v[238:239], off
	s_waitcnt vmcnt(8)
	s_waitcnt lgkmcnt(0)
	s_setprio 1
	s_barrier
; #define PG8_STAGE(bufoff, gbase, voff) do { _Pragma("unroll") for (int _i = 0; _i < 2; ++_i) \
;         __builtin_amdgcn_global_load_lds((const unsigned*)((const char*)(gbase) + (voff)[_i]), (PG8_LAS unsigned*)(lds + (bufoff) + ldsw + _i * 8192), 16, 0, 0); } while (0)
; #define PG8_LDA(dst, b, h) do { _Pragma("unroll") for (int m = 0; m < 4; ++m) _Pragma("unroll") for (int k = 0; k < 2; ++k) dst[m][k] = *(const PG8_LAS bf16x8*)(lds + PG8_SA(b, h) + aoff + m * 2048 + k * 1024); } while (0)
; #define PG8_LDB(dst, b, h) do { _Pragma("unroll") for (int n = 0; n < 2; ++n) _Pragma("unroll") for (int k = 0; k < 2; ++k) dst[n][k] = *(const PG8_LAS bf16x8*)(lds + PG8_SB(b, h) + boff + n * 2048 + k * 1024); } while (0)
; #define PG8_MMA(ai, bj, At, Bt) do { __builtin_amdgcn_s_setprio(1); _Pragma("unroll") for (int m = 0; m < 4; ++m) _Pragma("unroll") for (int n = 0; n < 2; ++n) _Pragma("unroll") for (int k = 0; k < 2; ++k) \
;         acc[ai][bj][m][n] = __builtin_amdgcn_mfma_f32_16x16x32_bf16(Bt[n][k], At[m][k], acc[ai][bj][m][n], 0, 0, 0); __builtin_amdgcn_s_setprio(0); } while (0)
; #define PG8_WAIT_V(n) asm volatile("s_waitcnt vmcnt(" #n ")" ::: "memory")
; #define PG8_WAIT_L(n) asm volatile("s_waitcnt lgkmcnt(" #n ")" ::: "memory")
; #define PG8_BAR __builtin_amdgcn_s_barrier()
; #define PG8_SCHED __builtin_amdgcn_sched_barrier(0)
; template <class Epi, class Sched, bool ALIGN_EPI = false, bool SP2 = false>
; __device__ __forceinline__ void gemm_phase(PG8_LAS unsigned char* lds, const Gemm g, const Sched& S, const Epi& E) {
;     ...
;             PG8_WAIT_V(8); PG8_WAIT_L(0); PG8_BAR; PG8_MMA(1, 0, At, B0); PG8_MMA(1, 1, At, B1); PG8_BAR; PG8_SCHED;
;             PG8_LDB(B0, 1, 0); PG8_LDB(B1, 1, 1); PG8_SCHED; PG8_LDA(At, 1, 0); PG8_STAGE(PG8_SA(0, 1), a2 + hstep, voffA);
;             PG8_WAIT_V(8); PG8_WAIT_L(0); PG8_BAR; PG8_MMA(0, 0, At, B0); PG8_MMA(0, 1, At, B1); PG8_BAR; PG8_SCHED;
	v_mfma_f32_16x16x32_bf16 v[62:65], v[144:147], v[192:195], 0
	v_mfma_f32_16x16x32_bf16 v[62:65], v[148:151], v[196:199], v[62:65]
	v_mfma_f32_16x16x32_bf16 v[58:61], v[152:155], v[192:195], 0
	v_mfma_f32_16x16x32_bf16 v[58:61], v[156:159], v[196:199], v[58:61]
	v_mfma_f32_16x16x32_bf16 v[50:53], v[152:155], v[200:203], 0
	v_mfma_f32_16x16x32_bf16 v[50:53], v[156:159], v[204:207], v[50:53]
	v_mfma_f32_16x16x32_bf16 v[54:57], v[144:147], v[200:203], 0
	v_mfma_f32_16x16x32_bf16 v[54:57], v[148:151], v[204:207], v[54:57]
	v_mfma_f32_16x16x32_bf16 v[38:41], v[144:147], v[208:211], 0
	v_mfma_f32_16x16x32_bf16 v[38:41], v[148:151], v[212:215], v[38:41]
	v_mfma_f32_16x16x32_bf16 v[34:37], v[152:155], v[208:211], 0
	v_mfma_f32_16x16x32_bf16 v[34:37], v[156:159], v[212:215], v[34:37]
	v_mfma_f32_16x16x32_bf16 v[18:21], v[152:155], v[216:219], 0
	v_mfma_f32_16x16x32_bf16 v[18:21], v[156:159], v[220:223], v[18:21]
	v_mfma_f32_16x16x32_bf16 v[22:25], v[144:147], v[216:219], 0
	v_mfma_f32_16x16x32_bf16 v[22:25], v[148:151], v[220:223], v[22:25]
	v_mfma_f32_16x16x32_bf16 v[46:49], v[176:179], v[192:195], 0
	v_mfma_f32_16x16x32_bf16 v[46:49], v[180:183], v[196:199], v[46:49]
	v_mfma_f32_16x16x32_bf16 v[42:45], v[184:187], v[192:195], 0
	v_mfma_f32_16x16x32_bf16 v[42:45], v[188:191], v[196:199], v[42:45]
	v_mfma_f32_16x16x32_bf16 v[26:29], v[184:187], v[200:203], 0
	v_mfma_f32_16x16x32_bf16 v[26:29], v[188:191], v[204:207], v[26:29]
	v_mfma_f32_16x16x32_bf16 v[30:33], v[176:179], v[200:203], 0
	v_mfma_f32_16x16x32_bf16 v[30:33], v[180:183], v[204:207], v[30:33]
	v_mfma_f32_16x16x32_bf16 v[14:17], v[176:179], v[208:211], 0
	v_mfma_f32_16x16x32_bf16 v[14:17], v[180:183], v[212:215], v[14:17]
	v_mfma_f32_16x16x32_bf16 v[10:13], v[184:187], v[208:211], 0
	v_mfma_f32_16x16x32_bf16 v[10:13], v[188:191], v[212:215], v[10:13]
	v_mfma_f32_16x16x32_bf16 v[2:5], v[184:187], v[216:219], 0
	v_mfma_f32_16x16x32_bf16 v[2:5], v[188:191], v[220:223], v[2:5]
	v_mfma_f32_16x16x32_bf16 v[6:9], v[176:179], v[216:219], 0
	v_mfma_f32_16x16x32_bf16 v[6:9], v[180:183], v[220:223], v[6:9]
	s_barrier
	s_setprio 0
	s_add_i32 s10, 16, 0x18000
	s_add_i32 s11, 16, 0x1c000
	v_add_u32_e32 v156, s10, v141
	v_add_u32_e32 v188, s11, v141
	ds_read_b128 v[144:147], v156
	ds_read_b128 v[148:151], v156 offset:1024
	ds_read_b128 v[152:155], v156 offset:2048
	ds_read_b128 v[156:159], v156 offset:3072
	ds_read_b128 v[176:179], v188
	ds_read_b128 v[180:183], v188 offset:1024
	ds_read_b128 v[184:187], v188 offset:2048
	ds_read_b128 v[188:191], v188 offset:3072
	s_add_u32 s50, s50, 0x40000
	s_addc_u32 s51, s51, 0
	s_mov_b32 m0, s6
	v_lshl_add_u64 v[240:241], s[50:51], 0, v[134:135]
	ds_read_b128 v[192:195], v143 offset:32768
	ds_read_b128 v[196:199], v143 offset:33792
	ds_read_b128 v[200:203], v143 offset:34816
	ds_read_b128 v[204:207], v143 offset:35840
	ds_read_b128 v[208:211], v143 offset:36864
	ds_read_b128 v[212:215], v143 offset:37888
	ds_read_b128 v[216:219], v143 offset:38912
	ds_read_b128 v[220:223], v143 offset:39936
	global_load_lds_dwordx4 v[240:241], off
	v_lshl_add_u64 v[240:241], s[50:51], 0, v[132:133]
	s_mov_b32 m0, s7
	s_nop 0
	global_load_lds_dwordx4 v[240:241], off
	s_waitcnt vmcnt(8)
	s_waitcnt lgkmcnt(0)
	s_setprio 1
	s_barrier
	v_mfma_f32_16x16x32_bf16 v[126:129], v[144:147], v[192:195], v[126:129]
	v_mfma_f32_16x16x32_bf16 v[126:129], v[148:151], v[196:199], v[126:129]
	v_mfma_f32_16x16x32_bf16 v[122:125], v[152:155], v[192:195], v[122:125]
	v_mfma_f32_16x16x32_bf16 v[122:125], v[156:159], v[196:199], v[122:125]
	v_mfma_f32_16x16x32_bf16 v[114:117], v[152:155], v[200:203], v[114:117]
	v_mfma_f32_16x16x32_bf16 v[114:117], v[156:159], v[204:207], v[114:117]
	v_mfma_f32_16x16x32_bf16 v[118:121], v[144:147], v[200:203], v[118:121]
	v_mfma_f32_16x16x32_bf16 v[118:121], v[148:151], v[204:207], v[118:121]
	v_mfma_f32_16x16x32_bf16 v[102:105], v[144:147], v[208:211], v[102:105]
	v_mfma_f32_16x16x32_bf16 v[102:105], v[148:151], v[212:215], v[102:105]
	v_mfma_f32_16x16x32_bf16 v[98:101], v[152:155], v[208:211], v[98:101]
	v_mfma_f32_16x16x32_bf16 v[98:101], v[156:159], v[212:215], v[98:101]
	v_mfma_f32_16x16x32_bf16 v[82:85], v[152:155], v[216:219], v[82:85]
	v_mfma_f32_16x16x32_bf16 v[82:85], v[156:159], v[220:223], v[82:85]
	v_mfma_f32_16x16x32_bf16 v[86:89], v[144:147], v[216:219], v[86:89]
	v_mfma_f32_16x16x32_bf16 v[86:89], v[148:151], v[220:223], v[86:89]
	v_mfma_f32_16x16x32_bf16 v[110:113], v[176:179], v[192:195], v[110:113]
	v_mfma_f32_16x16x32_bf16 v[110:113], v[180:183], v[196:199], v[110:113]
	v_mfma_f32_16x16x32_bf16 v[106:109], v[184:187], v[192:195], v[106:109]
	v_mfma_f32_16x16x32_bf16 v[106:109], v[188:191], v[196:199], v[106:109]
	v_mfma_f32_16x16x32_bf16 v[90:93], v[184:187], v[200:203], v[90:93]
	v_mfma_f32_16x16x32_bf16 v[90:93], v[188:191], v[204:207], v[90:93]
	v_mfma_f32_16x16x32_bf16 v[94:97], v[176:179], v[200:203], v[94:97]
	v_mfma_f32_16x16x32_bf16 v[94:97], v[180:183], v[204:207], v[94:97]
	v_mfma_f32_16x16x32_bf16 v[78:81], v[176:179], v[208:211], v[78:81]
	v_mfma_f32_16x16x32_bf16 v[78:81], v[180:183], v[212:215], v[78:81]
	v_mfma_f32_16x16x32_bf16 v[74:77], v[184:187], v[208:211], v[74:77]
	v_mfma_f32_16x16x32_bf16 v[74:77], v[188:191], v[212:215], v[74:77]
	v_mfma_f32_16x16x32_bf16 v[66:69], v[184:187], v[216:219], v[66:69]
	v_mfma_f32_16x16x32_bf16 v[66:69], v[188:191], v[220:223], v[66:69]
	v_mfma_f32_16x16x32_bf16 v[70:73], v[176:179], v[216:219], v[70:73]
	v_mfma_f32_16x16x32_bf16 v[70:73], v[180:183], v[220:223], v[70:73]
	s_barrier
; #define PG8_STAGE(bufoff, gbase, voff) do { _Pragma("unroll") for (int _i = 0; _i < 2; ++_i) \
;         __builtin_amdgcn_global_load_lds((const unsigned*)((const char*)(gbase) + (voff)[_i]), (PG8_LAS unsigned*)(lds + (bufoff) + ldsw + _i * 8192), 16, 0, 0); } while (0)
; #define PG8_LDA(dst, b, h) do { _Pragma("unroll") for (int m = 0; m < 4; ++m) _Pragma("unroll") for (int k = 0; k < 2; ++k) dst[m][k] = *(const PG8_LAS bf16x8*)(lds + PG8_SA(b, h) + aoff + m * 2048 + k * 1024); } while (0)
; #define PG8_MMA(ai, bj, At, Bt) do { __builtin_amdgcn_s_setprio(1); _Pragma("unroll") for (int m = 0; m < 4; ++m) _Pragma("unroll") for (int n = 0; n < 2; ++n) _Pragma("unroll") for (int k = 0; k < 2; ++k) \
;         acc[ai][bj][m][n] = __builtin_amdgcn_mfma_f32_16x16x32_bf16(Bt[n][k], At[m][k], acc[ai][bj][m][n], 0, 0, 0); __builtin_amdgcn_s_setprio(0); } while (0)
; #define PG8_WAIT_V(n) asm volatile("s_waitcnt vmcnt(" #n ")" ::: "memory")
; #define PG8_WAIT_L(n) asm volatile("s_waitcnt lgkmcnt(" #n ")" ::: "memory")
; #define PG8_BAR __builtin_amdgcn_s_barrier()
; #define PG8_SCHED __builtin_amdgcn_sched_barrier(0)
; template <class Epi, class Sched, bool ALIGN_EPI = false, bool SP2 = false>
; __device__ __forceinline__ void gemm_phase(PG8_LAS unsigned char* lds, const Gemm g, const Sched& S, const Epi& E) {
;     ...
;         for (int t = 0; t < nt; t += 2) {
;             const bool last = (t == nt - 2);
;             const char* a1 = cA + (size_t)(t + 1) * kstep;
;             const char* a2 = last ? nA : cA + (size_t)(t + 2) * kstep; const char* b2 = last ? nB : cB + (size_t)(t + 2) * kstep;
;             const char* a3 = a2 + kstep; const char* b3 = b2 + kstep;
;     ...
;             PG8_LDA(At, 1, 1); PG8_STAGE(PG8_SB(1, 0), b3, voffB); PG8_STAGE(PG8_SB(1, 1), b3 + hstep, voffB); PG8_STAGE(PG8_SA(1, 0), a3, voffA);
;             PG8_WAIT_V(8); PG8_WAIT_L(0); PG8_BAR; PG8_MMA(1, 0, At, B0); PG8_MMA(1, 1, At, B1); PG8_BAR; PG8_SCHED;
	s_setprio 0
	s_add_i32 s10, s10, s3
	v_lshl_add_u64 v[160:161], v[160:161], 0, s[28:29]
	s_mov_b32 m0, s10
	ds_read_b128 v[192:195], v143 offset:49152
	ds_read_b128 v[196:199], v143 offset:50176
	ds_read_b128 v[200:203], v143 offset:51200
	ds_read_b128 v[204:207], v143 offset:52224
	ds_read_b128 v[208:211], v143 offset:53248
	ds_read_b128 v[212:215], v143 offset:54272
	ds_read_b128 v[216:219], v143 offset:55296
	ds_read_b128 v[220:223], v143 offset:56320
	global_load_lds_dwordx4 v[160:161], off
	s_add_i32 m0, s10, 0x2000
	s_add_u32 s48, s48, 0x40080
	v_lshl_add_u64 v[160:161], v[224:225], 0, s[28:29]
	s_addc_u32 s49, s49, 0
	s_add_i32 s10, s11, s3
	global_load_lds_dwordx4 v[160:161], off
	v_lshl_add_u64 v[160:161], s[48:49], 0, v[0:1]
	s_mov_b32 m0, s10
	s_nop 0
	global_load_lds_dwordx4 v[160:161], off
	v_lshl_add_u64 v[160:161], s[48:49], 0, v[130:131]
	s_add_i32 m0, s10, 0x2000
	s_nop 0
	global_load_lds_dwordx4 v[160:161], off
	v_lshl_add_u64 v[160:161], v[226:227], 0, s[28:29]
	s_mov_b32 m0, s8
	s_nop 0
	global_load_lds_dwordx4 v[160:161], off
	v_lshl_add_u64 v[160:161], v[238:239], 0, s[28:29]
	s_mov_b32 m0, s9
	s_nop 0
	global_load_lds_dwordx4 v[160:161], off
	s_waitcnt vmcnt(8)
	s_waitcnt lgkmcnt(0)
	s_setprio 1
	s_barrier
	v_mfma_f32_16x16x32_bf16 v[62:65], v[144:147], v[192:195], v[62:65]
	v_mfma_f32_16x16x32_bf16 v[62:65], v[148:151], v[196:199], v[62:65]
	v_mfma_f32_16x16x32_bf16 v[58:61], v[152:155], v[192:195], v[58:61]
	v_mfma_f32_16x16x32_bf16 v[58:61], v[156:159], v[196:199], v[58:61]
	v_mfma_f32_16x16x32_bf16 v[50:53], v[152:155], v[200:203], v[50:53]
	v_mfma_f32_16x16x32_bf16 v[50:53], v[156:159], v[204:207], v[50:53]
	v_mfma_f32_16x16x32_bf16 v[54:57], v[144:147], v[200:203], v[54:57]
	v_mfma_f32_16x16x32_bf16 v[54:57], v[148:151], v[204:207], v[54:57]
	v_mfma_f32_16x16x32_bf16 v[38:41], v[144:147], v[208:211], v[38:41]
	v_mfma_f32_16x16x32_bf16 v[38:41], v[148:151], v[212:215], v[38:41]
	v_mfma_f32_16x16x32_bf16 v[34:37], v[152:155], v[208:211], v[34:37]
	v_mfma_f32_16x16x32_bf16 v[34:37], v[156:159], v[212:215], v[34:37]
	v_mfma_f32_16x16x32_bf16 v[18:21], v[152:155], v[216:219], v[18:21]
	v_mfma_f32_16x16x32_bf16 v[18:21], v[156:159], v[220:223], v[18:21]
	v_mfma_f32_16x16x32_bf16 v[22:25], v[144:147], v[216:219], v[22:25]
	v_mfma_f32_16x16x32_bf16 v[22:25], v[148:151], v[220:223], v[22:25]
	v_mfma_f32_16x16x32_bf16 v[46:49], v[176:179], v[192:195], v[46:49]
	v_mfma_f32_16x16x32_bf16 v[46:49], v[180:183], v[196:199], v[46:49]
	v_mfma_f32_16x16x32_bf16 v[42:45], v[184:187], v[192:195], v[42:45]
	v_mfma_f32_16x16x32_bf16 v[42:45], v[188:191], v[196:199], v[42:45]
	v_mfma_f32_16x16x32_bf16 v[26:29], v[184:187], v[200:203], v[26:29]
	v_mfma_f32_16x16x32_bf16 v[26:29], v[188:191], v[204:207], v[26:29]
	v_mfma_f32_16x16x32_bf16 v[30:33], v[176:179], v[200:203], v[30:33]
	v_mfma_f32_16x16x32_bf16 v[30:33], v[180:183], v[204:207], v[30:33]
	v_mfma_f32_16x16x32_bf16 v[14:17], v[176:179], v[208:211], v[14:17]
	v_mfma_f32_16x16x32_bf16 v[14:17], v[180:183], v[212:215], v[14:17]
	v_mfma_f32_16x16x32_bf16 v[10:13], v[184:187], v[208:211], v[10:13]
	v_mfma_f32_16x16x32_bf16 v[10:13], v[188:191], v[212:215], v[10:13]
	v_mfma_f32_16x16x32_bf16 v[2:5], v[184:187], v[216:219], v[2:5]
	v_mfma_f32_16x16x32_bf16 v[2:5], v[188:191], v[220:223], v[2:5]
	v_mfma_f32_16x16x32_bf16 v[6:9], v[176:179], v[216:219], v[6:9]
	v_mfma_f32_16x16x32_bf16 v[6:9], v[180:183], v[220:223], v[6:9]
	s_barrier
	s_setprio 0
	s_add_i32 s57, s57, 2
	s_add_u32 s55, s55, 0x100
	s_addc_u32 s56, s56, 0
	s_add_u32 s46, s46, 0x100
	s_addc_u32 s47, s47, 0
	s_cmp_gt_u32 s57, 13

; #define PG8_STAGE(bufoff, gbase, voff) do { _Pragma("unroll") for (int _i = 0; _i < 2; ++_i) \
;         __builtin_amdgcn_global_load_lds((const unsigned*)((const char*)(gbase) + (voff)[_i]), (PG8_LAS unsigned*)(lds + (bufoff) + ldsw + _i * 8192), 16, 0, 0); } while (0)
; #define PG8_LDA(dst, b, h) do { _Pragma("unroll") for (int m = 0; m < 4; ++m) _Pragma("unroll") for (int k = 0; k < 2; ++k) dst[m][k] = *(const PG8_LAS bf16x8*)(lds + PG8_SA(b, h) + aoff + m * 2048 + k * 1024); } while (0)
; #define PG8_LDB(dst, b, h) do { _Pragma("unroll") for (int n = 0; n < 2; ++n) _Pragma("unroll") for (int k = 0; k < 2; ++k) dst[n][k] = *(const PG8_LAS bf16x8*)(lds + PG8_SB(b, h) + boff + n * 2048 + k * 1024); } while (0)
; #define PG8_MMA(ai, bj, At, Bt) do { __builtin_amdgcn_s_setprio(1); _Pragma("unroll") for (int m = 0; m < 4; ++m) _Pragma("unroll") for (int n = 0; n < 2; ++n) _Pragma("unroll") for (int k = 0; k < 2; ++k) \
;         acc[ai][bj][m][n] = __builtin_amdgcn_mfma_f32_16x16x32_bf16(Bt[n][k], At[m][k], acc[ai][bj][m][n], 0, 0, 0); __builtin_amdgcn_s_setprio(0); } while (0)
; #define PG8_BAR __builtin_amdgcn_s_barrier()
; template <class Epi, class Sched, bool ALIGN_EPI = false, bool SP2 = false>
; __device__ __forceinline__ void gemm_phase(PG8_LAS unsigned char* lds, const Gemm g, const Sched& S, const Epi& E) {
;     ...
;         const bool has_next = S.next(ui + 1, nxt);
;         const char* nA = has_next ? (const char*)g.A + (size_t)nxt.pm * tstep : cA; const char* nB = has_next ? (const char*)g.Bt + (size_t)nxt.pn * tstep : cB;
;         for (int t = 0; t < nt; t += 2) {
;             const bool last = (t == nt - 2);
;             const char* a1 = cA + (size_t)(t + 1) * kstep;
;             const char* a2 = last ? nA : cA + (size_t)(t + 2) * kstep; const char* b2 = last ? nB : cB + (size_t)(t + 2) * kstep;
;             const char* a3 = a2 + kstep; const char* b3 = b2 + kstep;
;             if (last && has_next) S.a_ready(nxt);
;             if constexpr (SP2) {
;             PG8_LDB(B0, 0, 0); PG8_LDB(B1, 0, 1); PG8_SCHED; PG8_LDA(At, 0, 0); PG8_STAGE(PG8_SA(1, 1), a1 + hstep, voffA);
;             PG8_WAIT_V(8); PG8_WAIT_L(0); PG8_BAR; PG8_MMA(0, 0, At, B0); PG8_MMA(0, 1, At, B1); PG8_BAR; PG8_SCHED;
;             PG8_LDA(At, 0, 1); PG8_STAGE(PG8_SB(0, 0), b2, voffB); PG8_STAGE(PG8_SB(0, 1), b2 + hstep, voffB); PG8_STAGE(PG8_SA(0, 0), a2, voffA);
.LBB0_914:
	s_ashr_i32 s27, s26, 31
	s_lshl_b64 s[8:9], s[26:27], 19
	s_add_u32 s64, s4, s8
	s_addc_u32 s65, s5, s9
	s_and_b64 s[8:9], s[40:41], exec
	s_cselect_b32 s0, s65, s69
	s_cselect_b32 s8, s64, s68
	s_ashr_i32 s23, s22, 31
	s_lshl_b64 s[10:11], s[22:23], 19
	s_add_u32 s66, s52, s10
	s_addc_u32 s67, s53, s11
	s_and_b64 s[10:11], s[40:41], exec
	s_cselect_b32 s9, s67, s43
	s_cselect_b32 s23, s66, s42
	s_add_u32 s25, s42, 0x100
	s_addc_u32 s27, s43, 0
	s_add_u32 s42, s68, 0x40080
	s_addc_u32 s43, s69, 0
	s_mov_b32 s34, -2
	s_add_u32 s10, s42, 0xfffc0080
	s_addc_u32 s11, s43, -1
	s_add_i32 s35, 16, 0x10000
	s_cmp_eq_u32 s34, 12
	s_cselect_b32 s73, s0, s11
	s_cselect_b32 s72, s8, s10
	s_cselect_b32 s69, s9, s27
	s_cselect_b32 s68, s23, s25
	s_add_i32 s45, 16, 0x14000
	v_add_u32_e32 v78, s35, v197
	v_add_u32_e32 v94, s45, v197
	ds_read_b128 v[58:61], v78
	ds_read_b128 v[62:65], v78 offset:1024
	ds_read_b128 v[74:77], v78 offset:2048
	ds_read_b128 v[78:81], v78 offset:3072
	ds_read_b128 v[82:85], v94
	ds_read_b128 v[86:89], v94 offset:1024
	ds_read_b128 v[90:93], v94 offset:2048
	ds_read_b128 v[94:97], v94 offset:3072
	v_lshl_add_u64 v[194:195], s[42:43], 0, v[184:185]
	s_add_i32 m0, s77, 0xc000
	ds_read_b128 v[186:189], v199
	ds_read_b128 v[190:193], v199 offset:1024
	ds_read_b128 v[200:203], v199 offset:2048
	ds_read_b128 v[204:207], v199 offset:3072
	ds_read_b128 v[208:211], v199 offset:4096
	ds_read_b128 v[212:215], v199 offset:5120
	ds_read_b128 v[216:219], v199 offset:6144
	ds_read_b128 v[220:223], v199 offset:7168
	global_load_lds_dwordx4 v[194:195], off
	v_lshl_add_u64 v[194:195], s[42:43], 0, v[182:183]
	s_add_i32 m0, s77, 0xe000
	s_nop 0
	global_load_lds_dwordx4 v[194:195], off
	s_waitcnt vmcnt(8)
	s_waitcnt lgkmcnt(0)
	s_setprio 1
	s_barrier
	v_mfma_f32_16x16x32_bf16 v[158:161], v[58:61], v[186:189], 0
	v_mfma_f32_16x16x32_bf16 v[158:161], v[62:65], v[190:193], v[158:161]
	v_mfma_f32_16x16x32_bf16 v[154:157], v[74:77], v[186:189], 0
	v_mfma_f32_16x16x32_bf16 v[154:157], v[78:81], v[190:193], v[154:157]
	v_mfma_f32_16x16x32_bf16 v[138:141], v[74:77], v[200:203], 0
	v_mfma_f32_16x16x32_bf16 v[138:141], v[78:81], v[204:207], v[138:141]
	v_mfma_f32_16x16x32_bf16 v[142:145], v[58:61], v[200:203], 0
	v_mfma_f32_16x16x32_bf16 v[142:145], v[62:65], v[204:207], v[142:145]
	v_mfma_f32_16x16x32_bf16 v[126:129], v[58:61], v[208:211], 0
	v_mfma_f32_16x16x32_bf16 v[126:129], v[62:65], v[212:215], v[126:129]
	v_mfma_f32_16x16x32_bf16 v[122:125], v[74:77], v[208:211], 0
	v_mfma_f32_16x16x32_bf16 v[122:125], v[78:81], v[212:215], v[122:125]
	v_mfma_f32_16x16x32_bf16 v[106:109], v[74:77], v[216:219], 0
	v_mfma_f32_16x16x32_bf16 v[106:109], v[78:81], v[220:223], v[106:109]
	v_mfma_f32_16x16x32_bf16 v[110:113], v[58:61], v[216:219], 0
	v_mfma_f32_16x16x32_bf16 v[110:113], v[62:65], v[220:223], v[110:113]
	v_mfma_f32_16x16x32_bf16 v[150:153], v[82:85], v[186:189], 0
	v_mfma_f32_16x16x32_bf16 v[150:153], v[86:89], v[190:193], v[150:153]
	v_mfma_f32_16x16x32_bf16 v[146:149], v[90:93], v[186:189], 0
	v_mfma_f32_16x16x32_bf16 v[146:149], v[94:97], v[190:193], v[146:149]
	v_mfma_f32_16x16x32_bf16 v[130:133], v[90:93], v[200:203], 0
	v_mfma_f32_16x16x32_bf16 v[130:133], v[94:97], v[204:207], v[130:133]
	v_mfma_f32_16x16x32_bf16 v[134:137], v[82:85], v[200:203], 0
	v_mfma_f32_16x16x32_bf16 v[134:137], v[86:89], v[204:207], v[134:137]
	v_mfma_f32_16x16x32_bf16 v[118:121], v[82:85], v[208:211], 0
	v_mfma_f32_16x16x32_bf16 v[118:121], v[86:89], v[212:215], v[118:121]
	v_mfma_f32_16x16x32_bf16 v[114:117], v[90:93], v[208:211], 0
	v_mfma_f32_16x16x32_bf16 v[114:117], v[94:97], v[212:215], v[114:117]
	v_mfma_f32_16x16x32_bf16 v[98:101], v[90:93], v[216:219], 0
	v_mfma_f32_16x16x32_bf16 v[98:101], v[94:97], v[220:223], v[98:101]
	v_mfma_f32_16x16x32_bf16 v[102:105], v[82:85], v[216:219], 0
	v_mfma_f32_16x16x32_bf16 v[102:105], v[86:89], v[220:223], v[102:105]
	s_barrier
	s_setprio 0
	s_add_i32 s10, s35, s76
	v_lshl_add_u64 v[194:195], s[68:69], 0, v[0:1]
	s_mov_b32 m0, s10
	ds_read_b128 v[186:189], v199 offset:16384
	ds_read_b128 v[190:193], v199 offset:17408
	ds_read_b128 v[200:203], v199 offset:18432
	ds_read_b128 v[204:207], v199 offset:19456
	ds_read_b128 v[208:211], v199 offset:20480
	ds_read_b128 v[212:215], v199 offset:21504
	ds_read_b128 v[216:219], v199 offset:22528
	ds_read_b128 v[220:223], v199 offset:23552
	global_load_lds_dwordx4 v[194:195], off
	s_add_i32 m0, s10, 0x2000
	s_add_u32 s10, s68, 0x40000
	v_lshl_add_u64 v[224:225], s[68:69], 0, v[180:181]
	s_addc_u32 s11, s69, 0
	s_add_i32 s35, s45, s76
	global_load_lds_dwordx4 v[224:225], off
	v_lshl_add_u64 v[226:227], s[10:11], 0, v[0:1]
	s_mov_b32 m0, s35
	v_lshl_add_u64 v[238:239], s[72:73], 0, v[178:179]
	global_load_lds_dwordx4 v[226:227], off
	v_lshl_add_u64 v[226:227], s[10:11], 0, v[180:181]
	s_add_i32 m0, s35, 0x2000
	s_nop 0
	global_load_lds_dwordx4 v[226:227], off
	v_lshl_add_u64 v[226:227], s[72:73], 0, v[176:177]
	s_mov_b32 m0, s77
	s_nop 0
	global_load_lds_dwordx4 v[226:227], off
	s_mov_b32 m0, s2
	s_nop 0
	global_load_lds_dwordx4 v[238:239], off
	s_waitcnt vmcnt(8)
	s_waitcnt lgkmcnt(0)
	s_setprio 1
	s_barrier
; #define PG8_STAGE(bufoff, gbase, voff) do { _Pragma("unroll") for (int _i = 0; _i < 2; ++_i) \
;         __builtin_amdgcn_global_load_lds((const unsigned*)((const char*)(gbase) + (voff)[_i]), (PG8_LAS unsigned*)(lds + (bufoff) + ldsw + _i * 8192), 16, 0, 0); } while (0)
; #define PG8_LDA(dst, b, h) do { _Pragma("unroll") for (int m = 0; m < 4; ++m) _Pragma("unroll") for (int k = 0; k < 2; ++k) dst[m][k] = *(const PG8_LAS bf16x8*)(lds + PG8_SA(b, h) + aoff + m * 2048 + k * 1024); } while (0)
; #define PG8_LDB(dst, b, h) do { _Pragma("unroll") for (int n = 0; n < 2; ++n) _Pragma("unroll") for (int k = 0; k < 2; ++k) dst[n][k] = *(const PG8_LAS bf16x8*)(lds + PG8_SB(b, h) + boff + n * 2048 + k * 1024); } while (0)
; #define PG8_MMA(ai, bj, At, Bt) do { __builtin_amdgcn_s_setprio(1); _Pragma("unroll") for (int m = 0; m < 4; ++m) _Pragma("unroll") for (int n = 0; n < 2; ++n) _Pragma("unroll") for (int k = 0; k < 2; ++k) \
;         acc[ai][bj][m][n] = __builtin_amdgcn_mfma_f32_16x16x32_bf16(Bt[n][k], At[m][k], acc[ai][bj][m][n], 0, 0, 0); __builtin_amdgcn_s_setprio(0); } while (0)
; #define PG8_WAIT_V(n) asm volatile("s_waitcnt vmcnt(" #n ")" ::: "memory")
; #define PG8_WAIT_L(n) asm volatile("s_waitcnt lgkmcnt(" #n ")" ::: "memory")
; #define PG8_BAR __builtin_amdgcn_s_barrier()
; #define PG8_SCHED __builtin_amdgcn_sched_barrier(0)
; template <class Epi, class Sched, bool ALIGN_EPI = false, bool SP2 = false>
; __device__ __forceinline__ void gemm_phase(PG8_LAS unsigned char* lds, const Gemm g, const Sched& S, const Epi& E) {
;     ...
;             PG8_WAIT_V(8); PG8_WAIT_L(0); PG8_BAR; PG8_MMA(1, 0, At, B0); PG8_MMA(1, 1, At, B1); PG8_BAR; PG8_SCHED;
;             PG8_LDB(B0, 1, 0); PG8_LDB(B1, 1, 1); PG8_SCHED; PG8_LDA(At, 1, 0); PG8_STAGE(PG8_SA(0, 1), a2 + hstep, voffA);
;             PG8_WAIT_V(8); PG8_WAIT_L(0); PG8_BAR; PG8_MMA(0, 0, At, B0); PG8_MMA(0, 1, At, B1); PG8_BAR; PG8_SCHED;
	v_mfma_f32_16x16x32_bf16 v[70:73], v[58:61], v[186:189], 0
	v_mfma_f32_16x16x32_bf16 v[70:73], v[62:65], v[190:193], v[70:73]
	v_mfma_f32_16x16x32_bf16 v[66:69], v[74:77], v[186:189], 0
	v_mfma_f32_16x16x32_bf16 v[66:69], v[78:81], v[190:193], v[66:69]
	v_mfma_f32_16x16x32_bf16 v[42:45], v[74:77], v[200:203], 0
	v_mfma_f32_16x16x32_bf16 v[42:45], v[78:81], v[204:207], v[42:45]
	v_mfma_f32_16x16x32_bf16 v[46:49], v[58:61], v[200:203], 0
	v_mfma_f32_16x16x32_bf16 v[46:49], v[62:65], v[204:207], v[46:49]
	v_mfma_f32_16x16x32_bf16 v[30:33], v[58:61], v[208:211], 0
	v_mfma_f32_16x16x32_bf16 v[30:33], v[62:65], v[212:215], v[30:33]
	v_mfma_f32_16x16x32_bf16 v[26:29], v[74:77], v[208:211], 0
	v_mfma_f32_16x16x32_bf16 v[26:29], v[78:81], v[212:215], v[26:29]
	v_mfma_f32_16x16x32_bf16 v[10:13], v[74:77], v[216:219], 0
	v_mfma_f32_16x16x32_bf16 v[10:13], v[78:81], v[220:223], v[10:13]
	v_mfma_f32_16x16x32_bf16 v[14:17], v[58:61], v[216:219], 0
	v_mfma_f32_16x16x32_bf16 v[14:17], v[62:65], v[220:223], v[14:17]
	v_mfma_f32_16x16x32_bf16 v[54:57], v[82:85], v[186:189], 0
	v_mfma_f32_16x16x32_bf16 v[54:57], v[86:89], v[190:193], v[54:57]
	v_mfma_f32_16x16x32_bf16 v[50:53], v[90:93], v[186:189], 0
	v_mfma_f32_16x16x32_bf16 v[50:53], v[94:97], v[190:193], v[50:53]
	v_mfma_f32_16x16x32_bf16 v[34:37], v[90:93], v[200:203], 0
	v_mfma_f32_16x16x32_bf16 v[34:37], v[94:97], v[204:207], v[34:37]
	v_mfma_f32_16x16x32_bf16 v[38:41], v[82:85], v[200:203], 0
	v_mfma_f32_16x16x32_bf16 v[38:41], v[86:89], v[204:207], v[38:41]
	v_mfma_f32_16x16x32_bf16 v[22:25], v[82:85], v[208:211], 0
	v_mfma_f32_16x16x32_bf16 v[22:25], v[86:89], v[212:215], v[22:25]
	v_mfma_f32_16x16x32_bf16 v[18:21], v[90:93], v[208:211], 0
	v_mfma_f32_16x16x32_bf16 v[18:21], v[94:97], v[212:215], v[18:21]
	v_mfma_f32_16x16x32_bf16 v[2:5], v[90:93], v[216:219], 0
	v_mfma_f32_16x16x32_bf16 v[2:5], v[94:97], v[220:223], v[2:5]
	v_mfma_f32_16x16x32_bf16 v[6:9], v[82:85], v[216:219], 0
	v_mfma_f32_16x16x32_bf16 v[6:9], v[86:89], v[220:223], v[6:9]
	s_barrier
	s_setprio 0
	s_add_i32 s35, 16, 0x18000
	s_add_i32 s45, 16, 0x1c000
	v_add_u32_e32 v78, s35, v197
	v_add_u32_e32 v94, s45, v197
	ds_read_b128 v[58:61], v78
	ds_read_b128 v[62:65], v78 offset:1024
	ds_read_b128 v[74:77], v78 offset:2048
	ds_read_b128 v[78:81], v78 offset:3072
	ds_read_b128 v[82:85], v94
	ds_read_b128 v[86:89], v94 offset:1024
	ds_read_b128 v[90:93], v94 offset:2048
	ds_read_b128 v[94:97], v94 offset:3072
	s_add_u32 s10, s72, 0x40000
	s_addc_u32 s11, s73, 0
	s_mov_b32 m0, s3
	v_lshl_add_u64 v[240:241], s[10:11], 0, v[176:177]
	ds_read_b128 v[186:189], v199 offset:32768
	ds_read_b128 v[190:193], v199 offset:33792
	ds_read_b128 v[200:203], v199 offset:34816
	ds_read_b128 v[204:207], v199 offset:35840
	ds_read_b128 v[208:211], v199 offset:36864
	ds_read_b128 v[212:215], v199 offset:37888
	ds_read_b128 v[216:219], v199 offset:38912
	ds_read_b128 v[220:223], v199 offset:39936
	global_load_lds_dwordx4 v[240:241], off
	v_lshl_add_u64 v[240:241], s[10:11], 0, v[178:179]
	s_mov_b32 m0, s78
	s_nop 0
	global_load_lds_dwordx4 v[240:241], off
	s_waitcnt vmcnt(8)
	s_waitcnt lgkmcnt(0)
	s_setprio 1
	s_barrier
	v_mfma_f32_16x16x32_bf16 v[158:161], v[58:61], v[186:189], v[158:161]
	v_mfma_f32_16x16x32_bf16 v[158:161], v[62:65], v[190:193], v[158:161]
	v_mfma_f32_16x16x32_bf16 v[154:157], v[74:77], v[186:189], v[154:157]
	v_mfma_f32_16x16x32_bf16 v[154:157], v[78:81], v[190:193], v[154:157]
	v_mfma_f32_16x16x32_bf16 v[138:141], v[74:77], v[200:203], v[138:141]
	v_mfma_f32_16x16x32_bf16 v[138:141], v[78:81], v[204:207], v[138:141]
	v_mfma_f32_16x16x32_bf16 v[142:145], v[58:61], v[200:203], v[142:145]
	v_mfma_f32_16x16x32_bf16 v[142:145], v[62:65], v[204:207], v[142:145]
	v_mfma_f32_16x16x32_bf16 v[126:129], v[58:61], v[208:211], v[126:129]
	v_mfma_f32_16x16x32_bf16 v[126:129], v[62:65], v[212:215], v[126:129]
	v_mfma_f32_16x16x32_bf16 v[122:125], v[74:77], v[208:211], v[122:125]
	v_mfma_f32_16x16x32_bf16 v[122:125], v[78:81], v[212:215], v[122:125]
	v_mfma_f32_16x16x32_bf16 v[106:109], v[74:77], v[216:219], v[106:109]
	v_mfma_f32_16x16x32_bf16 v[106:109], v[78:81], v[220:223], v[106:109]
	v_mfma_f32_16x16x32_bf16 v[110:113], v[58:61], v[216:219], v[110:113]
	v_mfma_f32_16x16x32_bf16 v[110:113], v[62:65], v[220:223], v[110:113]
	v_mfma_f32_16x16x32_bf16 v[150:153], v[82:85], v[186:189], v[150:153]
	v_mfma_f32_16x16x32_bf16 v[150:153], v[86:89], v[190:193], v[150:153]
	v_mfma_f32_16x16x32_bf16 v[146:149], v[90:93], v[186:189], v[146:149]
	v_mfma_f32_16x16x32_bf16 v[146:149], v[94:97], v[190:193], v[146:149]
	v_mfma_f32_16x16x32_bf16 v[130:133], v[90:93], v[200:203], v[130:133]
	v_mfma_f32_16x16x32_bf16 v[130:133], v[94:97], v[204:207], v[130:133]
	v_mfma_f32_16x16x32_bf16 v[134:137], v[82:85], v[200:203], v[134:137]
	v_mfma_f32_16x16x32_bf16 v[134:137], v[86:89], v[204:207], v[134:137]
	v_mfma_f32_16x16x32_bf16 v[118:121], v[82:85], v[208:211], v[118:121]
	v_mfma_f32_16x16x32_bf16 v[118:121], v[86:89], v[212:215], v[118:121]
	v_mfma_f32_16x16x32_bf16 v[114:117], v[90:93], v[208:211], v[114:117]
	v_mfma_f32_16x16x32_bf16 v[114:117], v[94:97], v[212:215], v[114:117]
	v_mfma_f32_16x16x32_bf16 v[98:101], v[90:93], v[216:219], v[98:101]
	v_mfma_f32_16x16x32_bf16 v[98:101], v[94:97], v[220:223], v[98:101]
	v_mfma_f32_16x16x32_bf16 v[102:105], v[82:85], v[216:219], v[102:105]
	v_mfma_f32_16x16x32_bf16 v[102:105], v[86:89], v[220:223], v[102:105]
	s_barrier
; #define PG8_STAGE(bufoff, gbase, voff) do { _Pragma("unroll") for (int _i = 0; _i < 2; ++_i) \
;         __builtin_amdgcn_global_load_lds((const unsigned*)((const char*)(gbase) + (voff)[_i]), (PG8_LAS unsigned*)(lds + (bufoff) + ldsw + _i * 8192), 16, 0, 0); } while (0)
; #define PG8_LDA(dst, b, h) do { _Pragma("unroll") for (int m = 0; m < 4; ++m) _Pragma("unroll") for (int k = 0; k < 2; ++k) dst[m][k] = *(const PG8_LAS bf16x8*)(lds + PG8_SA(b, h) + aoff + m * 2048 + k * 1024); } while (0)
; #define PG8_MMA(ai, bj, At, Bt) do { __builtin_amdgcn_s_setprio(1); _Pragma("unroll") for (int m = 0; m < 4; ++m) _Pragma("unroll") for (int n = 0; n < 2; ++n) _Pragma("unroll") for (int k = 0; k < 2; ++k) \
;         acc[ai][bj][m][n] = __builtin_amdgcn_mfma_f32_16x16x32_bf16(Bt[n][k], At[m][k], acc[ai][bj][m][n], 0, 0, 0); __builtin_amdgcn_s_setprio(0); } while (0)
; #define PG8_WAIT_V(n) asm volatile("s_waitcnt vmcnt(" #n ")" ::: "memory")
; #define PG8_WAIT_L(n) asm volatile("s_waitcnt lgkmcnt(" #n ")" ::: "memory")
; #define PG8_BAR __builtin_amdgcn_s_barrier()
; #define PG8_SCHED __builtin_amdgcn_sched_barrier(0)
; template <class Epi, class Sched, bool ALIGN_EPI = false, bool SP2 = false>
; __device__ __forceinline__ void gemm_phase(PG8_LAS unsigned char* lds, const Gemm g, const Sched& S, const Epi& E) {
;     ...
;         for (int t = 0; t < nt; t += 2) {
;             const bool last = (t == nt - 2);
;             const char* a1 = cA + (size_t)(t + 1) * kstep;
;             const char* a2 = last ? nA : cA + (size_t)(t + 2) * kstep; const char* b2 = last ? nB : cB + (size_t)(t + 2) * kstep;
;             const char* a3 = a2 + kstep; const char* b3 = b2 + kstep;
;     ...
;             PG8_LDA(At, 1, 1); PG8_STAGE(PG8_SB(1, 0), b3, voffB); PG8_STAGE(PG8_SB(1, 1), b3 + hstep, voffB); PG8_STAGE(PG8_SA(1, 0), a3, voffA);
;             PG8_WAIT_V(8); PG8_WAIT_L(0); PG8_BAR; PG8_MMA(1, 0, At, B0); PG8_MMA(1, 1, At, B1); PG8_BAR; PG8_SCHED;
	s_setprio 0
	s_add_i32 s10, s35, s76
	v_lshl_add_u64 v[194:195], v[194:195], 0, s[28:29]
	s_mov_b32 m0, s10
	ds_read_b128 v[186:189], v199 offset:49152
	ds_read_b128 v[190:193], v199 offset:50176
	ds_read_b128 v[200:203], v199 offset:51200
	ds_read_b128 v[204:207], v199 offset:52224
	ds_read_b128 v[208:211], v199 offset:53248
	ds_read_b128 v[212:215], v199 offset:54272
	ds_read_b128 v[216:219], v199 offset:55296
	ds_read_b128 v[220:223], v199 offset:56320
	global_load_lds_dwordx4 v[194:195], off
	s_add_i32 m0, s10, 0x2000
	s_add_u32 s10, s68, 0x40080
	v_lshl_add_u64 v[194:195], v[224:225], 0, s[28:29]
	s_addc_u32 s11, s69, 0
	s_add_i32 s35, s45, s76
	global_load_lds_dwordx4 v[194:195], off
	v_lshl_add_u64 v[194:195], s[10:11], 0, v[0:1]
	s_mov_b32 m0, s35
	s_nop 0
	global_load_lds_dwordx4 v[194:195], off
	v_lshl_add_u64 v[194:195], s[10:11], 0, v[180:181]
	s_add_i32 m0, s35, 0x2000
	s_nop 0
	global_load_lds_dwordx4 v[194:195], off
	v_lshl_add_u64 v[194:195], v[226:227], 0, s[28:29]
	s_mov_b32 m0, s94
	s_nop 0
	global_load_lds_dwordx4 v[194:195], off
	v_lshl_add_u64 v[194:195], v[238:239], 0, s[28:29]
	s_mov_b32 m0, s95
	s_nop 0
	global_load_lds_dwordx4 v[194:195], off
	s_waitcnt vmcnt(8)
	s_waitcnt lgkmcnt(0)
	s_setprio 1
	s_barrier
	v_mfma_f32_16x16x32_bf16 v[70:73], v[58:61], v[186:189], v[70:73]
	v_mfma_f32_16x16x32_bf16 v[70:73], v[62:65], v[190:193], v[70:73]
	v_mfma_f32_16x16x32_bf16 v[66:69], v[74:77], v[186:189], v[66:69]
	v_mfma_f32_16x16x32_bf16 v[66:69], v[78:81], v[190:193], v[66:69]
	v_mfma_f32_16x16x32_bf16 v[42:45], v[74:77], v[200:203], v[42:45]
	v_mfma_f32_16x16x32_bf16 v[42:45], v[78:81], v[204:207], v[42:45]
	v_mfma_f32_16x16x32_bf16 v[46:49], v[58:61], v[200:203], v[46:49]
	v_mfma_f32_16x16x32_bf16 v[46:49], v[62:65], v[204:207], v[46:49]
	v_mfma_f32_16x16x32_bf16 v[30:33], v[58:61], v[208:211], v[30:33]
	v_mfma_f32_16x16x32_bf16 v[30:33], v[62:65], v[212:215], v[30:33]
	v_mfma_f32_16x16x32_bf16 v[26:29], v[74:77], v[208:211], v[26:29]
	v_mfma_f32_16x16x32_bf16 v[26:29], v[78:81], v[212:215], v[26:29]
	v_mfma_f32_16x16x32_bf16 v[10:13], v[74:77], v[216:219], v[10:13]
	v_mfma_f32_16x16x32_bf16 v[10:13], v[78:81], v[220:223], v[10:13]
	v_mfma_f32_16x16x32_bf16 v[14:17], v[58:61], v[216:219], v[14:17]
	v_mfma_f32_16x16x32_bf16 v[14:17], v[62:65], v[220:223], v[14:17]
	v_mfma_f32_16x16x32_bf16 v[54:57], v[82:85], v[186:189], v[54:57]
	v_mfma_f32_16x16x32_bf16 v[54:57], v[86:89], v[190:193], v[54:57]
	v_mfma_f32_16x16x32_bf16 v[50:53], v[90:93], v[186:189], v[50:53]
	v_mfma_f32_16x16x32_bf16 v[50:53], v[94:97], v[190:193], v[50:53]
	v_mfma_f32_16x16x32_bf16 v[34:37], v[90:93], v[200:203], v[34:37]
	v_mfma_f32_16x16x32_bf16 v[34:37], v[94:97], v[204:207], v[34:37]
	v_mfma_f32_16x16x32_bf16 v[38:41], v[82:85], v[200:203], v[38:41]
	v_mfma_f32_16x16x32_bf16 v[38:41], v[86:89], v[204:207], v[38:41]
	v_mfma_f32_16x16x32_bf16 v[22:25], v[82:85], v[208:211], v[22:25]
	v_mfma_f32_16x16x32_bf16 v[22:25], v[86:89], v[212:215], v[22:25]
	v_mfma_f32_16x16x32_bf16 v[18:21], v[90:93], v[208:211], v[18:21]
	v_mfma_f32_16x16x32_bf16 v[18:21], v[94:97], v[212:215], v[18:21]
	v_mfma_f32_16x16x32_bf16 v[2:5], v[90:93], v[216:219], v[2:5]
	v_mfma_f32_16x16x32_bf16 v[2:5], v[94:97], v[220:223], v[2:5]
	v_mfma_f32_16x16x32_bf16 v[6:9], v[82:85], v[216:219], v[6:9]
	v_mfma_f32_16x16x32_bf16 v[6:9], v[86:89], v[220:223], v[6:9]
	s_barrier
	s_setprio 0
	s_add_i32 s34, s34, 2
	s_add_u32 s25, s25, 0x100
	s_addc_u32 s27, s27, 0
	s_add_u32 s42, s42, 0x100
	s_addc_u32 s43, s43, 0
	s_cmp_gt_u32 s34, 13

; #define PG8_STAGE(bufoff, gbase, voff) do { _Pragma("unroll") for (int _i = 0; _i < 2; ++_i) \
;         __builtin_amdgcn_global_load_lds((const unsigned*)((const char*)(gbase) + (voff)[_i]), (PG8_LAS unsigned*)(lds + (bufoff) + ldsw + _i * 8192), 16, 0, 0); } while (0)
; #define PG8_LDA(dst, b, h) do { _Pragma("unroll") for (int m = 0; m < 4; ++m) _Pragma("unroll") for (int k = 0; k < 2; ++k) dst[m][k] = *(const PG8_LAS bf16x8*)(lds + PG8_SA(b, h) + aoff + m * 2048 + k * 1024); } while (0)
; #define PG8_LDB(dst, b, h) do { _Pragma("unroll") for (int n = 0; n < 2; ++n) _Pragma("unroll") for (int k = 0; k < 2; ++k) dst[n][k] = *(const PG8_LAS bf16x8*)(lds + PG8_SB(b, h) + boff + n * 2048 + k * 1024); } while (0)
; #define PG8_MMA(ai, bj, At, Bt) do { __builtin_amdgcn_s_setprio(1); _Pragma("unroll") for (int m = 0; m < 4; ++m) _Pragma("unroll") for (int n = 0; n < 2; ++n) _Pragma("unroll") for (int k = 0; k < 2; ++k) \
;         acc[ai][bj][m][n] = __builtin_amdgcn_mfma_f32_16x16x32_bf16(Bt[n][k], At[m][k], acc[ai][bj][m][n], 0, 0, 0); __builtin_amdgcn_s_setprio(0); } while (0)
; #define PG8_BAR __builtin_amdgcn_s_barrier()
; template <class Epi, class Sched, bool ALIGN_EPI = false, bool SP2 = false>
; __device__ __forceinline__ void gemm_phase(PG8_LAS unsigned char* lds, const Gemm g, const Sched& S, const Epi& E) {
;     ...
;         const bool has_next = S.next(ui + 1, nxt);
;         const char* nA = has_next ? (const char*)g.A + (size_t)nxt.pm * tstep : cA; const char* nB = has_next ? (const char*)g.Bt + (size_t)nxt.pn * tstep : cB;
;         for (int t = 0; t < nt; t += 2) {
;             const bool last = (t == nt - 2);
;             const char* a1 = cA + (size_t)(t + 1) * kstep;
;             const char* a2 = last ? nA : cA + (size_t)(t + 2) * kstep; const char* b2 = last ? nB : cB + (size_t)(t + 2) * kstep;
;             const char* a3 = a2 + kstep; const char* b3 = b2 + kstep;
;             if (last && has_next) S.a_ready(nxt);
;             if constexpr (SP2) {
;             PG8_LDB(B0, 0, 0); PG8_LDB(B1, 0, 1); PG8_SCHED; PG8_LDA(At, 0, 0); PG8_STAGE(PG8_SA(1, 1), a1 + hstep, voffA);
;             PG8_WAIT_V(8); PG8_WAIT_L(0); PG8_BAR; PG8_MMA(0, 0, At, B0); PG8_MMA(0, 1, At, B1); PG8_BAR; PG8_SCHED;
;             PG8_LDA(At, 0, 1); PG8_STAGE(PG8_SB(0, 0), b2, voffB); PG8_STAGE(PG8_SB(0, 1), b2 + hstep, voffB); PG8_STAGE(PG8_SA(0, 0), a2, voffA);
.LBB0_1032:
	s_and_b64 s[98:99], s[38:39], exec
	s_cselect_b32 s71, s42, s40
	s_cselect_b32 s73, s26, s41
	s_ashr_i32 s43, s42, 31
	s_lshl_b64 s[10:11], s[42:43], 19
	s_add_u32 s44, s2, s10
	s_addc_u32 s45, s3, s11
	s_and_b64 s[10:11], s[38:39], exec
	s_cselect_b32 s34, s45, s59
	s_cselect_b32 s35, s44, s58
	s_ashr_i32 s27, s26, 31
	s_lshl_b64 s[10:11], s[26:27], 19
	s_add_u32 s48, s4, s10
	s_addc_u32 s49, s5, s11
	s_and_b64 s[10:11], s[38:39], exec
	s_cselect_b32 s27, s49, s51
	s_cselect_b32 s43, s48, s50
	s_add_u32 s66, s50, 0x100
	s_addc_u32 s67, s51, 0
	s_add_u32 s50, s58, 0x40080
	s_addc_u32 s51, s59, 0
	s_mov_b32 s68, -2
	s_add_u32 s10, s50, 0xfffc0080
	s_addc_u32 s11, s51, -1
	s_add_i32 s69, 16, 0x10000
	s_cmp_eq_u32 s68, 12
	s_cselect_b32 s61, s34, s11
	s_cselect_b32 s60, s35, s10
	s_cselect_b32 s59, s27, s67
	s_cselect_b32 s58, s43, s66
	s_add_i32 s72, 16, 0x14000
	v_add_u32_e32 v142, s69, v177
	v_add_u32_e32 v188, s72, v177
	ds_read_b128 v[130:133], v142
	ds_read_b128 v[134:137], v142 offset:1024
	ds_read_b128 v[138:141], v142 offset:2048
	ds_read_b128 v[142:145], v142 offset:3072
	ds_read_b128 v[158:161], v188
	ds_read_b128 v[180:183], v188 offset:1024
	ds_read_b128 v[184:187], v188 offset:2048
	ds_read_b128 v[188:191], v188 offset:3072
	v_lshl_add_u64 v[224:225], s[50:51], 0, v[156:157]
	s_add_i32 m0, s9, 0xc000
	ds_read_b128 v[192:195], v179
	ds_read_b128 v[196:199], v179 offset:1024
	ds_read_b128 v[200:203], v179 offset:2048
	ds_read_b128 v[204:207], v179 offset:3072
	ds_read_b128 v[208:211], v179 offset:4096
	ds_read_b128 v[212:215], v179 offset:5120
	ds_read_b128 v[216:219], v179 offset:6144
	ds_read_b128 v[220:223], v179 offset:7168
	global_load_lds_dwordx4 v[224:225], off
	v_lshl_add_u64 v[224:225], s[50:51], 0, v[154:155]
	s_add_i32 m0, s9, 0xe000
	s_nop 0
	global_load_lds_dwordx4 v[224:225], off
	s_waitcnt vmcnt(8)
	s_waitcnt lgkmcnt(0)
	s_setprio 1
	s_barrier
	v_mfma_f32_16x16x32_bf16 v[126:129], v[130:133], v[192:195], 0
	v_mfma_f32_16x16x32_bf16 v[126:129], v[134:137], v[196:199], v[126:129]
	v_mfma_f32_16x16x32_bf16 v[122:125], v[138:141], v[192:195], 0
	v_mfma_f32_16x16x32_bf16 v[122:125], v[142:145], v[196:199], v[122:125]
	v_mfma_f32_16x16x32_bf16 v[106:109], v[138:141], v[200:203], 0
	v_mfma_f32_16x16x32_bf16 v[106:109], v[142:145], v[204:207], v[106:109]
	v_mfma_f32_16x16x32_bf16 v[110:113], v[130:133], v[200:203], 0
	v_mfma_f32_16x16x32_bf16 v[110:113], v[134:137], v[204:207], v[110:113]
	v_mfma_f32_16x16x32_bf16 v[94:97], v[130:133], v[208:211], 0
	v_mfma_f32_16x16x32_bf16 v[94:97], v[134:137], v[212:215], v[94:97]
	v_mfma_f32_16x16x32_bf16 v[90:93], v[138:141], v[208:211], 0
	v_mfma_f32_16x16x32_bf16 v[90:93], v[142:145], v[212:215], v[90:93]
	v_mfma_f32_16x16x32_bf16 v[74:77], v[138:141], v[216:219], 0
	v_mfma_f32_16x16x32_bf16 v[74:77], v[142:145], v[220:223], v[74:77]
	v_mfma_f32_16x16x32_bf16 v[78:81], v[130:133], v[216:219], 0
	v_mfma_f32_16x16x32_bf16 v[78:81], v[134:137], v[220:223], v[78:81]
	v_mfma_f32_16x16x32_bf16 v[118:121], v[158:161], v[192:195], 0
	v_mfma_f32_16x16x32_bf16 v[118:121], v[180:183], v[196:199], v[118:121]
	v_mfma_f32_16x16x32_bf16 v[114:117], v[184:187], v[192:195], 0
	v_mfma_f32_16x16x32_bf16 v[114:117], v[188:191], v[196:199], v[114:117]
	v_mfma_f32_16x16x32_bf16 v[98:101], v[184:187], v[200:203], 0
	v_mfma_f32_16x16x32_bf16 v[98:101], v[188:191], v[204:207], v[98:101]
	v_mfma_f32_16x16x32_bf16 v[102:105], v[158:161], v[200:203], 0
	v_mfma_f32_16x16x32_bf16 v[102:105], v[180:183], v[204:207], v[102:105]
	v_mfma_f32_16x16x32_bf16 v[86:89], v[158:161], v[208:211], 0
	v_mfma_f32_16x16x32_bf16 v[86:89], v[180:183], v[212:215], v[86:89]
	v_mfma_f32_16x16x32_bf16 v[82:85], v[184:187], v[208:211], 0
	v_mfma_f32_16x16x32_bf16 v[82:85], v[188:191], v[212:215], v[82:85]
	v_mfma_f32_16x16x32_bf16 v[66:69], v[184:187], v[216:219], 0
	v_mfma_f32_16x16x32_bf16 v[66:69], v[188:191], v[220:223], v[66:69]
	v_mfma_f32_16x16x32_bf16 v[70:73], v[158:161], v[216:219], 0
	v_mfma_f32_16x16x32_bf16 v[70:73], v[180:183], v[220:223], v[70:73]
	s_barrier
	s_setprio 0
	s_add_i32 s10, s69, s6
	v_lshl_add_u64 v[224:225], s[58:59], 0, v[0:1]
	s_mov_b32 m0, s10
	ds_read_b128 v[192:195], v179 offset:16384
	ds_read_b128 v[196:199], v179 offset:17408
	ds_read_b128 v[200:203], v179 offset:18432
	ds_read_b128 v[204:207], v179 offset:19456
	ds_read_b128 v[208:211], v179 offset:20480
	ds_read_b128 v[212:215], v179 offset:21504
	ds_read_b128 v[216:219], v179 offset:22528
	ds_read_b128 v[220:223], v179 offset:23552
	global_load_lds_dwordx4 v[224:225], off
	s_add_i32 m0, s10, 0x2000
	s_add_u32 s10, s58, 0x40000
	v_lshl_add_u64 v[226:227], s[58:59], 0, v[146:147]
	s_addc_u32 s11, s59, 0
	s_add_i32 s69, s72, s6
	global_load_lds_dwordx4 v[226:227], off
	v_lshl_add_u64 v[238:239], s[10:11], 0, v[0:1]
	s_mov_b32 m0, s69
	v_lshl_add_u64 v[240:241], s[60:61], 0, v[148:149]
	global_load_lds_dwordx4 v[238:239], off
	v_lshl_add_u64 v[238:239], s[10:11], 0, v[146:147]
	s_add_i32 m0, s69, 0x2000
	s_nop 0
	global_load_lds_dwordx4 v[238:239], off
	v_lshl_add_u64 v[238:239], s[60:61], 0, v[150:151]
	s_mov_b32 m0, s9
	s_nop 0
	global_load_lds_dwordx4 v[238:239], off
	s_mov_b32 m0, s54
	s_nop 0
	global_load_lds_dwordx4 v[240:241], off
	s_waitcnt vmcnt(8)
	s_waitcnt lgkmcnt(0)
	s_setprio 1
	s_barrier
; #define PG8_STAGE(bufoff, gbase, voff) do { _Pragma("unroll") for (int _i = 0; _i < 2; ++_i) \
;         __builtin_amdgcn_global_load_lds((const unsigned*)((const char*)(gbase) + (voff)[_i]), (PG8_LAS unsigned*)(lds + (bufoff) + ldsw + _i * 8192), 16, 0, 0); } while (0)
; #define PG8_LDA(dst, b, h) do { _Pragma("unroll") for (int m = 0; m < 4; ++m) _Pragma("unroll") for (int k = 0; k < 2; ++k) dst[m][k] = *(const PG8_LAS bf16x8*)(lds + PG8_SA(b, h) + aoff + m * 2048 + k * 1024); } while (0)
; #define PG8_LDB(dst, b, h) do { _Pragma("unroll") for (int n = 0; n < 2; ++n) _Pragma("unroll") for (int k = 0; k < 2; ++k) dst[n][k] = *(const PG8_LAS bf16x8*)(lds + PG8_SB(b, h) + boff + n * 2048 + k * 1024); } while (0)
; #define PG8_MMA(ai, bj, At, Bt) do { __builtin_amdgcn_s_setprio(1); _Pragma("unroll") for (int m = 0; m < 4; ++m) _Pragma("unroll") for (int n = 0; n < 2; ++n) _Pragma("unroll") for (int k = 0; k < 2; ++k) \
;         acc[ai][bj][m][n] = __builtin_amdgcn_mfma_f32_16x16x32_bf16(Bt[n][k], At[m][k], acc[ai][bj][m][n], 0, 0, 0); __builtin_amdgcn_s_setprio(0); } while (0)
; #define PG8_WAIT_V(n) asm volatile("s_waitcnt vmcnt(" #n ")" ::: "memory")
; #define PG8_WAIT_L(n) asm volatile("s_waitcnt lgkmcnt(" #n ")" ::: "memory")
; #define PG8_BAR __builtin_amdgcn_s_barrier()
; #define PG8_SCHED __builtin_amdgcn_sched_barrier(0)
; template <class Epi, class Sched, bool ALIGN_EPI = false, bool SP2 = false>
; __device__ __forceinline__ void gemm_phase(PG8_LAS unsigned char* lds, const Gemm g, const Sched& S, const Epi& E) {
;     ...
;             PG8_WAIT_V(8); PG8_WAIT_L(0); PG8_BAR; PG8_MMA(1, 0, At, B0); PG8_MMA(1, 1, At, B1); PG8_BAR; PG8_SCHED;
;             PG8_LDB(B0, 1, 0); PG8_LDB(B1, 1, 1); PG8_SCHED; PG8_LDA(At, 1, 0); PG8_STAGE(PG8_SA(0, 1), a2 + hstep, voffA);
;             PG8_WAIT_V(8); PG8_WAIT_L(0); PG8_BAR; PG8_MMA(0, 0, At, B0); PG8_MMA(0, 1, At, B1); PG8_BAR; PG8_SCHED;
	v_mfma_f32_16x16x32_bf16 v[62:65], v[130:133], v[192:195], 0
	v_mfma_f32_16x16x32_bf16 v[62:65], v[134:137], v[196:199], v[62:65]
	v_mfma_f32_16x16x32_bf16 v[58:61], v[138:141], v[192:195], 0
	v_mfma_f32_16x16x32_bf16 v[58:61], v[142:145], v[196:199], v[58:61]
	v_mfma_f32_16x16x32_bf16 v[42:45], v[138:141], v[200:203], 0
	v_mfma_f32_16x16x32_bf16 v[42:45], v[142:145], v[204:207], v[42:45]
	v_mfma_f32_16x16x32_bf16 v[46:49], v[130:133], v[200:203], 0
	v_mfma_f32_16x16x32_bf16 v[46:49], v[134:137], v[204:207], v[46:49]
	v_mfma_f32_16x16x32_bf16 v[30:33], v[130:133], v[208:211], 0
	v_mfma_f32_16x16x32_bf16 v[30:33], v[134:137], v[212:215], v[30:33]
	v_mfma_f32_16x16x32_bf16 v[26:29], v[138:141], v[208:211], 0
	v_mfma_f32_16x16x32_bf16 v[26:29], v[142:145], v[212:215], v[26:29]
	v_mfma_f32_16x16x32_bf16 v[10:13], v[138:141], v[216:219], 0
	v_mfma_f32_16x16x32_bf16 v[10:13], v[142:145], v[220:223], v[10:13]
	v_mfma_f32_16x16x32_bf16 v[14:17], v[130:133], v[216:219], 0
	v_mfma_f32_16x16x32_bf16 v[14:17], v[134:137], v[220:223], v[14:17]
	v_mfma_f32_16x16x32_bf16 v[54:57], v[158:161], v[192:195], 0
	v_mfma_f32_16x16x32_bf16 v[54:57], v[180:183], v[196:199], v[54:57]
	v_mfma_f32_16x16x32_bf16 v[50:53], v[184:187], v[192:195], 0
	v_mfma_f32_16x16x32_bf16 v[50:53], v[188:191], v[196:199], v[50:53]
	v_mfma_f32_16x16x32_bf16 v[34:37], v[184:187], v[200:203], 0
	v_mfma_f32_16x16x32_bf16 v[34:37], v[188:191], v[204:207], v[34:37]
	v_mfma_f32_16x16x32_bf16 v[38:41], v[158:161], v[200:203], 0
	v_mfma_f32_16x16x32_bf16 v[38:41], v[180:183], v[204:207], v[38:41]
	v_mfma_f32_16x16x32_bf16 v[22:25], v[158:161], v[208:211], 0
	v_mfma_f32_16x16x32_bf16 v[22:25], v[180:183], v[212:215], v[22:25]
	v_mfma_f32_16x16x32_bf16 v[18:21], v[184:187], v[208:211], 0
	v_mfma_f32_16x16x32_bf16 v[18:21], v[188:191], v[212:215], v[18:21]
	v_mfma_f32_16x16x32_bf16 v[2:5], v[184:187], v[216:219], 0
	v_mfma_f32_16x16x32_bf16 v[2:5], v[188:191], v[220:223], v[2:5]
	v_mfma_f32_16x16x32_bf16 v[6:9], v[158:161], v[216:219], 0
	v_mfma_f32_16x16x32_bf16 v[6:9], v[180:183], v[220:223], v[6:9]
	s_barrier
	s_setprio 0
	s_add_i32 s69, 16, 0x18000
	s_add_i32 s72, 16, 0x1c000
	v_add_u32_e32 v142, s69, v177
	v_add_u32_e32 v188, s72, v177
	ds_read_b128 v[130:133], v142
	ds_read_b128 v[134:137], v142 offset:1024
	ds_read_b128 v[138:141], v142 offset:2048
	ds_read_b128 v[142:145], v142 offset:3072
	ds_read_b128 v[158:161], v188
	ds_read_b128 v[180:183], v188 offset:1024
	ds_read_b128 v[184:187], v188 offset:2048
	ds_read_b128 v[188:191], v188 offset:3072
	s_add_u32 s10, s60, 0x40000
	s_addc_u32 s11, s61, 0
	s_mov_b32 m0, s55
	v_lshl_add_u64 v[242:243], s[10:11], 0, v[150:151]
	ds_read_b128 v[192:195], v179 offset:32768
	ds_read_b128 v[196:199], v179 offset:33792
	ds_read_b128 v[200:203], v179 offset:34816
	ds_read_b128 v[204:207], v179 offset:35840
	ds_read_b128 v[208:211], v179 offset:36864
	ds_read_b128 v[212:215], v179 offset:37888
	ds_read_b128 v[216:219], v179 offset:38912
	ds_read_b128 v[220:223], v179 offset:39936
	global_load_lds_dwordx4 v[242:243], off
	v_lshl_add_u64 v[242:243], s[10:11], 0, v[148:149]
	s_mov_b32 m0, s56
	s_nop 0
	global_load_lds_dwordx4 v[242:243], off
	s_waitcnt vmcnt(8)
	s_waitcnt lgkmcnt(0)
	s_setprio 1
	s_barrier
	v_mfma_f32_16x16x32_bf16 v[126:129], v[130:133], v[192:195], v[126:129]
	v_mfma_f32_16x16x32_bf16 v[126:129], v[134:137], v[196:199], v[126:129]
	v_mfma_f32_16x16x32_bf16 v[122:125], v[138:141], v[192:195], v[122:125]
	v_mfma_f32_16x16x32_bf16 v[122:125], v[142:145], v[196:199], v[122:125]
	v_mfma_f32_16x16x32_bf16 v[106:109], v[138:141], v[200:203], v[106:109]
	v_mfma_f32_16x16x32_bf16 v[106:109], v[142:145], v[204:207], v[106:109]
	v_mfma_f32_16x16x32_bf16 v[110:113], v[130:133], v[200:203], v[110:113]
	v_mfma_f32_16x16x32_bf16 v[110:113], v[134:137], v[204:207], v[110:113]
	v_mfma_f32_16x16x32_bf16 v[94:97], v[130:133], v[208:211], v[94:97]
	v_mfma_f32_16x16x32_bf16 v[94:97], v[134:137], v[212:215], v[94:97]
	v_mfma_f32_16x16x32_bf16 v[90:93], v[138:141], v[208:211], v[90:93]
	v_mfma_f32_16x16x32_bf16 v[90:93], v[142:145], v[212:215], v[90:93]
	v_mfma_f32_16x16x32_bf16 v[74:77], v[138:141], v[216:219], v[74:77]
	v_mfma_f32_16x16x32_bf16 v[74:77], v[142:145], v[220:223], v[74:77]
	v_mfma_f32_16x16x32_bf16 v[78:81], v[130:133], v[216:219], v[78:81]
	v_mfma_f32_16x16x32_bf16 v[78:81], v[134:137], v[220:223], v[78:81]
	v_mfma_f32_16x16x32_bf16 v[118:121], v[158:161], v[192:195], v[118:121]
	v_mfma_f32_16x16x32_bf16 v[118:121], v[180:183], v[196:199], v[118:121]
	v_mfma_f32_16x16x32_bf16 v[114:117], v[184:187], v[192:195], v[114:117]
	v_mfma_f32_16x16x32_bf16 v[114:117], v[188:191], v[196:199], v[114:117]
	v_mfma_f32_16x16x32_bf16 v[98:101], v[184:187], v[200:203], v[98:101]
	v_mfma_f32_16x16x32_bf16 v[98:101], v[188:191], v[204:207], v[98:101]
	v_mfma_f32_16x16x32_bf16 v[102:105], v[158:161], v[200:203], v[102:105]
	v_mfma_f32_16x16x32_bf16 v[102:105], v[180:183], v[204:207], v[102:105]
	v_mfma_f32_16x16x32_bf16 v[86:89], v[158:161], v[208:211], v[86:89]
	v_mfma_f32_16x16x32_bf16 v[86:89], v[180:183], v[212:215], v[86:89]
	v_mfma_f32_16x16x32_bf16 v[82:85], v[184:187], v[208:211], v[82:85]
	v_mfma_f32_16x16x32_bf16 v[82:85], v[188:191], v[212:215], v[82:85]
	v_mfma_f32_16x16x32_bf16 v[66:69], v[184:187], v[216:219], v[66:69]
	v_mfma_f32_16x16x32_bf16 v[66:69], v[188:191], v[220:223], v[66:69]
	v_mfma_f32_16x16x32_bf16 v[70:73], v[158:161], v[216:219], v[70:73]
	v_mfma_f32_16x16x32_bf16 v[70:73], v[180:183], v[220:223], v[70:73]
	s_barrier
; #define PG8_STAGE(bufoff, gbase, voff) do { _Pragma("unroll") for (int _i = 0; _i < 2; ++_i) \
;         __builtin_amdgcn_global_load_lds((const unsigned*)((const char*)(gbase) + (voff)[_i]), (PG8_LAS unsigned*)(lds + (bufoff) + ldsw + _i * 8192), 16, 0, 0); } while (0)
; #define PG8_LDA(dst, b, h) do { _Pragma("unroll") for (int m = 0; m < 4; ++m) _Pragma("unroll") for (int k = 0; k < 2; ++k) dst[m][k] = *(const PG8_LAS bf16x8*)(lds + PG8_SA(b, h) + aoff + m * 2048 + k * 1024); } while (0)
; #define PG8_MMA(ai, bj, At, Bt) do { __builtin_amdgcn_s_setprio(1); _Pragma("unroll") for (int m = 0; m < 4; ++m) _Pragma("unroll") for (int n = 0; n < 2; ++n) _Pragma("unroll") for (int k = 0; k < 2; ++k) \
;         acc[ai][bj][m][n] = __builtin_amdgcn_mfma_f32_16x16x32_bf16(Bt[n][k], At[m][k], acc[ai][bj][m][n], 0, 0, 0); __builtin_amdgcn_s_setprio(0); } while (0)
; #define PG8_WAIT_V(n) asm volatile("s_waitcnt vmcnt(" #n ")" ::: "memory")
; #define PG8_WAIT_L(n) asm volatile("s_waitcnt lgkmcnt(" #n ")" ::: "memory")
; #define PG8_BAR __builtin_amdgcn_s_barrier()
; #define PG8_SCHED __builtin_amdgcn_sched_barrier(0)
; template <class Epi, class Sched, bool ALIGN_EPI = false, bool SP2 = false>
; __device__ __forceinline__ void gemm_phase(PG8_LAS unsigned char* lds, const Gemm g, const Sched& S, const Epi& E) {
;     ...
;         for (int t = 0; t < nt; t += 2) {
;             const bool last = (t == nt - 2);
;             const char* a1 = cA + (size_t)(t + 1) * kstep;
;             const char* a2 = last ? nA : cA + (size_t)(t + 2) * kstep; const char* b2 = last ? nB : cB + (size_t)(t + 2) * kstep;
;             const char* a3 = a2 + kstep; const char* b3 = b2 + kstep;
;     ...
;             PG8_LDA(At, 1, 1); PG8_STAGE(PG8_SB(1, 0), b3, voffB); PG8_STAGE(PG8_SB(1, 1), b3 + hstep, voffB); PG8_STAGE(PG8_SA(1, 0), a3, voffA);
;             PG8_WAIT_V(8); PG8_WAIT_L(0); PG8_BAR; PG8_MMA(1, 0, At, B0); PG8_MMA(1, 1, At, B1); PG8_BAR; PG8_SCHED;
	s_setprio 0
	s_add_i32 s10, s69, s6
	v_lshl_add_u64 v[224:225], v[224:225], 0, s[28:29]
	s_mov_b32 m0, s10
	ds_read_b128 v[192:195], v179 offset:49152
	ds_read_b128 v[196:199], v179 offset:50176
	ds_read_b128 v[200:203], v179 offset:51200
	ds_read_b128 v[204:207], v179 offset:52224
	ds_read_b128 v[208:211], v179 offset:53248
	ds_read_b128 v[212:215], v179 offset:54272
	ds_read_b128 v[216:219], v179 offset:55296
	ds_read_b128 v[220:223], v179 offset:56320
	global_load_lds_dwordx4 v[224:225], off
	s_add_i32 m0, s10, 0x2000
	s_add_u32 s10, s58, 0x40080
	v_lshl_add_u64 v[224:225], v[226:227], 0, s[28:29]
	s_addc_u32 s11, s59, 0
	s_add_i32 s58, s72, s6
	global_load_lds_dwordx4 v[224:225], off
	v_lshl_add_u64 v[224:225], s[10:11], 0, v[0:1]
	s_mov_b32 m0, s58
	s_nop 0
	global_load_lds_dwordx4 v[224:225], off
	v_lshl_add_u64 v[224:225], s[10:11], 0, v[146:147]
	s_add_i32 m0, s58, 0x2000
	s_nop 0
	global_load_lds_dwordx4 v[224:225], off
	v_lshl_add_u64 v[224:225], v[238:239], 0, s[28:29]
	s_mov_b32 m0, s63
	s_nop 0
	global_load_lds_dwordx4 v[224:225], off
	v_lshl_add_u64 v[224:225], v[240:241], 0, s[28:29]
	s_mov_b32 m0, s64
	s_nop 0
	global_load_lds_dwordx4 v[224:225], off
	s_waitcnt vmcnt(8)
	s_waitcnt lgkmcnt(0)
	s_setprio 1
	s_barrier
	v_mfma_f32_16x16x32_bf16 v[62:65], v[130:133], v[192:195], v[62:65]
	v_mfma_f32_16x16x32_bf16 v[62:65], v[134:137], v[196:199], v[62:65]
	v_mfma_f32_16x16x32_bf16 v[58:61], v[138:141], v[192:195], v[58:61]
	v_mfma_f32_16x16x32_bf16 v[58:61], v[142:145], v[196:199], v[58:61]
	v_mfma_f32_16x16x32_bf16 v[42:45], v[138:141], v[200:203], v[42:45]
	v_mfma_f32_16x16x32_bf16 v[42:45], v[142:145], v[204:207], v[42:45]
	v_mfma_f32_16x16x32_bf16 v[46:49], v[130:133], v[200:203], v[46:49]
	v_mfma_f32_16x16x32_bf16 v[46:49], v[134:137], v[204:207], v[46:49]
	v_mfma_f32_16x16x32_bf16 v[30:33], v[130:133], v[208:211], v[30:33]
	v_mfma_f32_16x16x32_bf16 v[30:33], v[134:137], v[212:215], v[30:33]
	v_mfma_f32_16x16x32_bf16 v[26:29], v[138:141], v[208:211], v[26:29]
	v_mfma_f32_16x16x32_bf16 v[26:29], v[142:145], v[212:215], v[26:29]
	v_mfma_f32_16x16x32_bf16 v[10:13], v[138:141], v[216:219], v[10:13]
	v_mfma_f32_16x16x32_bf16 v[10:13], v[142:145], v[220:223], v[10:13]
	v_mfma_f32_16x16x32_bf16 v[14:17], v[130:133], v[216:219], v[14:17]
	v_mfma_f32_16x16x32_bf16 v[14:17], v[134:137], v[220:223], v[14:17]
	v_mfma_f32_16x16x32_bf16 v[54:57], v[158:161], v[192:195], v[54:57]
	v_mfma_f32_16x16x32_bf16 v[54:57], v[180:183], v[196:199], v[54:57]
	v_mfma_f32_16x16x32_bf16 v[50:53], v[184:187], v[192:195], v[50:53]
	v_mfma_f32_16x16x32_bf16 v[50:53], v[188:191], v[196:199], v[50:53]
	v_mfma_f32_16x16x32_bf16 v[34:37], v[184:187], v[200:203], v[34:37]
	v_mfma_f32_16x16x32_bf16 v[34:37], v[188:191], v[204:207], v[34:37]
	v_mfma_f32_16x16x32_bf16 v[38:41], v[158:161], v[200:203], v[38:41]
	v_mfma_f32_16x16x32_bf16 v[38:41], v[180:183], v[204:207], v[38:41]
	v_mfma_f32_16x16x32_bf16 v[22:25], v[158:161], v[208:211], v[22:25]
	v_mfma_f32_16x16x32_bf16 v[22:25], v[180:183], v[212:215], v[22:25]
	v_mfma_f32_16x16x32_bf16 v[18:21], v[184:187], v[208:211], v[18:21]
	v_mfma_f32_16x16x32_bf16 v[18:21], v[188:191], v[212:215], v[18:21]
	v_mfma_f32_16x16x32_bf16 v[2:5], v[184:187], v[216:219], v[2:5]
	v_mfma_f32_16x16x32_bf16 v[2:5], v[188:191], v[220:223], v[2:5]
	v_mfma_f32_16x16x32_bf16 v[6:9], v[158:161], v[216:219], v[6:9]
	v_mfma_f32_16x16x32_bf16 v[6:9], v[180:183], v[220:223], v[6:9]
	s_barrier
	s_setprio 0
	s_add_i32 s68, s68, 2
	s_add_u32 s66, s66, 0x100
	s_addc_u32 s67, s67, 0
	s_add_u32 s50, s50, 0x100
	s_addc_u32 s51, s51, 0
	s_cmp_gt_u32 s68, 13

; #define PG8_STAGE(bufoff, gbase, voff) do { _Pragma("unroll") for (int _i = 0; _i < 2; ++_i) \
;         __builtin_amdgcn_global_load_lds((const unsigned*)((const char*)(gbase) + (voff)[_i]), (PG8_LAS unsigned*)(lds + (bufoff) + ldsw + _i * 8192), 16, 0, 0); } while (0)
; #define PG8_LDA(dst, b, h) do { _Pragma("unroll") for (int m = 0; m < 4; ++m) _Pragma("unroll") for (int k = 0; k < 2; ++k) dst[m][k] = *(const PG8_LAS bf16x8*)(lds + PG8_SA(b, h) + aoff + m * 2048 + k * 1024); } while (0)
; #define PG8_LDB(dst, b, h) do { _Pragma("unroll") for (int n = 0; n < 2; ++n) _Pragma("unroll") for (int k = 0; k < 2; ++k) dst[n][k] = *(const PG8_LAS bf16x8*)(lds + PG8_SB(b, h) + boff + n * 2048 + k * 1024); } while (0)
; #define PG8_MMA(ai, bj, At, Bt) do { __builtin_amdgcn_s_setprio(1); _Pragma("unroll") for (int m = 0; m < 4; ++m) _Pragma("unroll") for (int n = 0; n < 2; ++n) _Pragma("unroll") for (int k = 0; k < 2; ++k) \
;         acc[ai][bj][m][n] = __builtin_amdgcn_mfma_f32_16x16x32_bf16(Bt[n][k], At[m][k], acc[ai][bj][m][n], 0, 0, 0); __builtin_amdgcn_s_setprio(0); } while (0)
; #define PG8_WAIT_V(n) asm volatile("s_waitcnt vmcnt(" #n ")" ::: "memory")
; #define PG8_WAIT_L(n) asm volatile("s_waitcnt lgkmcnt(" #n ")" ::: "memory")
; #define PG8_BAR __builtin_amdgcn_s_barrier()
; #define PG8_SCHED __builtin_amdgcn_sched_barrier(0)
; template <class Epi, class Sched, bool ALIGN_EPI = false, bool SP2 = false>
; __device__ __forceinline__ void gemm_phase(PG8_LAS unsigned char* lds, const Gemm g, const Sched& S, const Epi& E) {
;     ...
;         for (int t = 0; t < nt; t += 2) {
;             const bool last = (t == nt - 2);
;             const char* a1 = cA + (size_t)(t + 1) * kstep;
;             const char* a2 = last ? nA : cA + (size_t)(t + 2) * kstep; const char* b2 = last ? nB : cB + (size_t)(t + 2) * kstep;
;             const char* a3 = a2 + kstep; const char* b3 = b2 + kstep;
;             if (last && has_next) S.a_ready(nxt);
;             if constexpr (SP2) {
;             PG8_LDB(B0, 0, 0); PG8_LDB(B1, 0, 1); PG8_SCHED; PG8_LDA(At, 0, 0); PG8_STAGE(PG8_SA(1, 1), a1 + hstep, voffA);
;             PG8_WAIT_V(8); PG8_WAIT_L(0); PG8_BAR; PG8_MMA(0, 0, At, B0); PG8_MMA(0, 1, At, B1); PG8_BAR; PG8_SCHED;
;             PG8_LDA(At, 0, 1); PG8_STAGE(PG8_SB(0, 0), b2, voffB); PG8_STAGE(PG8_SB(0, 1), b2 + hstep, voffB); PG8_STAGE(PG8_SA(0, 0), a2, voffA);
.LBB0_1207:
	s_add_u32 s35, s44, 0x100
	s_addc_u32 s72, s45, 0
	s_mov_b32 s73, -2
	s_add_u32 s42, s24, 0x100
	s_addc_u32 s43, s25, 0
	s_add_i32 s10, 16, 0x10000
	s_cmp_eq_u32 s73, 40
	s_cselect_b32 s69, s23, s43
	s_cselect_b32 s68, s22, s42
	s_cselect_b32 s45, s27, s72
	s_cselect_b32 s44, s26, s35
	s_add_i32 vcc_lo, 16, 0x14000
	v_add_u32_e32 v78, s10, v197
	v_add_u32_e32 v94, vcc_lo, v197
	ds_read_b128 v[58:61], v78
	ds_read_b128 v[62:65], v78 offset:1024
	ds_read_b128 v[74:77], v78 offset:2048
	ds_read_b128 v[78:81], v78 offset:3072
	ds_read_b128 v[82:85], v94
	ds_read_b128 v[86:89], v94 offset:1024
	ds_read_b128 v[90:93], v94 offset:2048
	ds_read_b128 v[94:97], v94 offset:3072
	v_lshl_add_u64 v[194:195], s[24:25], 0, v[184:185]
	s_add_i32 m0, s95, 0xc000
	ds_read_b128 v[186:189], v199
	ds_read_b128 v[190:193], v199 offset:1024
	ds_read_b128 v[200:203], v199 offset:2048
	ds_read_b128 v[204:207], v199 offset:3072
	ds_read_b128 v[208:211], v199 offset:4096
	ds_read_b128 v[212:215], v199 offset:5120
	ds_read_b128 v[216:219], v199 offset:6144
	ds_read_b128 v[220:223], v199 offset:7168
	global_load_lds_dwordx4 v[194:195], off
	v_lshl_add_u64 v[194:195], s[24:25], 0, v[182:183]
	s_add_i32 m0, s95, 0xe000
	s_nop 0
	global_load_lds_dwordx4 v[194:195], off
	s_waitcnt vmcnt(8)
	s_waitcnt lgkmcnt(0)
	s_setprio 1
	s_barrier
	v_mfma_f32_16x16x32_bf16 v[158:161], v[58:61], v[186:189], 0
	v_mfma_f32_16x16x32_bf16 v[158:161], v[62:65], v[190:193], v[158:161]
	v_mfma_f32_16x16x32_bf16 v[154:157], v[74:77], v[186:189], 0
	v_mfma_f32_16x16x32_bf16 v[154:157], v[78:81], v[190:193], v[154:157]
	v_mfma_f32_16x16x32_bf16 v[138:141], v[74:77], v[200:203], 0
	v_mfma_f32_16x16x32_bf16 v[138:141], v[78:81], v[204:207], v[138:141]
	v_mfma_f32_16x16x32_bf16 v[142:145], v[58:61], v[200:203], 0
	v_mfma_f32_16x16x32_bf16 v[142:145], v[62:65], v[204:207], v[142:145]
	v_mfma_f32_16x16x32_bf16 v[126:129], v[58:61], v[208:211], 0
	v_mfma_f32_16x16x32_bf16 v[126:129], v[62:65], v[212:215], v[126:129]
	v_mfma_f32_16x16x32_bf16 v[122:125], v[74:77], v[208:211], 0
	v_mfma_f32_16x16x32_bf16 v[122:125], v[78:81], v[212:215], v[122:125]
	v_mfma_f32_16x16x32_bf16 v[106:109], v[74:77], v[216:219], 0
	v_mfma_f32_16x16x32_bf16 v[106:109], v[78:81], v[220:223], v[106:109]
	v_mfma_f32_16x16x32_bf16 v[110:113], v[58:61], v[216:219], 0
	v_mfma_f32_16x16x32_bf16 v[110:113], v[62:65], v[220:223], v[110:113]
	v_mfma_f32_16x16x32_bf16 v[150:153], v[82:85], v[186:189], 0
	v_mfma_f32_16x16x32_bf16 v[150:153], v[86:89], v[190:193], v[150:153]
	v_mfma_f32_16x16x32_bf16 v[146:149], v[90:93], v[186:189], 0
	v_mfma_f32_16x16x32_bf16 v[146:149], v[94:97], v[190:193], v[146:149]
	v_mfma_f32_16x16x32_bf16 v[130:133], v[90:93], v[200:203], 0
	v_mfma_f32_16x16x32_bf16 v[130:133], v[94:97], v[204:207], v[130:133]
	v_mfma_f32_16x16x32_bf16 v[134:137], v[82:85], v[200:203], 0
	v_mfma_f32_16x16x32_bf16 v[134:137], v[86:89], v[204:207], v[134:137]
	v_mfma_f32_16x16x32_bf16 v[118:121], v[82:85], v[208:211], 0
	v_mfma_f32_16x16x32_bf16 v[118:121], v[86:89], v[212:215], v[118:121]
	v_mfma_f32_16x16x32_bf16 v[114:117], v[90:93], v[208:211], 0
	v_mfma_f32_16x16x32_bf16 v[114:117], v[94:97], v[212:215], v[114:117]
	v_mfma_f32_16x16x32_bf16 v[98:101], v[90:93], v[216:219], 0
	v_mfma_f32_16x16x32_bf16 v[98:101], v[94:97], v[220:223], v[98:101]
	v_mfma_f32_16x16x32_bf16 v[102:105], v[82:85], v[216:219], 0
	v_mfma_f32_16x16x32_bf16 v[102:105], v[86:89], v[220:223], v[102:105]
	s_barrier
	s_setprio 0
	s_add_i32 s10, s10, s94
	v_lshl_add_u64 v[194:195], s[44:45], 0, v[0:1]
	s_mov_b32 m0, s10
	ds_read_b128 v[186:189], v199 offset:16384
	ds_read_b128 v[190:193], v199 offset:17408
	ds_read_b128 v[200:203], v199 offset:18432
	ds_read_b128 v[204:207], v199 offset:19456
	ds_read_b128 v[208:211], v199 offset:20480
	ds_read_b128 v[212:215], v199 offset:21504
	ds_read_b128 v[216:219], v199 offset:22528
	ds_read_b128 v[220:223], v199 offset:23552
	global_load_lds_dwordx4 v[194:195], off
	s_add_i32 m0, s10, 0x2000
	s_add_u32 s10, s44, 0xb0000
	v_lshl_add_u64 v[224:225], s[44:45], 0, v[180:181]
	s_addc_u32 s11, s45, 0
	s_add_i32 s24, vcc_lo, s94
	global_load_lds_dwordx4 v[224:225], off
	v_lshl_add_u64 v[226:227], s[10:11], 0, v[0:1]
	s_mov_b32 m0, s24
	v_lshl_add_u64 v[238:239], s[68:69], 0, v[178:179]
	global_load_lds_dwordx4 v[226:227], off
	v_lshl_add_u64 v[226:227], s[10:11], 0, v[180:181]
	s_add_i32 m0, s24, 0x2000
	s_nop 0
	global_load_lds_dwordx4 v[226:227], off
	v_lshl_add_u64 v[226:227], s[68:69], 0, v[176:177]
	s_mov_b32 m0, s95
	s_nop 0
	global_load_lds_dwordx4 v[226:227], off
	s_mov_b32 m0, s2
	s_nop 0
	global_load_lds_dwordx4 v[238:239], off
	s_waitcnt vmcnt(8)
	s_waitcnt lgkmcnt(0)
	s_setprio 1
	s_barrier
; #define PG8_STAGE(bufoff, gbase, voff) do { _Pragma("unroll") for (int _i = 0; _i < 2; ++_i) \
;         __builtin_amdgcn_global_load_lds((const unsigned*)((const char*)(gbase) + (voff)[_i]), (PG8_LAS unsigned*)(lds + (bufoff) + ldsw + _i * 8192), 16, 0, 0); } while (0)
; #define PG8_LDA(dst, b, h) do { _Pragma("unroll") for (int m = 0; m < 4; ++m) _Pragma("unroll") for (int k = 0; k < 2; ++k) dst[m][k] = *(const PG8_LAS bf16x8*)(lds + PG8_SA(b, h) + aoff + m * 2048 + k * 1024); } while (0)
; #define PG8_LDB(dst, b, h) do { _Pragma("unroll") for (int n = 0; n < 2; ++n) _Pragma("unroll") for (int k = 0; k < 2; ++k) dst[n][k] = *(const PG8_LAS bf16x8*)(lds + PG8_SB(b, h) + boff + n * 2048 + k * 1024); } while (0)
; #define PG8_MMA(ai, bj, At, Bt) do { __builtin_amdgcn_s_setprio(1); _Pragma("unroll") for (int m = 0; m < 4; ++m) _Pragma("unroll") for (int n = 0; n < 2; ++n) _Pragma("unroll") for (int k = 0; k < 2; ++k) \
;         acc[ai][bj][m][n] = __builtin_amdgcn_mfma_f32_16x16x32_bf16(Bt[n][k], At[m][k], acc[ai][bj][m][n], 0, 0, 0); __builtin_amdgcn_s_setprio(0); } while (0)
; #define PG8_WAIT_V(n) asm volatile("s_waitcnt vmcnt(" #n ")" ::: "memory")
; #define PG8_WAIT_L(n) asm volatile("s_waitcnt lgkmcnt(" #n ")" ::: "memory")
; #define PG8_BAR __builtin_amdgcn_s_barrier()
; #define PG8_SCHED __builtin_amdgcn_sched_barrier(0)
; template <class Epi, class Sched, bool ALIGN_EPI = false, bool SP2 = false>
; __device__ __forceinline__ void gemm_phase(PG8_LAS unsigned char* lds, const Gemm g, const Sched& S, const Epi& E) {
;     ...
;             PG8_WAIT_V(8); PG8_WAIT_L(0); PG8_BAR; PG8_MMA(1, 0, At, B0); PG8_MMA(1, 1, At, B1); PG8_BAR; PG8_SCHED;
;             PG8_LDB(B0, 1, 0); PG8_LDB(B1, 1, 1); PG8_SCHED; PG8_LDA(At, 1, 0); PG8_STAGE(PG8_SA(0, 1), a2 + hstep, voffA);
;             PG8_WAIT_V(8); PG8_WAIT_L(0); PG8_BAR; PG8_MMA(0, 0, At, B0); PG8_MMA(0, 1, At, B1); PG8_BAR; PG8_SCHED;
	v_mfma_f32_16x16x32_bf16 v[70:73], v[58:61], v[186:189], 0
	v_mfma_f32_16x16x32_bf16 v[70:73], v[62:65], v[190:193], v[70:73]
	v_mfma_f32_16x16x32_bf16 v[66:69], v[74:77], v[186:189], 0
	v_mfma_f32_16x16x32_bf16 v[66:69], v[78:81], v[190:193], v[66:69]
	v_mfma_f32_16x16x32_bf16 v[42:45], v[74:77], v[200:203], 0
	v_mfma_f32_16x16x32_bf16 v[42:45], v[78:81], v[204:207], v[42:45]
	v_mfma_f32_16x16x32_bf16 v[46:49], v[58:61], v[200:203], 0
	v_mfma_f32_16x16x32_bf16 v[46:49], v[62:65], v[204:207], v[46:49]
	v_mfma_f32_16x16x32_bf16 v[30:33], v[58:61], v[208:211], 0
	v_mfma_f32_16x16x32_bf16 v[30:33], v[62:65], v[212:215], v[30:33]
	v_mfma_f32_16x16x32_bf16 v[26:29], v[74:77], v[208:211], 0
	v_mfma_f32_16x16x32_bf16 v[26:29], v[78:81], v[212:215], v[26:29]
	v_mfma_f32_16x16x32_bf16 v[10:13], v[74:77], v[216:219], 0
	v_mfma_f32_16x16x32_bf16 v[10:13], v[78:81], v[220:223], v[10:13]
	v_mfma_f32_16x16x32_bf16 v[14:17], v[58:61], v[216:219], 0
	v_mfma_f32_16x16x32_bf16 v[14:17], v[62:65], v[220:223], v[14:17]
	v_mfma_f32_16x16x32_bf16 v[54:57], v[82:85], v[186:189], 0
	v_mfma_f32_16x16x32_bf16 v[54:57], v[86:89], v[190:193], v[54:57]
	v_mfma_f32_16x16x32_bf16 v[50:53], v[90:93], v[186:189], 0
	v_mfma_f32_16x16x32_bf16 v[50:53], v[94:97], v[190:193], v[50:53]
	v_mfma_f32_16x16x32_bf16 v[34:37], v[90:93], v[200:203], 0
	v_mfma_f32_16x16x32_bf16 v[34:37], v[94:97], v[204:207], v[34:37]
	v_mfma_f32_16x16x32_bf16 v[38:41], v[82:85], v[200:203], 0
	v_mfma_f32_16x16x32_bf16 v[38:41], v[86:89], v[204:207], v[38:41]
	v_mfma_f32_16x16x32_bf16 v[22:25], v[82:85], v[208:211], 0
	v_mfma_f32_16x16x32_bf16 v[22:25], v[86:89], v[212:215], v[22:25]
	v_mfma_f32_16x16x32_bf16 v[18:21], v[90:93], v[208:211], 0
	v_mfma_f32_16x16x32_bf16 v[18:21], v[94:97], v[212:215], v[18:21]
	v_mfma_f32_16x16x32_bf16 v[2:5], v[90:93], v[216:219], 0
	v_mfma_f32_16x16x32_bf16 v[2:5], v[94:97], v[220:223], v[2:5]
	v_mfma_f32_16x16x32_bf16 v[6:9], v[82:85], v[216:219], 0
	v_mfma_f32_16x16x32_bf16 v[6:9], v[86:89], v[220:223], v[6:9]
	s_barrier
	s_setprio 0
	s_add_i32 s24, 16, 0x18000
	s_add_i32 s25, 16, 0x1c000
	v_add_u32_e32 v78, s24, v197
	v_add_u32_e32 v94, s25, v197
	ds_read_b128 v[58:61], v78
	ds_read_b128 v[62:65], v78 offset:1024
	ds_read_b128 v[74:77], v78 offset:2048
	ds_read_b128 v[78:81], v78 offset:3072
	ds_read_b128 v[82:85], v94
	ds_read_b128 v[86:89], v94 offset:1024
	ds_read_b128 v[90:93], v94 offset:2048
	ds_read_b128 v[94:97], v94 offset:3072
	s_add_u32 s10, s68, 0xb0000
	s_addc_u32 s11, s69, 0
	s_mov_b32 m0, s3
	v_lshl_add_u64 v[240:241], s[10:11], 0, v[176:177]
	ds_read_b128 v[186:189], v199 offset:32768
	ds_read_b128 v[190:193], v199 offset:33792
	ds_read_b128 v[200:203], v199 offset:34816
	ds_read_b128 v[204:207], v199 offset:35840
	ds_read_b128 v[208:211], v199 offset:36864
	ds_read_b128 v[212:215], v199 offset:37888
	ds_read_b128 v[216:219], v199 offset:38912
	ds_read_b128 v[220:223], v199 offset:39936
	global_load_lds_dwordx4 v[240:241], off
	v_lshl_add_u64 v[240:241], s[10:11], 0, v[178:179]
	s_mov_b32 m0, s96
	s_nop 0
	global_load_lds_dwordx4 v[240:241], off
	s_waitcnt vmcnt(8)
	s_waitcnt lgkmcnt(0)
	s_setprio 1
	s_barrier
	v_mfma_f32_16x16x32_bf16 v[158:161], v[58:61], v[186:189], v[158:161]
	v_mfma_f32_16x16x32_bf16 v[158:161], v[62:65], v[190:193], v[158:161]
	v_mfma_f32_16x16x32_bf16 v[154:157], v[74:77], v[186:189], v[154:157]
	v_mfma_f32_16x16x32_bf16 v[154:157], v[78:81], v[190:193], v[154:157]
	v_mfma_f32_16x16x32_bf16 v[138:141], v[74:77], v[200:203], v[138:141]
	v_mfma_f32_16x16x32_bf16 v[138:141], v[78:81], v[204:207], v[138:141]
	v_mfma_f32_16x16x32_bf16 v[142:145], v[58:61], v[200:203], v[142:145]
	v_mfma_f32_16x16x32_bf16 v[142:145], v[62:65], v[204:207], v[142:145]
	v_mfma_f32_16x16x32_bf16 v[126:129], v[58:61], v[208:211], v[126:129]
	v_mfma_f32_16x16x32_bf16 v[126:129], v[62:65], v[212:215], v[126:129]
	v_mfma_f32_16x16x32_bf16 v[122:125], v[74:77], v[208:211], v[122:125]
	v_mfma_f32_16x16x32_bf16 v[122:125], v[78:81], v[212:215], v[122:125]
	v_mfma_f32_16x16x32_bf16 v[106:109], v[74:77], v[216:219], v[106:109]
	v_mfma_f32_16x16x32_bf16 v[106:109], v[78:81], v[220:223], v[106:109]
	v_mfma_f32_16x16x32_bf16 v[110:113], v[58:61], v[216:219], v[110:113]
	v_mfma_f32_16x16x32_bf16 v[110:113], v[62:65], v[220:223], v[110:113]
	v_mfma_f32_16x16x32_bf16 v[150:153], v[82:85], v[186:189], v[150:153]
	v_mfma_f32_16x16x32_bf16 v[150:153], v[86:89], v[190:193], v[150:153]
	v_mfma_f32_16x16x32_bf16 v[146:149], v[90:93], v[186:189], v[146:149]
	v_mfma_f32_16x16x32_bf16 v[146:149], v[94:97], v[190:193], v[146:149]
	v_mfma_f32_16x16x32_bf16 v[130:133], v[90:93], v[200:203], v[130:133]
	v_mfma_f32_16x16x32_bf16 v[130:133], v[94:97], v[204:207], v[130:133]
	v_mfma_f32_16x16x32_bf16 v[134:137], v[82:85], v[200:203], v[134:137]
	v_mfma_f32_16x16x32_bf16 v[134:137], v[86:89], v[204:207], v[134:137]
	v_mfma_f32_16x16x32_bf16 v[118:121], v[82:85], v[208:211], v[118:121]
	v_mfma_f32_16x16x32_bf16 v[118:121], v[86:89], v[212:215], v[118:121]
	v_mfma_f32_16x16x32_bf16 v[114:117], v[90:93], v[208:211], v[114:117]
	v_mfma_f32_16x16x32_bf16 v[114:117], v[94:97], v[212:215], v[114:117]
	v_mfma_f32_16x16x32_bf16 v[98:101], v[90:93], v[216:219], v[98:101]
	v_mfma_f32_16x16x32_bf16 v[98:101], v[94:97], v[220:223], v[98:101]
	v_mfma_f32_16x16x32_bf16 v[102:105], v[82:85], v[216:219], v[102:105]
	v_mfma_f32_16x16x32_bf16 v[102:105], v[86:89], v[220:223], v[102:105]
	s_barrier
; #define PG8_STAGE(bufoff, gbase, voff) do { _Pragma("unroll") for (int _i = 0; _i < 2; ++_i) \
;         __builtin_amdgcn_global_load_lds((const unsigned*)((const char*)(gbase) + (voff)[_i]), (PG8_LAS unsigned*)(lds + (bufoff) + ldsw + _i * 8192), 16, 0, 0); } while (0)
; #define PG8_LDA(dst, b, h) do { _Pragma("unroll") for (int m = 0; m < 4; ++m) _Pragma("unroll") for (int k = 0; k < 2; ++k) dst[m][k] = *(const PG8_LAS bf16x8*)(lds + PG8_SA(b, h) + aoff + m * 2048 + k * 1024); } while (0)
; #define PG8_MMA(ai, bj, At, Bt) do { __builtin_amdgcn_s_setprio(1); _Pragma("unroll") for (int m = 0; m < 4; ++m) _Pragma("unroll") for (int n = 0; n < 2; ++n) _Pragma("unroll") for (int k = 0; k < 2; ++k) \
;         acc[ai][bj][m][n] = __builtin_amdgcn_mfma_f32_16x16x32_bf16(Bt[n][k], At[m][k], acc[ai][bj][m][n], 0, 0, 0); __builtin_amdgcn_s_setprio(0); } while (0)
; #define PG8_WAIT_V(n) asm volatile("s_waitcnt vmcnt(" #n ")" ::: "memory")
; #define PG8_WAIT_L(n) asm volatile("s_waitcnt lgkmcnt(" #n ")" ::: "memory")
; #define PG8_BAR __builtin_amdgcn_s_barrier()
; #define PG8_SCHED __builtin_amdgcn_sched_barrier(0)
; template <class Epi, class Sched, bool ALIGN_EPI = false, bool SP2 = false>
; __device__ __forceinline__ void gemm_phase(PG8_LAS unsigned char* lds, const Gemm g, const Sched& S, const Epi& E) {
;     ...
;         for (int t = 0; t < nt; t += 2) {
;             const bool last = (t == nt - 2);
;             const char* a1 = cA + (size_t)(t + 1) * kstep;
;             const char* a2 = last ? nA : cA + (size_t)(t + 2) * kstep; const char* b2 = last ? nB : cB + (size_t)(t + 2) * kstep;
;             const char* a3 = a2 + kstep; const char* b3 = b2 + kstep;
;     ...
;             PG8_LDA(At, 1, 1); PG8_STAGE(PG8_SB(1, 0), b3, voffB); PG8_STAGE(PG8_SB(1, 1), b3 + hstep, voffB); PG8_STAGE(PG8_SA(1, 0), a3, voffA);
;             PG8_WAIT_V(8); PG8_WAIT_L(0); PG8_BAR; PG8_MMA(1, 0, At, B0); PG8_MMA(1, 1, At, B1); PG8_BAR; PG8_SCHED;
	s_setprio 0
	s_add_i32 s10, s24, s94
	v_lshl_add_u64 v[194:195], v[194:195], 0, s[28:29]
	s_mov_b32 m0, s10
	ds_read_b128 v[186:189], v199 offset:49152
	ds_read_b128 v[190:193], v199 offset:50176
	ds_read_b128 v[200:203], v199 offset:51200
	ds_read_b128 v[204:207], v199 offset:52224
	ds_read_b128 v[208:211], v199 offset:53248
	ds_read_b128 v[212:215], v199 offset:54272
	ds_read_b128 v[216:219], v199 offset:55296
	ds_read_b128 v[220:223], v199 offset:56320
	global_load_lds_dwordx4 v[194:195], off
	s_add_i32 m0, s10, 0x2000
	s_add_u32 s10, s44, 0xb0080
	v_lshl_add_u64 v[194:195], v[224:225], 0, s[28:29]
	s_addc_u32 s11, s45, 0
	s_add_i32 s24, s25, s94
	global_load_lds_dwordx4 v[194:195], off
	v_lshl_add_u64 v[194:195], s[10:11], 0, v[0:1]
	s_mov_b32 m0, s24
	s_nop 0
	global_load_lds_dwordx4 v[194:195], off
	v_lshl_add_u64 v[194:195], s[10:11], 0, v[180:181]
	s_add_i32 m0, s24, 0x2000
	s_nop 0
	global_load_lds_dwordx4 v[194:195], off
	v_lshl_add_u64 v[194:195], v[226:227], 0, s[28:29]
	s_mov_b32 m0, s57
	s_nop 0
	global_load_lds_dwordx4 v[194:195], off
	v_lshl_add_u64 v[194:195], v[238:239], 0, s[28:29]
	s_mov_b32 m0, s78
	s_nop 0
	global_load_lds_dwordx4 v[194:195], off
	s_waitcnt vmcnt(8)
	s_waitcnt lgkmcnt(0)
	s_setprio 1
	s_barrier
	v_mfma_f32_16x16x32_bf16 v[70:73], v[58:61], v[186:189], v[70:73]
	v_mfma_f32_16x16x32_bf16 v[70:73], v[62:65], v[190:193], v[70:73]
	v_mfma_f32_16x16x32_bf16 v[66:69], v[74:77], v[186:189], v[66:69]
	v_mfma_f32_16x16x32_bf16 v[66:69], v[78:81], v[190:193], v[66:69]
	v_mfma_f32_16x16x32_bf16 v[42:45], v[74:77], v[200:203], v[42:45]
	v_mfma_f32_16x16x32_bf16 v[42:45], v[78:81], v[204:207], v[42:45]
	v_mfma_f32_16x16x32_bf16 v[46:49], v[58:61], v[200:203], v[46:49]
	v_mfma_f32_16x16x32_bf16 v[46:49], v[62:65], v[204:207], v[46:49]
	v_mfma_f32_16x16x32_bf16 v[30:33], v[58:61], v[208:211], v[30:33]
	v_mfma_f32_16x16x32_bf16 v[30:33], v[62:65], v[212:215], v[30:33]
	v_mfma_f32_16x16x32_bf16 v[26:29], v[74:77], v[208:211], v[26:29]
	v_mfma_f32_16x16x32_bf16 v[26:29], v[78:81], v[212:215], v[26:29]
	v_mfma_f32_16x16x32_bf16 v[10:13], v[74:77], v[216:219], v[10:13]
	v_mfma_f32_16x16x32_bf16 v[10:13], v[78:81], v[220:223], v[10:13]
	v_mfma_f32_16x16x32_bf16 v[14:17], v[58:61], v[216:219], v[14:17]
	v_mfma_f32_16x16x32_bf16 v[14:17], v[62:65], v[220:223], v[14:17]
	v_mfma_f32_16x16x32_bf16 v[54:57], v[82:85], v[186:189], v[54:57]
	v_mfma_f32_16x16x32_bf16 v[54:57], v[86:89], v[190:193], v[54:57]
	v_mfma_f32_16x16x32_bf16 v[50:53], v[90:93], v[186:189], v[50:53]
	v_mfma_f32_16x16x32_bf16 v[50:53], v[94:97], v[190:193], v[50:53]
	v_mfma_f32_16x16x32_bf16 v[34:37], v[90:93], v[200:203], v[34:37]
	v_mfma_f32_16x16x32_bf16 v[34:37], v[94:97], v[204:207], v[34:37]
	v_mfma_f32_16x16x32_bf16 v[38:41], v[82:85], v[200:203], v[38:41]
	v_mfma_f32_16x16x32_bf16 v[38:41], v[86:89], v[204:207], v[38:41]
	v_mfma_f32_16x16x32_bf16 v[22:25], v[82:85], v[208:211], v[22:25]
	v_mfma_f32_16x16x32_bf16 v[22:25], v[86:89], v[212:215], v[22:25]
	v_mfma_f32_16x16x32_bf16 v[18:21], v[90:93], v[208:211], v[18:21]
	v_mfma_f32_16x16x32_bf16 v[18:21], v[94:97], v[212:215], v[18:21]
	v_mfma_f32_16x16x32_bf16 v[2:5], v[90:93], v[216:219], v[2:5]
	v_mfma_f32_16x16x32_bf16 v[2:5], v[94:97], v[220:223], v[2:5]
	v_mfma_f32_16x16x32_bf16 v[6:9], v[82:85], v[216:219], v[6:9]
	v_mfma_f32_16x16x32_bf16 v[6:9], v[86:89], v[220:223], v[6:9]
	s_barrier
	s_setprio 0
	s_add_i32 s73, s73, 2
	s_add_u32 s35, s35, 0x100
	s_addc_u32 s72, s72, 0
	s_cmp_gt_u32 s73, 41
	s_mov_b64 s[24:25], s[42:43]

; #define PG8_STAGE(bufoff, gbase, voff) do { _Pragma("unroll") for (int _i = 0; _i < 2; ++_i) \
;         __builtin_amdgcn_global_load_lds((const unsigned*)((const char*)(gbase) + (voff)[_i]), (PG8_LAS unsigned*)(lds + (bufoff) + ldsw + _i * 8192), 16, 0, 0); } while (0)
; #define PG8_LDA(dst, b, h) do { _Pragma("unroll") for (int m = 0; m < 4; ++m) _Pragma("unroll") for (int k = 0; k < 2; ++k) dst[m][k] = *(const PG8_LAS bf16x8*)(lds + PG8_SA(b, h) + aoff + m * 2048 + k * 1024); } while (0)
; #define PG8_LDB(dst, b, h) do { _Pragma("unroll") for (int n = 0; n < 2; ++n) _Pragma("unroll") for (int k = 0; k < 2; ++k) dst[n][k] = *(const PG8_LAS bf16x8*)(lds + PG8_SB(b, h) + boff + n * 2048 + k * 1024); } while (0)
; #define PG8_MMA(ai, bj, At, Bt) do { __builtin_amdgcn_s_setprio(1); _Pragma("unroll") for (int m = 0; m < 4; ++m) _Pragma("unroll") for (int n = 0; n < 2; ++n) _Pragma("unroll") for (int k = 0; k < 2; ++k) \
;         acc[ai][bj][m][n] = __builtin_amdgcn_mfma_f32_16x16x32_bf16(Bt[n][k], At[m][k], acc[ai][bj][m][n], 0, 0, 0); __builtin_amdgcn_s_setprio(0); } while (0)
; #define PG8_BAR __builtin_amdgcn_s_barrier()
; template <class Epi, class Sched, bool ALIGN_EPI = false, bool SP2 = false>
; __device__ __forceinline__ void gemm_phase(PG8_LAS unsigned char* lds, const Gemm g, const Sched& S, const Epi& E) {
;     ...
;         const bool has_next = S.next(ui + 1, nxt);
;         const char* nA = has_next ? (const char*)g.A + (size_t)nxt.pm * tstep : cA; const char* nB = has_next ? (const char*)g.Bt + (size_t)nxt.pn * tstep : cB;
;         for (int t = 0; t < nt; t += 2) {
;             const bool last = (t == nt - 2);
;             const char* a1 = cA + (size_t)(t + 1) * kstep;
;             const char* a2 = last ? nA : cA + (size_t)(t + 2) * kstep; const char* b2 = last ? nB : cB + (size_t)(t + 2) * kstep;
;             const char* a3 = a2 + kstep; const char* b3 = b2 + kstep;
;             if (last && has_next) S.a_ready(nxt);
;             if constexpr (SP2) {
;             PG8_LDB(B0, 0, 0); PG8_LDB(B1, 0, 1); PG8_SCHED; PG8_LDA(At, 0, 0); PG8_STAGE(PG8_SA(1, 1), a1 + hstep, voffA);
;             PG8_WAIT_V(8); PG8_WAIT_L(0); PG8_BAR; PG8_MMA(0, 0, At, B0); PG8_MMA(0, 1, At, B1); PG8_BAR; PG8_SCHED;
;             PG8_LDA(At, 0, 1); PG8_STAGE(PG8_SB(0, 0), b2, voffB); PG8_STAGE(PG8_SB(0, 1), b2 + hstep, voffB); PG8_STAGE(PG8_SA(0, 0), a2, voffA);
.LBB0_1274:
	s_and_b64 s[98:99], s[38:39], exec
	s_cselect_b32 s71, s42, s58
	s_cselect_b32 s72, s26, s57
	s_ashr_i32 s43, s42, 31
	s_lshl_b64 s[10:11], s[42:43], 19
	s_add_u32 s44, s60, s10
	s_addc_u32 s45, s61, s11
	s_and_b64 s[10:11], s[38:39], exec
	s_cselect_b32 s34, s45, s49
	s_cselect_b32 s35, s44, s48
	s_ashr_i32 s27, s26, 31
	s_lshl_b64 s[10:11], s[26:27], 19
	s_add_u32 s46, s0, s10
	s_addc_u32 s47, s2, s11
	s_and_b64 s[10:11], s[38:39], exec
	s_cselect_b32 s27, s47, s41
	s_cselect_b32 s43, s46, s40
	s_add_u32 s59, s40, 0x100
	s_addc_u32 s62, s41, 0
	s_add_u32 s40, s48, 0x40080
	s_addc_u32 s41, s49, 0
	s_mov_b32 s63, -2
	s_add_u32 s10, s40, 0xfffc0080
	s_addc_u32 s11, s41, -1
	s_add_i32 s64, 16, 0x10000
	s_cmp_eq_u32 s63, 12
	s_cselect_b32 s51, s34, s11
	s_cselect_b32 s50, s35, s10
	s_cselect_b32 s49, s27, s62
	s_cselect_b32 s48, s43, s59
	s_add_i32 s65, 16, 0x14000
	v_add_u32_e32 v142, s64, v179
	v_add_u32_e32 v176, s65, v179
	ds_read_b128 v[130:133], v142
	ds_read_b128 v[134:137], v142 offset:1024
	ds_read_b128 v[138:141], v142 offset:2048
	ds_read_b128 v[142:145], v142 offset:3072
	ds_read_b128 v[158:161], v176
	ds_read_b128 v[182:185], v176 offset:1024
	ds_read_b128 v[186:189], v176 offset:2048
	ds_read_b128 v[190:193], v176 offset:3072
	v_lshl_add_u64 v[176:177], s[40:41], 0, v[156:157]
	s_add_i32 m0, s4, 0xc000
	ds_read_b128 v[194:197], v181
	ds_read_b128 v[198:201], v181 offset:1024
	ds_read_b128 v[202:205], v181 offset:2048
	ds_read_b128 v[206:209], v181 offset:3072
	ds_read_b128 v[210:213], v181 offset:4096
	ds_read_b128 v[214:217], v181 offset:5120
	ds_read_b128 v[218:221], v181 offset:6144
	ds_read_b128 v[222:225], v181 offset:7168
	global_load_lds_dwordx4 v[176:177], off
	v_lshl_add_u64 v[176:177], s[40:41], 0, v[154:155]
	s_add_i32 m0, s4, 0xe000
	s_nop 0
	global_load_lds_dwordx4 v[176:177], off
	s_waitcnt vmcnt(8)
	s_waitcnt lgkmcnt(0)
	s_setprio 1
	s_barrier
	v_mfma_f32_16x16x32_bf16 v[126:129], v[130:133], v[194:197], 0
	v_mfma_f32_16x16x32_bf16 v[126:129], v[134:137], v[198:201], v[126:129]
	v_mfma_f32_16x16x32_bf16 v[122:125], v[138:141], v[194:197], 0
	v_mfma_f32_16x16x32_bf16 v[122:125], v[142:145], v[198:201], v[122:125]
	v_mfma_f32_16x16x32_bf16 v[106:109], v[138:141], v[202:205], 0
	v_mfma_f32_16x16x32_bf16 v[106:109], v[142:145], v[206:209], v[106:109]
	v_mfma_f32_16x16x32_bf16 v[110:113], v[130:133], v[202:205], 0
	v_mfma_f32_16x16x32_bf16 v[110:113], v[134:137], v[206:209], v[110:113]
	v_mfma_f32_16x16x32_bf16 v[94:97], v[130:133], v[210:213], 0
	v_mfma_f32_16x16x32_bf16 v[94:97], v[134:137], v[214:217], v[94:97]
	v_mfma_f32_16x16x32_bf16 v[90:93], v[138:141], v[210:213], 0
	v_mfma_f32_16x16x32_bf16 v[90:93], v[142:145], v[214:217], v[90:93]
	v_mfma_f32_16x16x32_bf16 v[74:77], v[138:141], v[218:221], 0
	v_mfma_f32_16x16x32_bf16 v[74:77], v[142:145], v[222:225], v[74:77]
	v_mfma_f32_16x16x32_bf16 v[78:81], v[130:133], v[218:221], 0
	v_mfma_f32_16x16x32_bf16 v[78:81], v[134:137], v[222:225], v[78:81]
	v_mfma_f32_16x16x32_bf16 v[118:121], v[158:161], v[194:197], 0
	v_mfma_f32_16x16x32_bf16 v[118:121], v[182:185], v[198:201], v[118:121]
	v_mfma_f32_16x16x32_bf16 v[114:117], v[186:189], v[194:197], 0
	v_mfma_f32_16x16x32_bf16 v[114:117], v[190:193], v[198:201], v[114:117]
	v_mfma_f32_16x16x32_bf16 v[98:101], v[186:189], v[202:205], 0
	v_mfma_f32_16x16x32_bf16 v[98:101], v[190:193], v[206:209], v[98:101]
	v_mfma_f32_16x16x32_bf16 v[102:105], v[158:161], v[202:205], 0
	v_mfma_f32_16x16x32_bf16 v[102:105], v[182:185], v[206:209], v[102:105]
	v_mfma_f32_16x16x32_bf16 v[86:89], v[158:161], v[210:213], 0
	v_mfma_f32_16x16x32_bf16 v[86:89], v[182:185], v[214:217], v[86:89]
	v_mfma_f32_16x16x32_bf16 v[82:85], v[186:189], v[210:213], 0
	v_mfma_f32_16x16x32_bf16 v[82:85], v[190:193], v[214:217], v[82:85]
	v_mfma_f32_16x16x32_bf16 v[66:69], v[186:189], v[218:221], 0
	v_mfma_f32_16x16x32_bf16 v[66:69], v[190:193], v[222:225], v[66:69]
	v_mfma_f32_16x16x32_bf16 v[70:73], v[158:161], v[218:221], 0
	v_mfma_f32_16x16x32_bf16 v[70:73], v[182:185], v[222:225], v[70:73]
	s_barrier
	s_setprio 0
	s_add_i32 s10, s64, s3
	v_lshl_add_u64 v[176:177], s[48:49], 0, v[0:1]
	s_mov_b32 m0, s10
	ds_read_b128 v[194:197], v181 offset:16384
	ds_read_b128 v[198:201], v181 offset:17408
	ds_read_b128 v[202:205], v181 offset:18432
	ds_read_b128 v[206:209], v181 offset:19456
	ds_read_b128 v[210:213], v181 offset:20480
	ds_read_b128 v[214:217], v181 offset:21504
	ds_read_b128 v[218:221], v181 offset:22528
	ds_read_b128 v[222:225], v181 offset:23552
	global_load_lds_dwordx4 v[176:177], off
	s_add_i32 m0, s10, 0x2000
	s_add_u32 s10, s48, 0x40000
	v_lshl_add_u64 v[226:227], s[48:49], 0, v[146:147]
	s_addc_u32 s11, s49, 0
	s_add_i32 s64, s65, s3
	global_load_lds_dwordx4 v[226:227], off
	v_lshl_add_u64 v[238:239], s[10:11], 0, v[0:1]
	s_mov_b32 m0, s64
	v_lshl_add_u64 v[240:241], s[50:51], 0, v[148:149]
	global_load_lds_dwordx4 v[238:239], off
	v_lshl_add_u64 v[238:239], s[10:11], 0, v[146:147]
	s_add_i32 m0, s64, 0x2000
	s_nop 0
	global_load_lds_dwordx4 v[238:239], off
	v_lshl_add_u64 v[238:239], s[50:51], 0, v[150:151]
	s_mov_b32 m0, s4
	s_nop 0
	global_load_lds_dwordx4 v[238:239], off
	s_mov_b32 m0, s5
	s_nop 0
	global_load_lds_dwordx4 v[240:241], off
	s_waitcnt vmcnt(8)
	s_waitcnt lgkmcnt(0)
	s_setprio 1
	s_barrier
; #define PG8_STAGE(bufoff, gbase, voff) do { _Pragma("unroll") for (int _i = 0; _i < 2; ++_i) \
;         __builtin_amdgcn_global_load_lds((const unsigned*)((const char*)(gbase) + (voff)[_i]), (PG8_LAS unsigned*)(lds + (bufoff) + ldsw + _i * 8192), 16, 0, 0); } while (0)
; #define PG8_LDA(dst, b, h) do { _Pragma("unroll") for (int m = 0; m < 4; ++m) _Pragma("unroll") for (int k = 0; k < 2; ++k) dst[m][k] = *(const PG8_LAS bf16x8*)(lds + PG8_SA(b, h) + aoff + m * 2048 + k * 1024); } while (0)
; #define PG8_LDB(dst, b, h) do { _Pragma("unroll") for (int n = 0; n < 2; ++n) _Pragma("unroll") for (int k = 0; k < 2; ++k) dst[n][k] = *(const PG8_LAS bf16x8*)(lds + PG8_SB(b, h) + boff + n * 2048 + k * 1024); } while (0)
; #define PG8_MMA(ai, bj, At, Bt) do { __builtin_amdgcn_s_setprio(1); _Pragma("unroll") for (int m = 0; m < 4; ++m) _Pragma("unroll") for (int n = 0; n < 2; ++n) _Pragma("unroll") for (int k = 0; k < 2; ++k) \
;         acc[ai][bj][m][n] = __builtin_amdgcn_mfma_f32_16x16x32_bf16(Bt[n][k], At[m][k], acc[ai][bj][m][n], 0, 0, 0); __builtin_amdgcn_s_setprio(0); } while (0)
; #define PG8_WAIT_V(n) asm volatile("s_waitcnt vmcnt(" #n ")" ::: "memory")
; #define PG8_WAIT_L(n) asm volatile("s_waitcnt lgkmcnt(" #n ")" ::: "memory")
; #define PG8_BAR __builtin_amdgcn_s_barrier()
; #define PG8_SCHED __builtin_amdgcn_sched_barrier(0)
; template <class Epi, class Sched, bool ALIGN_EPI = false, bool SP2 = false>
; __device__ __forceinline__ void gemm_phase(PG8_LAS unsigned char* lds, const Gemm g, const Sched& S, const Epi& E) {
;     ...
;             PG8_WAIT_V(8); PG8_WAIT_L(0); PG8_BAR; PG8_MMA(1, 0, At, B0); PG8_MMA(1, 1, At, B1); PG8_BAR; PG8_SCHED;
;             PG8_LDB(B0, 1, 0); PG8_LDB(B1, 1, 1); PG8_SCHED; PG8_LDA(At, 1, 0); PG8_STAGE(PG8_SA(0, 1), a2 + hstep, voffA);
;             PG8_WAIT_V(8); PG8_WAIT_L(0); PG8_BAR; PG8_MMA(0, 0, At, B0); PG8_MMA(0, 1, At, B1); PG8_BAR; PG8_SCHED;
	v_mfma_f32_16x16x32_bf16 v[62:65], v[130:133], v[194:197], 0
	v_mfma_f32_16x16x32_bf16 v[62:65], v[134:137], v[198:201], v[62:65]
	v_mfma_f32_16x16x32_bf16 v[58:61], v[138:141], v[194:197], 0
	v_mfma_f32_16x16x32_bf16 v[58:61], v[142:145], v[198:201], v[58:61]
	v_mfma_f32_16x16x32_bf16 v[42:45], v[138:141], v[202:205], 0
	v_mfma_f32_16x16x32_bf16 v[42:45], v[142:145], v[206:209], v[42:45]
	v_mfma_f32_16x16x32_bf16 v[46:49], v[130:133], v[202:205], 0
	v_mfma_f32_16x16x32_bf16 v[46:49], v[134:137], v[206:209], v[46:49]
	v_mfma_f32_16x16x32_bf16 v[30:33], v[130:133], v[210:213], 0
	v_mfma_f32_16x16x32_bf16 v[30:33], v[134:137], v[214:217], v[30:33]
	v_mfma_f32_16x16x32_bf16 v[26:29], v[138:141], v[210:213], 0
	v_mfma_f32_16x16x32_bf16 v[26:29], v[142:145], v[214:217], v[26:29]
	v_mfma_f32_16x16x32_bf16 v[10:13], v[138:141], v[218:221], 0
	v_mfma_f32_16x16x32_bf16 v[10:13], v[142:145], v[222:225], v[10:13]
	v_mfma_f32_16x16x32_bf16 v[14:17], v[130:133], v[218:221], 0
	v_mfma_f32_16x16x32_bf16 v[14:17], v[134:137], v[222:225], v[14:17]
	v_mfma_f32_16x16x32_bf16 v[54:57], v[158:161], v[194:197], 0
	v_mfma_f32_16x16x32_bf16 v[54:57], v[182:185], v[198:201], v[54:57]
	v_mfma_f32_16x16x32_bf16 v[50:53], v[186:189], v[194:197], 0
	v_mfma_f32_16x16x32_bf16 v[50:53], v[190:193], v[198:201], v[50:53]
	v_mfma_f32_16x16x32_bf16 v[34:37], v[186:189], v[202:205], 0
	v_mfma_f32_16x16x32_bf16 v[34:37], v[190:193], v[206:209], v[34:37]
	v_mfma_f32_16x16x32_bf16 v[38:41], v[158:161], v[202:205], 0
	v_mfma_f32_16x16x32_bf16 v[38:41], v[182:185], v[206:209], v[38:41]
	v_mfma_f32_16x16x32_bf16 v[22:25], v[158:161], v[210:213], 0
	v_mfma_f32_16x16x32_bf16 v[22:25], v[182:185], v[214:217], v[22:25]
	v_mfma_f32_16x16x32_bf16 v[18:21], v[186:189], v[210:213], 0
	v_mfma_f32_16x16x32_bf16 v[18:21], v[190:193], v[214:217], v[18:21]
	v_mfma_f32_16x16x32_bf16 v[2:5], v[186:189], v[218:221], 0
	v_mfma_f32_16x16x32_bf16 v[2:5], v[190:193], v[222:225], v[2:5]
	v_mfma_f32_16x16x32_bf16 v[6:9], v[158:161], v[218:221], 0
	v_mfma_f32_16x16x32_bf16 v[6:9], v[182:185], v[222:225], v[6:9]
	s_barrier
	s_setprio 0
	s_add_i32 s64, 16, 0x18000
	s_add_i32 s65, 16, 0x1c000
	v_add_u32_e32 v142, s64, v179
	v_add_u32_e32 v190, s65, v179
	ds_read_b128 v[130:133], v142
	ds_read_b128 v[134:137], v142 offset:1024
	ds_read_b128 v[138:141], v142 offset:2048
	ds_read_b128 v[142:145], v142 offset:3072
	ds_read_b128 v[158:161], v190
	ds_read_b128 v[182:185], v190 offset:1024
	ds_read_b128 v[186:189], v190 offset:2048
	ds_read_b128 v[190:193], v190 offset:3072
	s_add_u32 s10, s50, 0x40000
	s_addc_u32 s11, s51, 0
	s_mov_b32 m0, s6
	v_lshl_add_u64 v[242:243], s[10:11], 0, v[150:151]
	ds_read_b128 v[194:197], v181 offset:32768
	ds_read_b128 v[198:201], v181 offset:33792
	ds_read_b128 v[202:205], v181 offset:34816
	ds_read_b128 v[206:209], v181 offset:35840
	ds_read_b128 v[210:213], v181 offset:36864
	ds_read_b128 v[214:217], v181 offset:37888
	ds_read_b128 v[218:221], v181 offset:38912
	ds_read_b128 v[222:225], v181 offset:39936
	global_load_lds_dwordx4 v[242:243], off
	v_lshl_add_u64 v[242:243], s[10:11], 0, v[148:149]
	s_mov_b32 m0, s7
	s_nop 0
	global_load_lds_dwordx4 v[242:243], off
	s_waitcnt vmcnt(8)
	s_waitcnt lgkmcnt(0)
	s_setprio 1
	s_barrier
	v_mfma_f32_16x16x32_bf16 v[126:129], v[130:133], v[194:197], v[126:129]
	v_mfma_f32_16x16x32_bf16 v[126:129], v[134:137], v[198:201], v[126:129]
	v_mfma_f32_16x16x32_bf16 v[122:125], v[138:141], v[194:197], v[122:125]
	v_mfma_f32_16x16x32_bf16 v[122:125], v[142:145], v[198:201], v[122:125]
	v_mfma_f32_16x16x32_bf16 v[106:109], v[138:141], v[202:205], v[106:109]
	v_mfma_f32_16x16x32_bf16 v[106:109], v[142:145], v[206:209], v[106:109]
	v_mfma_f32_16x16x32_bf16 v[110:113], v[130:133], v[202:205], v[110:113]
	v_mfma_f32_16x16x32_bf16 v[110:113], v[134:137], v[206:209], v[110:113]
	v_mfma_f32_16x16x32_bf16 v[94:97], v[130:133], v[210:213], v[94:97]
	v_mfma_f32_16x16x32_bf16 v[94:97], v[134:137], v[214:217], v[94:97]
	v_mfma_f32_16x16x32_bf16 v[90:93], v[138:141], v[210:213], v[90:93]
	v_mfma_f32_16x16x32_bf16 v[90:93], v[142:145], v[214:217], v[90:93]
	v_mfma_f32_16x16x32_bf16 v[74:77], v[138:141], v[218:221], v[74:77]
	v_mfma_f32_16x16x32_bf16 v[74:77], v[142:145], v[222:225], v[74:77]
	v_mfma_f32_16x16x32_bf16 v[78:81], v[130:133], v[218:221], v[78:81]
	v_mfma_f32_16x16x32_bf16 v[78:81], v[134:137], v[222:225], v[78:81]
	v_mfma_f32_16x16x32_bf16 v[118:121], v[158:161], v[194:197], v[118:121]
	v_mfma_f32_16x16x32_bf16 v[118:121], v[182:185], v[198:201], v[118:121]
	v_mfma_f32_16x16x32_bf16 v[114:117], v[186:189], v[194:197], v[114:117]
	v_mfma_f32_16x16x32_bf16 v[114:117], v[190:193], v[198:201], v[114:117]
	v_mfma_f32_16x16x32_bf16 v[98:101], v[186:189], v[202:205], v[98:101]
	v_mfma_f32_16x16x32_bf16 v[98:101], v[190:193], v[206:209], v[98:101]
	v_mfma_f32_16x16x32_bf16 v[102:105], v[158:161], v[202:205], v[102:105]
	v_mfma_f32_16x16x32_bf16 v[102:105], v[182:185], v[206:209], v[102:105]
	v_mfma_f32_16x16x32_bf16 v[86:89], v[158:161], v[210:213], v[86:89]
	v_mfma_f32_16x16x32_bf16 v[86:89], v[182:185], v[214:217], v[86:89]
	v_mfma_f32_16x16x32_bf16 v[82:85], v[186:189], v[210:213], v[82:85]
	v_mfma_f32_16x16x32_bf16 v[82:85], v[190:193], v[214:217], v[82:85]
	v_mfma_f32_16x16x32_bf16 v[66:69], v[186:189], v[218:221], v[66:69]
	v_mfma_f32_16x16x32_bf16 v[66:69], v[190:193], v[222:225], v[66:69]
	v_mfma_f32_16x16x32_bf16 v[70:73], v[158:161], v[218:221], v[70:73]
	v_mfma_f32_16x16x32_bf16 v[70:73], v[182:185], v[222:225], v[70:73]
	s_barrier
; #define PG8_STAGE(bufoff, gbase, voff) do { _Pragma("unroll") for (int _i = 0; _i < 2; ++_i) \
;         __builtin_amdgcn_global_load_lds((const unsigned*)((const char*)(gbase) + (voff)[_i]), (PG8_LAS unsigned*)(lds + (bufoff) + ldsw + _i * 8192), 16, 0, 0); } while (0)
; #define PG8_LDA(dst, b, h) do { _Pragma("unroll") for (int m = 0; m < 4; ++m) _Pragma("unroll") for (int k = 0; k < 2; ++k) dst[m][k] = *(const PG8_LAS bf16x8*)(lds + PG8_SA(b, h) + aoff + m * 2048 + k * 1024); } while (0)
; #define PG8_MMA(ai, bj, At, Bt) do { __builtin_amdgcn_s_setprio(1); _Pragma("unroll") for (int m = 0; m < 4; ++m) _Pragma("unroll") for (int n = 0; n < 2; ++n) _Pragma("unroll") for (int k = 0; k < 2; ++k) \
;         acc[ai][bj][m][n] = __builtin_amdgcn_mfma_f32_16x16x32_bf16(Bt[n][k], At[m][k], acc[ai][bj][m][n], 0, 0, 0); __builtin_amdgcn_s_setprio(0); } while (0)
; #define PG8_WAIT_V(n) asm volatile("s_waitcnt vmcnt(" #n ")" ::: "memory")
; #define PG8_WAIT_L(n) asm volatile("s_waitcnt lgkmcnt(" #n ")" ::: "memory")
; #define PG8_BAR __builtin_amdgcn_s_barrier()
; #define PG8_SCHED __builtin_amdgcn_sched_barrier(0)
; template <class Epi, class Sched, bool ALIGN_EPI = false, bool SP2 = false>
; __device__ __forceinline__ void gemm_phase(PG8_LAS unsigned char* lds, const Gemm g, const Sched& S, const Epi& E) {
;     ...
;         for (int t = 0; t < nt; t += 2) {
;             const bool last = (t == nt - 2);
;             const char* a1 = cA + (size_t)(t + 1) * kstep;
;             const char* a2 = last ? nA : cA + (size_t)(t + 2) * kstep; const char* b2 = last ? nB : cB + (size_t)(t + 2) * kstep;
;             const char* a3 = a2 + kstep; const char* b3 = b2 + kstep;
;     ...
;             PG8_LDA(At, 1, 1); PG8_STAGE(PG8_SB(1, 0), b3, voffB); PG8_STAGE(PG8_SB(1, 1), b3 + hstep, voffB); PG8_STAGE(PG8_SA(1, 0), a3, voffA);
;             PG8_WAIT_V(8); PG8_WAIT_L(0); PG8_BAR; PG8_MMA(1, 0, At, B0); PG8_MMA(1, 1, At, B1); PG8_BAR; PG8_SCHED;
	s_setprio 0
	s_add_i32 s10, s64, s3
	v_lshl_add_u64 v[176:177], v[176:177], 0, s[28:29]
	s_mov_b32 m0, s10
	ds_read_b128 v[194:197], v181 offset:49152
	ds_read_b128 v[198:201], v181 offset:50176
	ds_read_b128 v[202:205], v181 offset:51200
	ds_read_b128 v[206:209], v181 offset:52224
	ds_read_b128 v[210:213], v181 offset:53248
	ds_read_b128 v[214:217], v181 offset:54272
	ds_read_b128 v[218:221], v181 offset:55296
	ds_read_b128 v[222:225], v181 offset:56320
	global_load_lds_dwordx4 v[176:177], off
	s_add_i32 m0, s10, 0x2000
	s_add_u32 s10, s48, 0x40080
	v_lshl_add_u64 v[176:177], v[226:227], 0, s[28:29]
	s_addc_u32 s11, s49, 0
	s_add_i32 s48, s65, s3
	global_load_lds_dwordx4 v[176:177], off
	v_lshl_add_u64 v[176:177], s[10:11], 0, v[0:1]
	s_mov_b32 m0, s48
	s_nop 0
	global_load_lds_dwordx4 v[176:177], off
	v_lshl_add_u64 v[176:177], s[10:11], 0, v[146:147]
	s_add_i32 m0, s48, 0x2000
	s_nop 0
	global_load_lds_dwordx4 v[176:177], off
	v_lshl_add_u64 v[176:177], v[238:239], 0, s[28:29]
	s_mov_b32 m0, s54
	s_nop 0
	global_load_lds_dwordx4 v[176:177], off
	v_lshl_add_u64 v[176:177], v[240:241], 0, s[28:29]
	s_mov_b32 m0, s55
	s_nop 0
	global_load_lds_dwordx4 v[176:177], off
	s_waitcnt vmcnt(8)
	s_waitcnt lgkmcnt(0)
	s_setprio 1
	s_barrier
	v_mfma_f32_16x16x32_bf16 v[62:65], v[130:133], v[194:197], v[62:65]
	v_mfma_f32_16x16x32_bf16 v[62:65], v[134:137], v[198:201], v[62:65]
	v_mfma_f32_16x16x32_bf16 v[58:61], v[138:141], v[194:197], v[58:61]
	v_mfma_f32_16x16x32_bf16 v[58:61], v[142:145], v[198:201], v[58:61]
	v_mfma_f32_16x16x32_bf16 v[42:45], v[138:141], v[202:205], v[42:45]
	v_mfma_f32_16x16x32_bf16 v[42:45], v[142:145], v[206:209], v[42:45]
	v_mfma_f32_16x16x32_bf16 v[46:49], v[130:133], v[202:205], v[46:49]
	v_mfma_f32_16x16x32_bf16 v[46:49], v[134:137], v[206:209], v[46:49]
	v_mfma_f32_16x16x32_bf16 v[30:33], v[130:133], v[210:213], v[30:33]
	v_mfma_f32_16x16x32_bf16 v[30:33], v[134:137], v[214:217], v[30:33]
	v_mfma_f32_16x16x32_bf16 v[26:29], v[138:141], v[210:213], v[26:29]
	v_mfma_f32_16x16x32_bf16 v[26:29], v[142:145], v[214:217], v[26:29]
	v_mfma_f32_16x16x32_bf16 v[10:13], v[138:141], v[218:221], v[10:13]
	v_mfma_f32_16x16x32_bf16 v[10:13], v[142:145], v[222:225], v[10:13]
	v_mfma_f32_16x16x32_bf16 v[14:17], v[130:133], v[218:221], v[14:17]
	v_mfma_f32_16x16x32_bf16 v[14:17], v[134:137], v[222:225], v[14:17]
	v_mfma_f32_16x16x32_bf16 v[54:57], v[158:161], v[194:197], v[54:57]
	v_mfma_f32_16x16x32_bf16 v[54:57], v[182:185], v[198:201], v[54:57]
	v_mfma_f32_16x16x32_bf16 v[50:53], v[186:189], v[194:197], v[50:53]
	v_mfma_f32_16x16x32_bf16 v[50:53], v[190:193], v[198:201], v[50:53]
	v_mfma_f32_16x16x32_bf16 v[34:37], v[186:189], v[202:205], v[34:37]
	v_mfma_f32_16x16x32_bf16 v[34:37], v[190:193], v[206:209], v[34:37]
	v_mfma_f32_16x16x32_bf16 v[38:41], v[158:161], v[202:205], v[38:41]
	v_mfma_f32_16x16x32_bf16 v[38:41], v[182:185], v[206:209], v[38:41]
	v_mfma_f32_16x16x32_bf16 v[22:25], v[158:161], v[210:213], v[22:25]
	v_mfma_f32_16x16x32_bf16 v[22:25], v[182:185], v[214:217], v[22:25]
	v_mfma_f32_16x16x32_bf16 v[18:21], v[186:189], v[210:213], v[18:21]
	v_mfma_f32_16x16x32_bf16 v[18:21], v[190:193], v[214:217], v[18:21]
	v_mfma_f32_16x16x32_bf16 v[2:5], v[186:189], v[218:221], v[2:5]
	v_mfma_f32_16x16x32_bf16 v[2:5], v[190:193], v[222:225], v[2:5]
	v_mfma_f32_16x16x32_bf16 v[6:9], v[158:161], v[218:221], v[6:9]
	v_mfma_f32_16x16x32_bf16 v[6:9], v[182:185], v[222:225], v[6:9]
	s_barrier
	s_setprio 0
	s_add_i32 s63, s63, 2
	s_add_u32 s59, s59, 0x100
	s_addc_u32 s62, s62, 0
	s_add_u32 s40, s40, 0x100
	s_addc_u32 s41, s41, 0
	s_cmp_gt_u32 s63, 13

; #define PG8_STAGE(bufoff, gbase, voff) do { _Pragma("unroll") for (int _i = 0; _i < 2; ++_i) \
;         __builtin_amdgcn_global_load_lds((const unsigned*)((const char*)(gbase) + (voff)[_i]), (PG8_LAS unsigned*)(lds + (bufoff) + ldsw + _i * 8192), 16, 0, 0); } while (0)
; #define PG8_LDA(dst, b, h) do { _Pragma("unroll") for (int m = 0; m < 4; ++m) _Pragma("unroll") for (int k = 0; k < 2; ++k) dst[m][k] = *(const PG8_LAS bf16x8*)(lds + PG8_SA(b, h) + aoff + m * 2048 + k * 1024); } while (0)
; #define PG8_LDB(dst, b, h) do { _Pragma("unroll") for (int n = 0; n < 2; ++n) _Pragma("unroll") for (int k = 0; k < 2; ++k) dst[n][k] = *(const PG8_LAS bf16x8*)(lds + PG8_SB(b, h) + boff + n * 2048 + k * 1024); } while (0)
; #define PG8_MMA(ai, bj, At, Bt) do { __builtin_amdgcn_s_setprio(1); _Pragma("unroll") for (int m = 0; m < 4; ++m) _Pragma("unroll") for (int n = 0; n < 2; ++n) _Pragma("unroll") for (int k = 0; k < 2; ++k) \
;         acc[ai][bj][m][n] = __builtin_amdgcn_mfma_f32_16x16x32_bf16(Bt[n][k], At[m][k], acc[ai][bj][m][n], 0, 0, 0); __builtin_amdgcn_s_setprio(0); } while (0)
; #define PG8_WAIT_V(n) asm volatile("s_waitcnt vmcnt(" #n ")" ::: "memory")
; #define PG8_WAIT_L(n) asm volatile("s_waitcnt lgkmcnt(" #n ")" ::: "memory")
; #define PG8_BAR __builtin_amdgcn_s_barrier()
; #define PG8_SCHED __builtin_amdgcn_sched_barrier(0)
; template <class Epi, class Sched, bool ALIGN_EPI = false, bool SP2 = false>
; __device__ __forceinline__ void gemm_phase(PG8_LAS unsigned char* lds, const Gemm g, const Sched& S, const Epi& E) {
;     ...
;             PG8_LDB(B0, 0, 0); PG8_LDB(B1, 0, 1); PG8_SCHED; PG8_LDA(At, 0, 0); PG8_STAGE(PG8_SA(1, 1), a1 + hstep, voffA);
;             PG8_WAIT_V(8); PG8_WAIT_L(0); PG8_BAR; PG8_MMA(0, 0, At, B0); PG8_MMA(0, 1, At, B1); PG8_BAR; PG8_SCHED;
;             PG8_LDA(At, 0, 1); PG8_STAGE(PG8_SB(0, 0), b2, voffB); PG8_STAGE(PG8_SB(0, 1), b2 + hstep, voffB); PG8_STAGE(PG8_SA(0, 0), a2, voffA);
;             PG8_WAIT_V(8); PG8_WAIT_L(0); PG8_BAR; PG8_MMA(1, 0, At, B0); PG8_MMA(1, 1, At, B1); PG8_BAR; PG8_SCHED;
;     ...
;         for (int a = 0; a < 2; ++a)
; #pragma unroll
;             for (int b = 0; b < 2; ++b)
; #pragma unroll
;                 for (int m = 0; m < 4; ++m)
; #pragma unroll
;                     for (int n = 0; n < 2; ++n) acc[a][b][m][n] = (f32x4){0.f, 0.f, 0.f, 0.f};
.LBB0_1294:
	s_add_u32 s66, s48, 0x100
	s_addc_u32 s67, s49, 0
	s_mov_b32 s68, -2
	s_add_u32 s40, s42, 0x100
	s_addc_u32 s41, s43, 0
	s_add_i32 s10, 16, 0x10000
	s_cmp_eq_u32 s68, 40
	s_cselect_b32 s49, s25, s41
	s_cselect_b32 s48, s24, s40
	v_add_u32_e32 v140, s10, v143
	s_cselect_b32 s47, s27, s67
	s_cselect_b32 s46, s26, s66
	s_add_i32 s69, 16, 0x14000
	ds_read_b128 v[146:149], v140
	ds_read_b128 v[150:153], v140 offset:1024
	ds_read_b128 v[154:157], v140 offset:2048
	ds_read_b128 v[158:161], v140 offset:3072
	v_add_u32_e32 v140, s69, v143
	ds_read_b128 v[176:179], v140
	ds_read_b128 v[180:183], v140 offset:1024
	ds_read_b128 v[184:187], v140 offset:2048
	ds_read_b128 v[188:191], v140 offset:3072
	v_lshl_add_u64 v[140:141], s[42:43], 0, v[138:139]
	s_add_i32 m0, s9, 0xc000
	ds_read_b128 v[192:195], v145
	ds_read_b128 v[196:199], v145 offset:1024
	ds_read_b128 v[200:203], v145 offset:2048
	ds_read_b128 v[204:207], v145 offset:3072
	ds_read_b128 v[208:211], v145 offset:4096
	ds_read_b128 v[212:215], v145 offset:5120
	ds_read_b128 v[216:219], v145 offset:6144
	ds_read_b128 v[220:223], v145 offset:7168
	global_load_lds_dwordx4 v[140:141], off
	v_lshl_add_u64 v[140:141], s[42:43], 0, v[136:137]
	s_add_i32 m0, s9, 0xe000
	s_nop 0
	global_load_lds_dwordx4 v[140:141], off
	s_waitcnt vmcnt(8)
	s_waitcnt lgkmcnt(0)
	s_setprio 1
	s_barrier
	v_mfma_f32_16x16x32_bf16 v[126:129], v[146:149], v[192:195], 0
	v_mfma_f32_16x16x32_bf16 v[126:129], v[150:153], v[196:199], v[126:129]
	v_mfma_f32_16x16x32_bf16 v[122:125], v[154:157], v[192:195], 0
	v_mfma_f32_16x16x32_bf16 v[122:125], v[158:161], v[196:199], v[122:125]
	v_mfma_f32_16x16x32_bf16 v[110:113], v[154:157], v[200:203], 0
	v_mfma_f32_16x16x32_bf16 v[110:113], v[158:161], v[204:207], v[110:113]
	v_mfma_f32_16x16x32_bf16 v[114:117], v[146:149], v[200:203], 0
	v_mfma_f32_16x16x32_bf16 v[114:117], v[150:153], v[204:207], v[114:117]
	v_mfma_f32_16x16x32_bf16 v[98:101], v[146:149], v[208:211], 0
	v_mfma_f32_16x16x32_bf16 v[98:101], v[150:153], v[212:215], v[98:101]
	v_mfma_f32_16x16x32_bf16 v[94:97], v[154:157], v[208:211], 0
	v_mfma_f32_16x16x32_bf16 v[94:97], v[158:161], v[212:215], v[94:97]
	v_mfma_f32_16x16x32_bf16 v[78:81], v[154:157], v[216:219], 0
	v_mfma_f32_16x16x32_bf16 v[78:81], v[158:161], v[220:223], v[78:81]
	v_mfma_f32_16x16x32_bf16 v[82:85], v[146:149], v[216:219], 0
	v_mfma_f32_16x16x32_bf16 v[82:85], v[150:153], v[220:223], v[82:85]
	v_mfma_f32_16x16x32_bf16 v[118:121], v[176:179], v[192:195], 0
	v_mfma_f32_16x16x32_bf16 v[118:121], v[180:183], v[196:199], v[118:121]
	v_mfma_f32_16x16x32_bf16 v[106:109], v[184:187], v[192:195], 0
	v_mfma_f32_16x16x32_bf16 v[106:109], v[188:191], v[196:199], v[106:109]
	v_mfma_f32_16x16x32_bf16 v[90:93], v[184:187], v[200:203], 0
	v_mfma_f32_16x16x32_bf16 v[90:93], v[188:191], v[204:207], v[90:93]
	v_mfma_f32_16x16x32_bf16 v[102:105], v[176:179], v[200:203], 0
	v_mfma_f32_16x16x32_bf16 v[102:105], v[180:183], v[204:207], v[102:105]
	v_mfma_f32_16x16x32_bf16 v[86:89], v[176:179], v[208:211], 0
	v_mfma_f32_16x16x32_bf16 v[86:89], v[180:183], v[212:215], v[86:89]
	v_mfma_f32_16x16x32_bf16 v[74:77], v[184:187], v[208:211], 0
	v_mfma_f32_16x16x32_bf16 v[74:77], v[188:191], v[212:215], v[74:77]
	v_mfma_f32_16x16x32_bf16 v[66:69], v[184:187], v[216:219], 0
	v_mfma_f32_16x16x32_bf16 v[66:69], v[188:191], v[220:223], v[66:69]
	v_mfma_f32_16x16x32_bf16 v[70:73], v[176:179], v[216:219], 0
	v_mfma_f32_16x16x32_bf16 v[70:73], v[180:183], v[220:223], v[70:73]
	s_barrier
	s_setprio 0
	s_add_i32 s10, s10, s6
	v_lshl_add_u64 v[140:141], s[46:47], 0, v[0:1]
	s_mov_b32 m0, s10
	ds_read_b128 v[192:195], v145 offset:16384
	ds_read_b128 v[196:199], v145 offset:17408
	ds_read_b128 v[200:203], v145 offset:18432
	ds_read_b128 v[204:207], v145 offset:19456
	ds_read_b128 v[208:211], v145 offset:20480
	ds_read_b128 v[212:215], v145 offset:21504
	ds_read_b128 v[216:219], v145 offset:22528
	ds_read_b128 v[220:223], v145 offset:23552
	global_load_lds_dwordx4 v[140:141], off
	s_add_i32 m0, s10, 0x2000
	s_add_u32 s10, s46, 0xb0000
	v_lshl_add_u64 v[224:225], s[46:47], 0, v[130:131]
	s_addc_u32 s11, s47, 0
	s_add_i32 s42, s69, s6
	global_load_lds_dwordx4 v[224:225], off
	v_lshl_add_u64 v[226:227], s[10:11], 0, v[0:1]
	s_mov_b32 m0, s42
	v_lshl_add_u64 v[238:239], s[48:49], 0, v[132:133]
	global_load_lds_dwordx4 v[226:227], off
	v_lshl_add_u64 v[226:227], s[10:11], 0, v[130:131]
	s_add_i32 m0, s42, 0x2000
	s_nop 0
	global_load_lds_dwordx4 v[226:227], off
	v_lshl_add_u64 v[226:227], s[48:49], 0, v[134:135]
	s_mov_b32 m0, s9
	s_nop 0
	global_load_lds_dwordx4 v[226:227], off
	s_mov_b32 m0, s50
	s_nop 0
	global_load_lds_dwordx4 v[238:239], off
	s_waitcnt vmcnt(8)
	s_waitcnt lgkmcnt(0)
	s_setprio 1
	s_barrier
; #define PG8_STAGE(bufoff, gbase, voff) do { _Pragma("unroll") for (int _i = 0; _i < 2; ++_i) \
;         __builtin_amdgcn_global_load_lds((const unsigned*)((const char*)(gbase) + (voff)[_i]), (PG8_LAS unsigned*)(lds + (bufoff) + ldsw + _i * 8192), 16, 0, 0); } while (0)
; #define PG8_LDA(dst, b, h) do { _Pragma("unroll") for (int m = 0; m < 4; ++m) _Pragma("unroll") for (int k = 0; k < 2; ++k) dst[m][k] = *(const PG8_LAS bf16x8*)(lds + PG8_SA(b, h) + aoff + m * 2048 + k * 1024); } while (0)
; #define PG8_LDB(dst, b, h) do { _Pragma("unroll") for (int n = 0; n < 2; ++n) _Pragma("unroll") for (int k = 0; k < 2; ++k) dst[n][k] = *(const PG8_LAS bf16x8*)(lds + PG8_SB(b, h) + boff + n * 2048 + k * 1024); } while (0)
; #define PG8_MMA(ai, bj, At, Bt) do { __builtin_amdgcn_s_setprio(1); _Pragma("unroll") for (int m = 0; m < 4; ++m) _Pragma("unroll") for (int n = 0; n < 2; ++n) _Pragma("unroll") for (int k = 0; k < 2; ++k) \
;         acc[ai][bj][m][n] = __builtin_amdgcn_mfma_f32_16x16x32_bf16(Bt[n][k], At[m][k], acc[ai][bj][m][n], 0, 0, 0); __builtin_amdgcn_s_setprio(0); } while (0)
; #define PG8_WAIT_V(n) asm volatile("s_waitcnt vmcnt(" #n ")" ::: "memory")
; #define PG8_WAIT_L(n) asm volatile("s_waitcnt lgkmcnt(" #n ")" ::: "memory")
; #define PG8_BAR __builtin_amdgcn_s_barrier()
; #define PG8_SCHED __builtin_amdgcn_sched_barrier(0)
; template <class Epi, class Sched, bool ALIGN_EPI = false, bool SP2 = false>
; __device__ __forceinline__ void gemm_phase(PG8_LAS unsigned char* lds, const Gemm g, const Sched& S, const Epi& E) {
;     ...
;             PG8_WAIT_V(8); PG8_WAIT_L(0); PG8_BAR; PG8_MMA(1, 0, At, B0); PG8_MMA(1, 1, At, B1); PG8_BAR; PG8_SCHED;
;             PG8_LDB(B0, 1, 0); PG8_LDB(B1, 1, 1); PG8_SCHED; PG8_LDA(At, 1, 0); PG8_STAGE(PG8_SA(0, 1), a2 + hstep, voffA);
;             PG8_WAIT_V(8); PG8_WAIT_L(0); PG8_BAR; PG8_MMA(0, 0, At, B0); PG8_MMA(0, 1, At, B1); PG8_BAR; PG8_SCHED;
	v_mfma_f32_16x16x32_bf16 v[62:65], v[146:149], v[192:195], 0
	v_mfma_f32_16x16x32_bf16 v[62:65], v[150:153], v[196:199], v[62:65]
	v_mfma_f32_16x16x32_bf16 v[58:61], v[154:157], v[192:195], 0
	v_mfma_f32_16x16x32_bf16 v[58:61], v[158:161], v[196:199], v[58:61]
	v_mfma_f32_16x16x32_bf16 v[46:49], v[154:157], v[200:203], 0
	v_mfma_f32_16x16x32_bf16 v[46:49], v[158:161], v[204:207], v[46:49]
	v_mfma_f32_16x16x32_bf16 v[50:53], v[146:149], v[200:203], 0
	v_mfma_f32_16x16x32_bf16 v[50:53], v[150:153], v[204:207], v[50:53]
	v_mfma_f32_16x16x32_bf16 v[34:37], v[146:149], v[208:211], 0
	v_mfma_f32_16x16x32_bf16 v[34:37], v[150:153], v[212:215], v[34:37]
	v_mfma_f32_16x16x32_bf16 v[30:33], v[154:157], v[208:211], 0
	v_mfma_f32_16x16x32_bf16 v[30:33], v[158:161], v[212:215], v[30:33]
	v_mfma_f32_16x16x32_bf16 v[14:17], v[154:157], v[216:219], 0
	v_mfma_f32_16x16x32_bf16 v[14:17], v[158:161], v[220:223], v[14:17]
	v_mfma_f32_16x16x32_bf16 v[18:21], v[146:149], v[216:219], 0
	v_mfma_f32_16x16x32_bf16 v[18:21], v[150:153], v[220:223], v[18:21]
	v_mfma_f32_16x16x32_bf16 v[54:57], v[176:179], v[192:195], 0
	v_mfma_f32_16x16x32_bf16 v[54:57], v[180:183], v[196:199], v[54:57]
	v_mfma_f32_16x16x32_bf16 v[42:45], v[184:187], v[192:195], 0
	v_mfma_f32_16x16x32_bf16 v[42:45], v[188:191], v[196:199], v[42:45]
	v_mfma_f32_16x16x32_bf16 v[26:29], v[184:187], v[200:203], 0
	v_mfma_f32_16x16x32_bf16 v[26:29], v[188:191], v[204:207], v[26:29]
	v_mfma_f32_16x16x32_bf16 v[38:41], v[176:179], v[200:203], 0
	v_mfma_f32_16x16x32_bf16 v[38:41], v[180:183], v[204:207], v[38:41]
	v_mfma_f32_16x16x32_bf16 v[22:25], v[176:179], v[208:211], 0
	v_mfma_f32_16x16x32_bf16 v[22:25], v[180:183], v[212:215], v[22:25]
	v_mfma_f32_16x16x32_bf16 v[10:13], v[184:187], v[208:211], 0
	v_mfma_f32_16x16x32_bf16 v[10:13], v[188:191], v[212:215], v[10:13]
	v_mfma_f32_16x16x32_bf16 v[2:5], v[184:187], v[216:219], 0
	v_mfma_f32_16x16x32_bf16 v[2:5], v[188:191], v[220:223], v[2:5]
	v_mfma_f32_16x16x32_bf16 v[6:9], v[176:179], v[216:219], 0
	v_mfma_f32_16x16x32_bf16 v[6:9], v[180:183], v[220:223], v[6:9]
	s_barrier
	s_setprio 0
	s_add_i32 s42, 16, 0x18000
	s_add_i32 s43, 16, 0x1c000
	v_add_u32_e32 v158, s42, v143
	v_add_u32_e32 v188, s43, v143
	ds_read_b128 v[146:149], v158
	ds_read_b128 v[150:153], v158 offset:1024
	ds_read_b128 v[154:157], v158 offset:2048
	ds_read_b128 v[158:161], v158 offset:3072
	ds_read_b128 v[176:179], v188
	ds_read_b128 v[180:183], v188 offset:1024
	ds_read_b128 v[184:187], v188 offset:2048
	ds_read_b128 v[188:191], v188 offset:3072
	s_add_u32 s10, s48, 0xb0000
	s_addc_u32 s11, s49, 0
	s_mov_b32 m0, s51
	v_lshl_add_u64 v[240:241], s[10:11], 0, v[134:135]
	ds_read_b128 v[192:195], v145 offset:32768
	ds_read_b128 v[196:199], v145 offset:33792
	ds_read_b128 v[200:203], v145 offset:34816
	ds_read_b128 v[204:207], v145 offset:35840
	ds_read_b128 v[208:211], v145 offset:36864
	ds_read_b128 v[212:215], v145 offset:37888
	ds_read_b128 v[216:219], v145 offset:38912
	ds_read_b128 v[220:223], v145 offset:39936
	global_load_lds_dwordx4 v[240:241], off
	v_lshl_add_u64 v[240:241], s[10:11], 0, v[132:133]
	s_mov_b32 m0, s54
	s_nop 0
	global_load_lds_dwordx4 v[240:241], off
	s_waitcnt vmcnt(8)
	s_waitcnt lgkmcnt(0)
	s_setprio 1
	s_barrier
	v_mfma_f32_16x16x32_bf16 v[126:129], v[146:149], v[192:195], v[126:129]
	v_mfma_f32_16x16x32_bf16 v[126:129], v[150:153], v[196:199], v[126:129]
	v_mfma_f32_16x16x32_bf16 v[122:125], v[154:157], v[192:195], v[122:125]
	v_mfma_f32_16x16x32_bf16 v[122:125], v[158:161], v[196:199], v[122:125]
	v_mfma_f32_16x16x32_bf16 v[110:113], v[154:157], v[200:203], v[110:113]
	v_mfma_f32_16x16x32_bf16 v[110:113], v[158:161], v[204:207], v[110:113]
	v_mfma_f32_16x16x32_bf16 v[114:117], v[146:149], v[200:203], v[114:117]
	v_mfma_f32_16x16x32_bf16 v[114:117], v[150:153], v[204:207], v[114:117]
	v_mfma_f32_16x16x32_bf16 v[98:101], v[146:149], v[208:211], v[98:101]
	v_mfma_f32_16x16x32_bf16 v[98:101], v[150:153], v[212:215], v[98:101]
	v_mfma_f32_16x16x32_bf16 v[94:97], v[154:157], v[208:211], v[94:97]
	v_mfma_f32_16x16x32_bf16 v[94:97], v[158:161], v[212:215], v[94:97]
	v_mfma_f32_16x16x32_bf16 v[78:81], v[154:157], v[216:219], v[78:81]
	v_mfma_f32_16x16x32_bf16 v[78:81], v[158:161], v[220:223], v[78:81]
	v_mfma_f32_16x16x32_bf16 v[82:85], v[146:149], v[216:219], v[82:85]
	v_mfma_f32_16x16x32_bf16 v[82:85], v[150:153], v[220:223], v[82:85]
	v_mfma_f32_16x16x32_bf16 v[118:121], v[176:179], v[192:195], v[118:121]
	v_mfma_f32_16x16x32_bf16 v[118:121], v[180:183], v[196:199], v[118:121]
	v_mfma_f32_16x16x32_bf16 v[106:109], v[184:187], v[192:195], v[106:109]
	v_mfma_f32_16x16x32_bf16 v[106:109], v[188:191], v[196:199], v[106:109]
	v_mfma_f32_16x16x32_bf16 v[90:93], v[184:187], v[200:203], v[90:93]
	v_mfma_f32_16x16x32_bf16 v[90:93], v[188:191], v[204:207], v[90:93]
	v_mfma_f32_16x16x32_bf16 v[102:105], v[176:179], v[200:203], v[102:105]
	v_mfma_f32_16x16x32_bf16 v[102:105], v[180:183], v[204:207], v[102:105]
	v_mfma_f32_16x16x32_bf16 v[86:89], v[176:179], v[208:211], v[86:89]
	v_mfma_f32_16x16x32_bf16 v[86:89], v[180:183], v[212:215], v[86:89]
	v_mfma_f32_16x16x32_bf16 v[74:77], v[184:187], v[208:211], v[74:77]
	v_mfma_f32_16x16x32_bf16 v[74:77], v[188:191], v[212:215], v[74:77]
	v_mfma_f32_16x16x32_bf16 v[66:69], v[184:187], v[216:219], v[66:69]
	v_mfma_f32_16x16x32_bf16 v[66:69], v[188:191], v[220:223], v[66:69]
	v_mfma_f32_16x16x32_bf16 v[70:73], v[176:179], v[216:219], v[70:73]
	v_mfma_f32_16x16x32_bf16 v[70:73], v[180:183], v[220:223], v[70:73]
	s_barrier
; #define PG8_STAGE(bufoff, gbase, voff) do { _Pragma("unroll") for (int _i = 0; _i < 2; ++_i) \
;         __builtin_amdgcn_global_load_lds((const unsigned*)((const char*)(gbase) + (voff)[_i]), (PG8_LAS unsigned*)(lds + (bufoff) + ldsw + _i * 8192), 16, 0, 0); } while (0)
; #define PG8_LDA(dst, b, h) do { _Pragma("unroll") for (int m = 0; m < 4; ++m) _Pragma("unroll") for (int k = 0; k < 2; ++k) dst[m][k] = *(const PG8_LAS bf16x8*)(lds + PG8_SA(b, h) + aoff + m * 2048 + k * 1024); } while (0)
; #define PG8_MMA(ai, bj, At, Bt) do { __builtin_amdgcn_s_setprio(1); _Pragma("unroll") for (int m = 0; m < 4; ++m) _Pragma("unroll") for (int n = 0; n < 2; ++n) _Pragma("unroll") for (int k = 0; k < 2; ++k) \
;         acc[ai][bj][m][n] = __builtin_amdgcn_mfma_f32_16x16x32_bf16(Bt[n][k], At[m][k], acc[ai][bj][m][n], 0, 0, 0); __builtin_amdgcn_s_setprio(0); } while (0)
; #define PG8_WAIT_V(n) asm volatile("s_waitcnt vmcnt(" #n ")" ::: "memory")
; #define PG8_WAIT_L(n) asm volatile("s_waitcnt lgkmcnt(" #n ")" ::: "memory")
; #define PG8_BAR __builtin_amdgcn_s_barrier()
; #define PG8_SCHED __builtin_amdgcn_sched_barrier(0)
; template <class Epi, class Sched, bool ALIGN_EPI = false, bool SP2 = false>
; __device__ __forceinline__ void gemm_phase(PG8_LAS unsigned char* lds, const Gemm g, const Sched& S, const Epi& E) {
;     ...
;         for (int t = 0; t < nt; t += 2) {
;     ...
;             PG8_LDA(At, 1, 1); PG8_STAGE(PG8_SB(1, 0), b3, voffB); PG8_STAGE(PG8_SB(1, 1), b3 + hstep, voffB); PG8_STAGE(PG8_SA(1, 0), a3, voffA);
;             PG8_WAIT_V(8); PG8_WAIT_L(0); PG8_BAR; PG8_MMA(1, 0, At, B0); PG8_MMA(1, 1, At, B1); PG8_BAR; PG8_SCHED;
	s_setprio 0
	s_add_i32 s10, s42, s6
	v_lshl_add_u64 v[140:141], v[140:141], 0, s[28:29]
	s_mov_b32 m0, s10
	ds_read_b128 v[192:195], v145 offset:49152
	ds_read_b128 v[196:199], v145 offset:50176
	ds_read_b128 v[200:203], v145 offset:51200
	ds_read_b128 v[204:207], v145 offset:52224
	ds_read_b128 v[208:211], v145 offset:53248
	ds_read_b128 v[212:215], v145 offset:54272
	ds_read_b128 v[216:219], v145 offset:55296
	ds_read_b128 v[220:223], v145 offset:56320
	global_load_lds_dwordx4 v[140:141], off
	s_add_i32 m0, s10, 0x2000
	s_add_u32 s10, s46, 0xb0080
	v_lshl_add_u64 v[140:141], v[224:225], 0, s[28:29]
	s_addc_u32 s11, s47, 0
	s_add_i32 s42, s43, s6
	global_load_lds_dwordx4 v[140:141], off
	v_lshl_add_u64 v[140:141], s[10:11], 0, v[0:1]
	s_mov_b32 m0, s42
	s_nop 0
	global_load_lds_dwordx4 v[140:141], off
	v_lshl_add_u64 v[140:141], s[10:11], 0, v[130:131]
	s_add_i32 m0, s42, 0x2000
	s_nop 0
	global_load_lds_dwordx4 v[140:141], off
	v_lshl_add_u64 v[140:141], v[226:227], 0, s[28:29]
	s_mov_b32 m0, s57
	s_nop 0
	global_load_lds_dwordx4 v[140:141], off
	v_lshl_add_u64 v[140:141], v[238:239], 0, s[28:29]
	s_mov_b32 m0, s58
	s_nop 0
	global_load_lds_dwordx4 v[140:141], off
	s_waitcnt vmcnt(8)
	s_waitcnt lgkmcnt(0)
	s_setprio 1
	s_barrier
	v_mfma_f32_16x16x32_bf16 v[62:65], v[146:149], v[192:195], v[62:65]
	v_mfma_f32_16x16x32_bf16 v[62:65], v[150:153], v[196:199], v[62:65]
	v_mfma_f32_16x16x32_bf16 v[58:61], v[154:157], v[192:195], v[58:61]
	v_mfma_f32_16x16x32_bf16 v[58:61], v[158:161], v[196:199], v[58:61]
	v_mfma_f32_16x16x32_bf16 v[46:49], v[154:157], v[200:203], v[46:49]
	v_mfma_f32_16x16x32_bf16 v[46:49], v[158:161], v[204:207], v[46:49]
	v_mfma_f32_16x16x32_bf16 v[50:53], v[146:149], v[200:203], v[50:53]
	v_mfma_f32_16x16x32_bf16 v[50:53], v[150:153], v[204:207], v[50:53]
	v_mfma_f32_16x16x32_bf16 v[34:37], v[146:149], v[208:211], v[34:37]
	v_mfma_f32_16x16x32_bf16 v[34:37], v[150:153], v[212:215], v[34:37]
	v_mfma_f32_16x16x32_bf16 v[30:33], v[154:157], v[208:211], v[30:33]
	v_mfma_f32_16x16x32_bf16 v[30:33], v[158:161], v[212:215], v[30:33]
	v_mfma_f32_16x16x32_bf16 v[14:17], v[154:157], v[216:219], v[14:17]
	v_mfma_f32_16x16x32_bf16 v[14:17], v[158:161], v[220:223], v[14:17]
	v_mfma_f32_16x16x32_bf16 v[18:21], v[146:149], v[216:219], v[18:21]
	v_mfma_f32_16x16x32_bf16 v[18:21], v[150:153], v[220:223], v[18:21]
	v_mfma_f32_16x16x32_bf16 v[54:57], v[176:179], v[192:195], v[54:57]
	v_mfma_f32_16x16x32_bf16 v[54:57], v[180:183], v[196:199], v[54:57]
	v_mfma_f32_16x16x32_bf16 v[42:45], v[184:187], v[192:195], v[42:45]
	v_mfma_f32_16x16x32_bf16 v[42:45], v[188:191], v[196:199], v[42:45]
	v_mfma_f32_16x16x32_bf16 v[26:29], v[184:187], v[200:203], v[26:29]
	v_mfma_f32_16x16x32_bf16 v[26:29], v[188:191], v[204:207], v[26:29]
	v_mfma_f32_16x16x32_bf16 v[38:41], v[176:179], v[200:203], v[38:41]
	v_mfma_f32_16x16x32_bf16 v[38:41], v[180:183], v[204:207], v[38:41]
	v_mfma_f32_16x16x32_bf16 v[22:25], v[176:179], v[208:211], v[22:25]
	v_mfma_f32_16x16x32_bf16 v[22:25], v[180:183], v[212:215], v[22:25]
	v_mfma_f32_16x16x32_bf16 v[10:13], v[184:187], v[208:211], v[10:13]
	v_mfma_f32_16x16x32_bf16 v[10:13], v[188:191], v[212:215], v[10:13]
	v_mfma_f32_16x16x32_bf16 v[2:5], v[184:187], v[216:219], v[2:5]
	v_mfma_f32_16x16x32_bf16 v[2:5], v[188:191], v[220:223], v[2:5]
	v_mfma_f32_16x16x32_bf16 v[6:9], v[176:179], v[216:219], v[6:9]
	v_mfma_f32_16x16x32_bf16 v[6:9], v[180:183], v[220:223], v[6:9]
	s_barrier
	s_setprio 0
	s_add_i32 s68, s68, 2
	s_add_u32 s66, s66, 0x100
	s_addc_u32 s67, s67, 0
	s_cmp_gt_u32 s68, 41
	s_mov_b64 s[42:43], s[40:41]
